# attention unit epilogue: all 16 gate loads of the gate-multiply/store loop issued up front, loop unrolled x4 with counted waits (on top of rope pipelining + tile-loop edits)
# baseline (speedup 1.0000x reference)
.LBB0_299:
	s_andn2_b64 vcc, exec, s[0:1]
	s_waitcnt lgkmcnt(0)
	s_barrier
	s_cbranch_vccnz .LBB0_266
	ds_read2st64_b32 v[4:5], v143 offset1:1
	ds_read2st64_b32 v[12:13], v143 offset0:2 offset1:3
	ds_read2st64_b32 v[14:15], v143 offset0:4 offset1:5
	ds_read2st64_b32 v[16:17], v143 offset0:6 offset1:7
	s_lshl_b32 s0, s36, 6
	s_and_b32 s4, s0, 0x2000
	s_waitcnt lgkmcnt(2)
	v_sub_f32_e32 v7, v135, v12
	v_sub_f32_e32 v112, v0, v4
	v_sub_f32_e32 v10, v134, v5
	v_sub_f32_e32 v5, v136, v13
	s_waitcnt lgkmcnt(1)
	v_sub_f32_e32 v4, v2, v14
	v_sub_f32_e32 v2, v20, v15
	s_waitcnt lgkmcnt(0)
	v_sub_f32_e32 v0, v21, v16
	ds_read2st64_b32 v[12:13], v143 offset0:8 offset1:9
	v_sub_f32_e32 v3, v3, v17
	ds_read2st64_b32 v[16:17], v143 offset0:10 offset1:11
	ds_read2st64_b32 v[20:21], v143 offset0:12 offset1:13
	ds_read2st64_b32 v[30:31], v143 offset0:14 offset1:15
	s_waitcnt lgkmcnt(3)
	v_sub_f32_e32 v15, v6, v12
	v_sub_f32_e32 v14, v8, v13
	s_waitcnt lgkmcnt(2)
	v_sub_f32_e32 v13, v9, v16
	v_sub_f32_e32 v12, v22, v17
	s_waitcnt lgkmcnt(1)
	v_sub_f32_e32 v8, v28, v21
	s_waitcnt lgkmcnt(0)
	v_sub_f32_e32 v6, v29, v30
	ds_read2st64_b32 v[16:17], v143 offset0:16 offset1:17
	v_sub_f32_e32 v9, v23, v31
	ds_read2st64_b32 v[28:29], v143 offset0:18 offset1:19
	ds_read2st64_b32 v[30:31], v143 offset0:20 offset1:21
	ds_read2st64_b32 v[32:33], v143 offset0:22 offset1:23
	v_sub_f32_e32 v11, v11, v20
	s_waitcnt lgkmcnt(3)
	v_sub_f32_e32 v22, v133, v16
	v_sub_f32_e32 v23, v132, v17
	s_waitcnt lgkmcnt(2)
	v_sub_f32_e32 v21, v131, v28
	v_sub_f32_e32 v20, v130, v29
	s_waitcnt lgkmcnt(0)
	v_sub_f32_e32 v16, v35, v32
	v_sub_f32_e32 v17, v34, v33
	ds_read2st64_b32 v[28:29], v143 offset0:24 offset1:25
	ds_read2st64_b32 v[32:33], v143 offset0:26 offset1:27
	ds_read2st64_b32 v[34:35], v143 offset0:28 offset1:29
	ds_read2st64_b32 v[46:47], v143 offset0:30 offset1:31
	v_sub_f32_e32 v19, v19, v30
	v_sub_f32_e32 v18, v18, v31
	v_mul_f32_e32 v151, v22, v22
	s_waitcnt lgkmcnt(3)
	v_sub_f32_e32 v31, v39, v28
	v_sub_f32_e32 v30, v38, v29
	s_waitcnt lgkmcnt(2)
	v_sub_f32_e32 v29, v25, v32
	v_sub_f32_e32 v28, v24, v33
	s_waitcnt lgkmcnt(1)
	v_sub_f32_e32 v27, v27, v34
	v_sub_f32_e32 v26, v26, v35
	s_waitcnt lgkmcnt(0)
	v_sub_f32_e32 v24, v43, v46
	v_sub_f32_e32 v25, v42, v47
	ds_read2st64_b32 v[32:33], v143 offset0:32 offset1:33
	ds_read2st64_b32 v[34:35], v143 offset0:34 offset1:35
	ds_read2st64_b32 v[38:39], v143 offset0:36 offset1:37
	ds_read2st64_b32 v[42:43], v143 offset0:38 offset1:39
	v_fmac_f32_e32 v151, v112, v112
	v_mul_f32_e32 v148, v23, v23
	v_fmac_f32_e32 v148, v10, v10
	s_waitcnt lgkmcnt(1)
	v_sub_f32_e32 v36, v36, v38
	v_sub_f32_e32 v37, v37, v39
	s_waitcnt lgkmcnt(0)
	v_sub_f32_e32 v38, v53, v42
	v_sub_f32_e32 v39, v52, v43
	ds_read2st64_b32 v[42:43], v143 offset0:40 offset1:41
	ds_read2st64_b32 v[46:47], v143 offset0:42 offset1:43
	ds_read2st64_b32 v[48:49], v143 offset0:44 offset1:45
	ds_read2st64_b32 v[52:53], v143 offset0:46 offset1:47
	v_sub_f32_e32 v32, v161, v32
	v_fmac_f32_e32 v151, v32, v32
	v_sub_f32_e32 v33, v160, v33
	s_waitcnt lgkmcnt(3)
	v_sub_f32_e32 v40, v40, v42
	v_sub_f32_e32 v41, v41, v43
	s_waitcnt lgkmcnt(2)
	v_sub_f32_e32 v42, v55, v46
	v_sub_f32_e32 v43, v54, v47
	s_waitcnt lgkmcnt(1)
	v_sub_f32_e32 v44, v44, v48
	v_sub_f32_e32 v45, v45, v49
	s_waitcnt lgkmcnt(0)
	v_sub_f32_e32 v46, v61, v52
	v_sub_f32_e32 v47, v60, v53
	ds_read2st64_b32 v[48:49], v143 offset0:48 offset1:49
	ds_read2st64_b32 v[60:61], v143 offset0:50 offset1:51
	ds_read2st64_b32 v[62:63], v143 offset0:52 offset1:53
	ds_read2st64_b32 v[64:65], v143 offset0:54 offset1:55
	v_fmac_f32_e32 v148, v33, v33
	v_mul_f32_e32 v144, v21, v21
	s_waitcnt lgkmcnt(2)
	v_sub_f32_e32 v53, v153, v60
	v_sub_f32_e32 v55, v155, v48
	v_sub_f32_e32 v54, v154, v49
	v_sub_f32_e32 v52, v152, v61
	s_waitcnt lgkmcnt(0)
	v_sub_f32_e32 v48, v87, v64
	v_sub_f32_e32 v49, v86, v65
	ds_read2st64_b32 v[60:61], v143 offset0:56 offset1:57
	ds_read2st64_b32 v[64:65], v143 offset0:58 offset1:59
	ds_read2st64_b32 v[86:87], v143 offset0:60 offset1:61
	ds_read2st64_b32 v[152:153], v143 offset0:62 offset1:63
	v_sub_f32_e32 v51, v51, v62
	v_sub_f32_e32 v50, v50, v63
	v_fmac_f32_e32 v151, v55, v55
	s_waitcnt lgkmcnt(3)
	v_sub_f32_e32 v63, v157, v60
	v_sub_f32_e32 v62, v156, v61
	s_waitcnt lgkmcnt(2)
	v_sub_f32_e32 v61, v57, v64
	v_sub_f32_e32 v60, v56, v65
	s_waitcnt lgkmcnt(1)
	v_sub_f32_e32 v59, v59, v86
	v_sub_f32_e32 v58, v58, v87
	s_waitcnt lgkmcnt(0)
	v_sub_f32_e32 v56, v95, v152
	v_sub_f32_e32 v57, v94, v153
	ds_read2st64_b32 v[64:65], v143 offset0:64 offset1:65
	ds_read2st64_b32 v[86:87], v143 offset0:66 offset1:67
	ds_read2st64_b32 v[94:95], v143 offset0:68 offset1:69
	ds_read2st64_b32 v[152:153], v143 offset0:70 offset1:71
	v_fmac_f32_e32 v148, v54, v54
	v_fmac_f32_e32 v144, v7, v7
	s_waitcnt lgkmcnt(2)
	v_sub_f32_e32 v66, v66, v86
	v_sub_f32_e32 v64, v69, v64
	v_sub_f32_e32 v65, v68, v65
	v_sub_f32_e32 v67, v67, v87
	s_waitcnt lgkmcnt(1)
	v_sub_f32_e32 v68, v73, v94
	v_sub_f32_e32 v69, v72, v95
	s_waitcnt lgkmcnt(0)
	v_sub_f32_e32 v70, v70, v152
	v_sub_f32_e32 v71, v71, v153
	ds_read2st64_b32 v[72:73], v143 offset0:72 offset1:73
	ds_read2st64_b32 v[86:87], v143 offset0:74 offset1:75
	ds_read2st64_b32 v[94:95], v143 offset0:76 offset1:77
	ds_read2st64_b32 v[152:153], v143 offset0:78 offset1:79
	v_fmac_f32_e32 v151, v64, v64
	v_fmac_f32_e32 v148, v65, v65
	s_waitcnt lgkmcnt(2)
	v_sub_f32_e32 v74, v74, v86
	v_sub_f32_e32 v72, v77, v72
	v_sub_f32_e32 v73, v76, v73
	s_waitcnt lgkmcnt(1)
	v_sub_f32_e32 v76, v81, v94
	v_sub_f32_e32 v77, v80, v95
	s_waitcnt lgkmcnt(0)
	v_sub_f32_e32 v78, v78, v152
	v_sub_f32_e32 v79, v79, v153
	ds_read2st64_b32 v[80:81], v143 offset0:80 offset1:81
	ds_read2st64_b32 v[94:95], v143 offset0:82 offset1:83
	ds_read2st64_b32 v[152:153], v143 offset0:84 offset1:85
	ds_read2st64_b32 v[154:155], v143 offset0:86 offset1:87
	v_sub_f32_e32 v75, v75, v87
	v_sub_f32_e32 v34, v159, v34
	v_fmac_f32_e32 v144, v34, v34
	s_waitcnt lgkmcnt(3)
	v_sub_f32_e32 v87, v85, v80
	v_sub_f32_e32 v86, v84, v81
	s_waitcnt lgkmcnt(2)
	v_sub_f32_e32 v85, v83, v94
	v_sub_f32_e32 v84, v82, v95
	s_waitcnt lgkmcnt(1)
	v_sub_f32_e32 v83, v147, v152
	v_sub_f32_e32 v82, v146, v153
	s_waitcnt lgkmcnt(0)
	v_sub_f32_e32 v80, v89, v154
	v_sub_f32_e32 v81, v88, v155
	ds_read2st64_b32 v[88:89], v143 offset0:88 offset1:89
	ds_read2st64_b32 v[146:147], v143 offset0:90 offset1:91
	ds_read2st64_b32 v[152:153], v143 offset0:92 offset1:93
	ds_read2st64_b32 v[154:155], v143 offset0:94 offset1:95
	v_fmac_f32_e32 v151, v87, v87
	v_fmac_f32_e32 v148, v86, v86
	v_fmac_f32_e32 v144, v53, v53
	s_waitcnt lgkmcnt(3)
	v_sub_f32_e32 v95, v93, v88
	v_sub_f32_e32 v94, v92, v89
	s_waitcnt lgkmcnt(2)
	v_sub_f32_e32 v93, v91, v146
	v_sub_f32_e32 v92, v90, v147
	s_waitcnt lgkmcnt(1)
	v_sub_f32_e32 v91, v150, v152
	v_sub_f32_e32 v90, v149, v153
	s_waitcnt lgkmcnt(0)
	v_sub_f32_e32 v88, v97, v154
	v_sub_f32_e32 v89, v96, v155
	ds_read2st64_b32 v[96:97], v143 offset0:96 offset1:97
	ds_read2st64_b32 v[146:147], v143 offset0:98 offset1:99
	ds_read2st64_b32 v[152:153], v143 offset0:100 offset1:101
	ds_read2st64_b32 v[154:155], v143 offset0:102 offset1:103
	v_fmac_f32_e32 v144, v66, v66
	v_fmac_f32_e32 v144, v85, v85
	s_waitcnt lgkmcnt(2)
	v_sub_f32_e32 v98, v98, v146
	v_sub_f32_e32 v96, v101, v96
	v_sub_f32_e32 v97, v100, v97
	v_sub_f32_e32 v99, v99, v147
	s_waitcnt lgkmcnt(1)
	v_sub_f32_e32 v100, v105, v152
	v_sub_f32_e32 v101, v104, v153
	s_waitcnt lgkmcnt(0)
	v_sub_f32_e32 v102, v102, v154
	v_sub_f32_e32 v103, v103, v155
	ds_read2st64_b32 v[104:105], v143 offset0:104 offset1:105
	ds_read2st64_b32 v[146:147], v143 offset0:106 offset1:107
	ds_read2st64_b32 v[152:153], v143 offset0:108 offset1:109
	ds_read2st64_b32 v[154:155], v143 offset0:110 offset1:111
	v_fmac_f32_e32 v151, v96, v96
	v_fmac_f32_e32 v148, v97, v97
	s_waitcnt lgkmcnt(2)
	v_sub_f32_e32 v106, v106, v146
	v_sub_f32_e32 v107, v107, v147
	ds_read2st64_b32 v[146:147], v143 offset0:112 offset1:113
	v_sub_f32_e32 v104, v109, v104
	v_sub_f32_e32 v105, v108, v105
	s_waitcnt lgkmcnt(2)
	v_sub_f32_e32 v108, v145, v152
	v_sub_f32_e32 v109, v113, v153
	s_waitcnt lgkmcnt(1)
	v_sub_f32_e32 v110, v110, v154
	v_sub_f32_e32 v111, v111, v155
	ds_read2st64_b32 v[152:153], v143 offset0:114 offset1:115
	ds_read2st64_b32 v[154:155], v143 offset0:116 offset1:117
	ds_read2st64_b32 v[156:157], v143 offset0:118 offset1:119
	s_waitcnt lgkmcnt(3)
	v_sub_f32_e32 v117, v117, v146
	v_fmac_f32_e32 v151, v117, v117
	v_sub_f32_e32 v116, v116, v147
	s_waitcnt lgkmcnt(1)
	v_sub_f32_e32 v113, v121, v154
	ds_bpermute_b32 v121, v213, v151
	ds_read2st64_b32 v[146:147], v143 offset0:120 offset1:121
	v_sub_f32_e32 v115, v115, v152
	v_sub_f32_e32 v114, v114, v153
	v_sub_f32_e32 v119, v119, v155
	s_waitcnt lgkmcnt(1)
	v_add_f32_e32 v121, v151, v121
	ds_bpermute_b32 v145, v214, v121
	ds_read2st64_b32 v[150:151], v143 offset0:122 offset1:123
	ds_read2st64_b32 v[152:153], v143 offset0:124 offset1:125
	ds_read2st64_b32 v[154:155], v143 offset0:126 offset1:127
	v_fmac_f32_e32 v148, v116, v116
	s_waitcnt lgkmcnt(4)
	v_sub_f32_e32 v124, v124, v147
	ds_bpermute_b32 v147, v213, v148
	s_waitcnt lgkmcnt(4)
	v_add_f32_e32 v145, v121, v145
	ds_bpermute_b32 v149, v215, v145
	v_sub_f32_e32 v121, v125, v146
	v_fmac_f32_e32 v144, v98, v98
	s_waitcnt lgkmcnt(1)
	v_add_f32_e32 v147, v148, v147
	ds_bpermute_b32 v148, v214, v147
	s_waitcnt lgkmcnt(1)
	v_add_f32_e32 v125, v145, v149
	ds_bpermute_b32 v143, v216, v125
	v_fmac_f32_e32 v144, v115, v115
	v_sub_f32_e32 v122, v122, v150
	v_mul_f32_e32 v131, v20, v20
	v_fmac_f32_e32 v131, v5, v5
	s_waitcnt lgkmcnt(0)
	v_add_f32_e32 v143, v125, v143
	ds_bpermute_b32 v145, v217, v143
	v_sub_f32_e32 v125, v123, v151
	v_sub_f32_e32 v123, v129, v152
	ds_bpermute_b32 v151, v213, v144
	v_sub_f32_e32 v35, v158, v35
	s_waitcnt lgkmcnt(1)
	v_add_f32_e32 v129, v143, v145
	v_fmamk_f32 v129, v129, 0x3b800000, v244
	v_mul_f32_e32 v143, 0x4f800000, v129
	v_cmp_gt_f32_e32 vcc, s25, v129
	s_waitcnt lgkmcnt(0)
	v_add_f32_e32 v144, v144, v151
	ds_bpermute_b32 v151, v214, v144
	v_cndmask_b32_e32 v129, v129, v143, vcc
	v_sqrt_f32_e32 v143, v129
	v_fmac_f32_e32 v131, v35, v35
	v_fmac_f32_e32 v131, v52, v52
	s_waitcnt lgkmcnt(0)
	v_add_f32_e32 v144, v144, v151
	v_add_u32_e32 v145, -1, v143
	v_fma_f32 v146, -v145, v143, v129
	v_cmp_ge_f32_e64 s[0:1], 0, v146
	v_add_u32_e32 v146, 1, v143
	v_fmac_f32_e32 v131, v67, v67
	v_cndmask_b32_e64 v145, v143, v145, s[0:1]
	v_fma_f32 v143, -v146, v143, v129
	v_cmp_lt_f32_e64 s[0:1], 0, v143
	v_fmac_f32_e32 v131, v84, v84
	v_fmac_f32_e32 v131, v99, v99
	v_cndmask_b32_e64 v143, v145, v146, s[0:1]
	v_mul_f32_e32 v145, 0x37800000, v143
	v_cndmask_b32_e32 v143, v143, v145, vcc
	v_add_f32_e32 v145, v147, v148
	ds_bpermute_b32 v146, v215, v145
	v_cmp_class_f32_e32 vcc, v129, v245
	v_fmac_f32_e32 v131, v114, v114
	ds_bpermute_b32 v151, v213, v131
	v_cndmask_b32_e32 v129, v143, v129, vcc
	s_waitcnt lgkmcnt(1)
	v_add_f32_e32 v145, v145, v146
	ds_bpermute_b32 v146, v216, v145
	v_div_scale_f32 v143, s[0:1], v129, v129, s26
	v_rcp_f32_e32 v147, v143
	s_waitcnt lgkmcnt(1)
	v_add_f32_e32 v131, v131, v151
	s_waitcnt lgkmcnt(0)
	v_add_f32_e32 v145, v145, v146
	ds_bpermute_b32 v146, v217, v145
	v_fma_f32 v148, -v143, v147, 1.0
	v_fmac_f32_e32 v147, v148, v147
	v_div_scale_f32 v148, vcc, s26, v129, s26
	s_waitcnt lgkmcnt(0)
	v_add_f32_e32 v145, v145, v146
	v_fmamk_f32 v145, v145, 0x3b800000, v244
	v_mul_f32_e32 v146, 0x4f800000, v145
	v_cmp_gt_f32_e64 s[0:1], s25, v145
	v_mul_f32_e32 v149, v148, v147
	v_fma_f32 v150, -v143, v149, v148
	v_cndmask_b32_e64 v145, v145, v146, s[0:1]
	v_sqrt_f32_e32 v146, v145
	v_fmac_f32_e32 v149, v150, v147
	v_fma_f32 v143, -v143, v149, v148
	v_div_fmas_f32 v143, v143, v147, v149
	v_add_u32_e32 v148, -1, v146
	v_fma_f32 v150, -v148, v146, v145
	v_cmp_ge_f32_e64 s[2:3], 0, v150
	v_add_u32_e32 v150, 1, v146
	v_div_fixup_f32 v129, v143, v129, s26
	v_cndmask_b32_e64 v148, v146, v148, s[2:3]
	v_fma_f32 v146, -v150, v146, v145
	v_cmp_lt_f32_e64 s[2:3], 0, v146
	ds_bpermute_b32 v151, v214, v131
	v_mul_f32_e32 v133, v19, v19
	v_cndmask_b32_e64 v146, v148, v150, s[2:3]
	v_mul_f32_e32 v148, 0x37800000, v146
	v_cndmask_b32_e64 v146, v146, v148, s[0:1]
	ds_bpermute_b32 v148, v215, v144
	v_cmp_class_f32_e64 s[0:1], v145, v245
	s_waitcnt lgkmcnt(1)
	v_add_f32_e32 v131, v131, v151
	v_fmac_f32_e32 v133, v4, v4
	v_cndmask_b32_e64 v145, v146, v145, s[0:1]
	s_waitcnt lgkmcnt(0)
	v_add_f32_e32 v144, v144, v148
	ds_bpermute_b32 v148, v216, v144
	v_div_scale_f32 v146, s[0:1], v145, v145, s26
	v_rcp_f32_e32 v150, v146
	v_fmac_f32_e32 v133, v36, v36
	s_waitcnt lgkmcnt(0)
	v_add_f32_e32 v144, v144, v148
	ds_bpermute_b32 v147, v217, v144
	v_fma_f32 v143, -v146, v150, 1.0
	v_fmac_f32_e32 v150, v143, v150
	v_div_scale_f32 v143, vcc, s26, v145, s26
	s_waitcnt lgkmcnt(0)
	v_add_f32_e32 v144, v144, v147
	v_fmamk_f32 v144, v144, 0x3b800000, v244
	v_mul_f32_e32 v147, 0x4f800000, v144
	v_cmp_gt_f32_e64 s[0:1], s25, v144
	v_mul_f32_e32 v148, v143, v150
	v_fma_f32 v149, -v146, v148, v143
	v_cndmask_b32_e64 v144, v144, v147, s[0:1]
	v_sqrt_f32_e32 v147, v144
	v_fmac_f32_e32 v148, v149, v150
	v_fma_f32 v143, -v146, v148, v143
	v_fmac_f32_e32 v133, v51, v51
	v_add_u32_e32 v146, -1, v147
	v_fma_f32 v149, -v146, v147, v144
	v_cmp_ge_f32_e64 s[2:3], 0, v149
	v_add_u32_e32 v149, 1, v147
	v_fmac_f32_e32 v133, v68, v68
	v_cndmask_b32_e64 v146, v147, v146, s[2:3]
	v_fma_f32 v147, -v149, v147, v144
	v_cmp_lt_f32_e64 s[2:3], 0, v147
	v_fmac_f32_e32 v133, v83, v83
	v_fmac_f32_e32 v133, v100, v100
	v_cndmask_b32_e64 v146, v146, v149, s[2:3]
	v_mul_f32_e32 v147, 0x37800000, v146
	v_cndmask_b32_e64 v146, v146, v147, s[0:1]
	ds_bpermute_b32 v147, v215, v131
	v_cmp_class_f32_e64 s[0:1], v144, v245
	v_fmac_f32_e32 v133, v113, v113
	v_mul_f32_e32 v135, v18, v18
	v_cndmask_b32_e64 v144, v146, v144, s[0:1]
	s_waitcnt lgkmcnt(0)
	v_add_f32_e32 v147, v131, v147
	ds_bpermute_b32 v151, v216, v147
	v_div_fmas_f32 v131, v143, v150, v148
	v_div_fixup_f32 v131, v131, v145, s26
	v_div_scale_f32 v146, s[0:1], v144, v144, s26
	s_waitcnt lgkmcnt(0)
	v_add_f32_e32 v145, v147, v151
	ds_bpermute_b32 v147, v217, v145
	v_rcp_f32_e32 v149, v146
	ds_bpermute_b32 v151, v213, v133
	v_fmac_f32_e32 v135, v2, v2
	v_fmac_f32_e32 v135, v37, v37
	s_waitcnt lgkmcnt(1)
	v_add_f32_e32 v145, v145, v147
	v_fmamk_f32 v145, v145, 0x3b800000, v244
	v_mul_f32_e32 v147, 0x4f800000, v145
	v_cmp_gt_f32_e64 s[0:1], s25, v145
	v_fma_f32 v143, -v146, v149, 1.0
	v_fmac_f32_e32 v149, v143, v149
	v_cndmask_b32_e64 v145, v145, v147, s[0:1]
	v_div_scale_f32 v143, vcc, s26, v144, s26
	v_sqrt_f32_e32 v147, v145
	v_mul_f32_e32 v148, v143, v149
	v_fma_f32 v150, -v146, v148, v143
	v_fmac_f32_e32 v148, v150, v149
	v_fma_f32 v143, -v146, v148, v143
	v_add_u32_e32 v146, -1, v147
	s_waitcnt lgkmcnt(0)
	v_add_f32_e32 v133, v133, v151
	v_fma_f32 v150, -v146, v147, v145
	ds_bpermute_b32 v151, v214, v133
	v_cmp_ge_f32_e64 s[2:3], 0, v150
	v_add_u32_e32 v150, 1, v147
	v_fmac_f32_e32 v135, v50, v50
	v_cndmask_b32_e64 v146, v147, v146, s[2:3]
	v_fma_f32 v147, -v150, v147, v145
	v_cmp_lt_f32_e64 s[2:3], 0, v147
	s_waitcnt lgkmcnt(0)
	v_add_f32_e32 v133, v133, v151
	v_fmac_f32_e32 v135, v69, v69
	v_cndmask_b32_e64 v146, v146, v150, s[2:3]
	v_mul_f32_e32 v147, 0x37800000, v146
	v_cndmask_b32_e64 v146, v146, v147, s[0:1]
	ds_bpermute_b32 v147, v215, v133
	v_cmp_class_f32_e64 s[0:1], v145, v245
	v_fmac_f32_e32 v135, v82, v82
	v_fmac_f32_e32 v135, v101, v101
	v_cndmask_b32_e64 v145, v146, v145, s[0:1]
	s_waitcnt lgkmcnt(0)
	v_add_f32_e32 v147, v133, v147
	ds_bpermute_b32 v151, v216, v147
	v_div_fmas_f32 v133, v143, v149, v148
	v_div_fixup_f32 v133, v133, v144, s26
	v_div_scale_f32 v146, s[0:1], v145, v145, s26
	s_waitcnt lgkmcnt(0)
	v_add_f32_e32 v144, v147, v151
	ds_bpermute_b32 v147, v217, v144
	v_rcp_f32_e32 v150, v146
	v_fmac_f32_e32 v135, v119, v119
	ds_bpermute_b32 v151, v213, v135
	v_mul_f32_e32 v137, v16, v16
	s_waitcnt lgkmcnt(1)
	v_add_f32_e32 v144, v144, v147
	v_fmamk_f32 v144, v144, 0x3b800000, v244
	v_mul_f32_e32 v147, 0x4f800000, v144
	v_cmp_gt_f32_e64 s[0:1], s25, v144
	v_fma_f32 v143, -v146, v150, 1.0
	v_fmac_f32_e32 v150, v143, v150
	v_cndmask_b32_e64 v144, v144, v147, s[0:1]
	v_div_scale_f32 v143, vcc, s26, v145, s26
	v_sqrt_f32_e32 v147, v144
	v_mul_f32_e32 v148, v143, v150
	v_fma_f32 v149, -v146, v148, v143
	v_fmac_f32_e32 v148, v149, v150
	v_fma_f32 v143, -v146, v148, v143
	v_add_u32_e32 v146, -1, v147
	s_waitcnt lgkmcnt(0)
	v_add_f32_e32 v135, v135, v151
	v_fma_f32 v149, -v146, v147, v144
	ds_bpermute_b32 v151, v214, v135
	v_cmp_ge_f32_e64 s[2:3], 0, v149
	v_add_u32_e32 v149, 1, v147
	v_fmac_f32_e32 v137, v0, v0
	v_cndmask_b32_e64 v146, v147, v146, s[2:3]
	v_fma_f32 v147, -v149, v147, v144
	v_cmp_lt_f32_e64 s[2:3], 0, v147
	s_waitcnt lgkmcnt(0)
	v_add_f32_e32 v135, v135, v151
	v_fmac_f32_e32 v137, v38, v38
	v_cndmask_b32_e64 v146, v146, v149, s[2:3]
	v_mul_f32_e32 v147, 0x37800000, v146
	v_cndmask_b32_e64 v146, v146, v147, s[0:1]
	ds_bpermute_b32 v147, v215, v135
	v_cmp_class_f32_e64 s[0:1], v144, v245
	v_fmac_f32_e32 v137, v48, v48
	v_fmac_f32_e32 v137, v70, v70
	v_cndmask_b32_e64 v144, v146, v144, s[0:1]
	s_waitcnt lgkmcnt(0)
	v_add_f32_e32 v147, v135, v147
	ds_bpermute_b32 v151, v216, v147
	v_div_fmas_f32 v135, v143, v150, v148
	v_div_fixup_f32 v135, v135, v145, s26
	v_div_scale_f32 v146, s[0:1], v144, v144, s26
	s_waitcnt lgkmcnt(0)
	v_add_f32_e32 v145, v147, v151
	ds_bpermute_b32 v147, v217, v145
	v_rcp_f32_e32 v149, v146
	v_fmac_f32_e32 v137, v80, v80
	v_fmac_f32_e32 v137, v102, v102
	v_sub_f32_e32 v118, v118, v156
	s_waitcnt lgkmcnt(0)
	v_add_f32_e32 v145, v145, v147
	v_fmamk_f32 v145, v145, 0x3b800000, v244
	v_fmac_f32_e32 v137, v118, v118
	v_mul_f32_e32 v147, 0x4f800000, v145
	v_cmp_gt_f32_e64 s[0:1], s25, v145
	v_fma_f32 v143, -v146, v149, 1.0
	ds_bpermute_b32 v151, v213, v137
	v_cndmask_b32_e64 v145, v145, v147, s[0:1]
	v_fmac_f32_e32 v149, v143, v149
	v_div_scale_f32 v143, vcc, s26, v144, s26
	v_sqrt_f32_e32 v147, v145
	v_mul_f32_e32 v148, v143, v149
	v_fma_f32 v150, -v146, v148, v143
	v_fmac_f32_e32 v148, v150, v149
	v_fma_f32 v143, -v146, v148, v143
	v_add_u32_e32 v146, -1, v147
	s_waitcnt lgkmcnt(0)
	v_add_f32_e32 v137, v137, v151
	v_fma_f32 v150, -v146, v147, v145
	ds_bpermute_b32 v151, v214, v137
	v_cmp_ge_f32_e64 s[2:3], 0, v150
	v_add_u32_e32 v150, 1, v147
	v_mul_f32_e32 v139, v17, v17
	v_cndmask_b32_e64 v146, v147, v146, s[2:3]
	v_fma_f32 v147, -v150, v147, v145
	v_cmp_lt_f32_e64 s[2:3], 0, v147
	s_waitcnt lgkmcnt(0)
	v_add_f32_e32 v137, v137, v151
	v_fmac_f32_e32 v139, v3, v3
	v_cndmask_b32_e64 v146, v146, v150, s[2:3]
	v_mul_f32_e32 v147, 0x37800000, v146
	v_cndmask_b32_e64 v146, v146, v147, s[0:1]
	ds_bpermute_b32 v147, v215, v137
	v_cmp_class_f32_e64 s[0:1], v145, v245
	v_fmac_f32_e32 v139, v39, v39
	v_fmac_f32_e32 v139, v49, v49
	v_cndmask_b32_e64 v145, v146, v145, s[0:1]
	s_waitcnt lgkmcnt(0)
	v_add_f32_e32 v147, v137, v147
	ds_bpermute_b32 v151, v216, v147
	v_div_fmas_f32 v137, v143, v149, v148
	v_div_fixup_f32 v137, v137, v144, s26
	v_div_scale_f32 v146, s[0:1], v145, v145, s26
	s_waitcnt lgkmcnt(0)
	v_add_f32_e32 v144, v147, v151
	ds_bpermute_b32 v147, v217, v144
	v_fmac_f32_e32 v139, v71, v71
	v_rcp_f32_e32 v150, v146
	v_fmac_f32_e32 v139, v81, v81
	v_fmac_f32_e32 v139, v103, v103
	s_waitcnt lgkmcnt(0)
	v_add_f32_e32 v144, v144, v147
	v_sub_f32_e32 v120, v120, v157
	v_fmamk_f32 v144, v144, 0x3b800000, v244
	v_fmac_f32_e32 v139, v120, v120
	v_mul_f32_e32 v147, 0x4f800000, v144
	v_cmp_gt_f32_e64 s[0:1], s25, v144
	v_fma_f32 v143, -v146, v150, 1.0
	ds_bpermute_b32 v151, v213, v139
	v_cndmask_b32_e64 v144, v144, v147, s[0:1]
	v_fmac_f32_e32 v150, v143, v150
	v_div_scale_f32 v143, vcc, s26, v145, s26
	v_sqrt_f32_e32 v147, v144
	v_mul_f32_e32 v148, v143, v150
	v_fma_f32 v149, -v146, v148, v143
	v_fmac_f32_e32 v148, v149, v150
	v_fma_f32 v143, -v146, v148, v143
	v_add_u32_e32 v146, -1, v147
	s_waitcnt lgkmcnt(0)
	v_add_f32_e32 v139, v139, v151
	v_fma_f32 v149, -v146, v147, v144
	ds_bpermute_b32 v151, v214, v139
	v_cmp_ge_f32_e64 s[2:3], 0, v149
	v_add_u32_e32 v149, 1, v147
	v_mul_f32_e32 v141, v31, v31
	v_cndmask_b32_e64 v146, v147, v146, s[2:3]
	v_fma_f32 v147, -v149, v147, v144
	v_cmp_lt_f32_e64 s[2:3], 0, v147
	s_waitcnt lgkmcnt(0)
	v_add_f32_e32 v139, v139, v151
	v_fmac_f32_e32 v141, v15, v15
	v_cndmask_b32_e64 v146, v146, v149, s[2:3]
	v_mul_f32_e32 v147, 0x37800000, v146
	v_cndmask_b32_e64 v146, v146, v147, s[0:1]
	ds_bpermute_b32 v147, v215, v139
	v_cmp_class_f32_e64 s[0:1], v144, v245
	v_fmac_f32_e32 v141, v40, v40
	v_fmac_f32_e32 v141, v63, v63
	v_cndmask_b32_e64 v144, v146, v144, s[0:1]
	s_waitcnt lgkmcnt(0)
	v_add_f32_e32 v147, v139, v147
	ds_bpermute_b32 v151, v216, v147
	v_div_fmas_f32 v139, v143, v150, v148
	v_div_fixup_f32 v139, v139, v145, s26
	v_div_scale_f32 v146, s[0:1], v144, v144, s26
	s_waitcnt lgkmcnt(0)
	v_add_f32_e32 v145, v147, v151
	ds_bpermute_b32 v147, v217, v145
	v_fmac_f32_e32 v141, v72, v72
	v_rcp_f32_e32 v149, v146
	v_fmac_f32_e32 v141, v95, v95
	v_fmac_f32_e32 v141, v104, v104
	s_waitcnt lgkmcnt(0)
	v_add_f32_e32 v145, v145, v147
	v_fmamk_f32 v145, v145, 0x3b800000, v244
	v_fmac_f32_e32 v141, v121, v121
	v_mul_f32_e32 v147, 0x4f800000, v145
	v_cmp_gt_f32_e64 s[0:1], s25, v145
	v_fma_f32 v143, -v146, v149, 1.0
	ds_bpermute_b32 v151, v213, v141
	v_cndmask_b32_e64 v145, v145, v147, s[0:1]
	v_fmac_f32_e32 v149, v143, v149
	v_div_scale_f32 v143, vcc, s26, v144, s26
	v_sqrt_f32_e32 v147, v145
	v_mul_f32_e32 v148, v143, v149
	v_fma_f32 v150, -v146, v148, v143
	v_fmac_f32_e32 v148, v150, v149
	v_fma_f32 v143, -v146, v148, v143
	v_add_u32_e32 v146, -1, v147
	s_waitcnt lgkmcnt(0)
	v_add_f32_e32 v141, v141, v151
	v_fma_f32 v150, -v146, v147, v145
	ds_bpermute_b32 v151, v214, v141
	v_cmp_ge_f32_e64 s[2:3], 0, v150
	v_add_u32_e32 v150, 1, v147
	v_mul_f32_e32 v142, v30, v30
	v_cndmask_b32_e64 v146, v147, v146, s[2:3]
	v_fma_f32 v147, -v150, v147, v145
	v_cmp_lt_f32_e64 s[2:3], 0, v147
	s_waitcnt lgkmcnt(0)
	v_add_f32_e32 v141, v141, v151
	v_fmac_f32_e32 v142, v14, v14
	v_cndmask_b32_e64 v146, v146, v150, s[2:3]
	v_mul_f32_e32 v147, 0x37800000, v146
	v_cndmask_b32_e64 v146, v146, v147, s[0:1]
	ds_bpermute_b32 v147, v215, v141
	v_cmp_class_f32_e64 s[0:1], v145, v245
	v_fmac_f32_e32 v142, v41, v41
	v_fmac_f32_e32 v142, v62, v62
	v_cndmask_b32_e64 v145, v146, v145, s[0:1]
	s_waitcnt lgkmcnt(0)
	v_add_f32_e32 v147, v141, v147
	ds_bpermute_b32 v151, v216, v147
	v_div_fmas_f32 v141, v143, v149, v148
	v_div_fixup_f32 v141, v141, v144, s26
	v_div_scale_f32 v146, s[0:1], v145, v145, s26
	s_waitcnt lgkmcnt(0)
	v_add_f32_e32 v144, v147, v151
	ds_bpermute_b32 v147, v217, v144
	v_fmac_f32_e32 v142, v73, v73
	v_rcp_f32_e32 v150, v146
	v_fmac_f32_e32 v142, v94, v94
	v_fmac_f32_e32 v142, v105, v105
	s_waitcnt lgkmcnt(0)
	v_add_f32_e32 v144, v144, v147
	v_fmamk_f32 v144, v144, 0x3b800000, v244
	v_fmac_f32_e32 v142, v124, v124
	v_mul_f32_e32 v147, 0x4f800000, v144
	v_cmp_gt_f32_e64 s[0:1], s25, v144
	v_fma_f32 v143, -v146, v150, 1.0
	ds_bpermute_b32 v151, v213, v142
	v_cndmask_b32_e64 v144, v144, v147, s[0:1]
	v_fmac_f32_e32 v150, v143, v150
	v_div_scale_f32 v143, vcc, s26, v145, s26
	v_sqrt_f32_e32 v147, v144
	v_mul_f32_e32 v148, v143, v150
	v_fma_f32 v149, -v146, v148, v143
	v_fmac_f32_e32 v148, v149, v150
	v_fma_f32 v143, -v146, v148, v143
	v_add_u32_e32 v146, -1, v147
	s_waitcnt lgkmcnt(0)
	v_add_f32_e32 v142, v142, v151
	v_fma_f32 v149, -v146, v147, v144
	ds_bpermute_b32 v151, v214, v142
	v_cmp_ge_f32_e64 s[2:3], 0, v149
	v_add_u32_e32 v149, 1, v147
	v_mul_f32_e32 v140, v29, v29
	v_cndmask_b32_e64 v146, v147, v146, s[2:3]
	v_fma_f32 v147, -v149, v147, v144
	v_cmp_lt_f32_e64 s[2:3], 0, v147
	s_waitcnt lgkmcnt(0)
	v_add_f32_e32 v142, v142, v151
	v_fmac_f32_e32 v140, v13, v13
	v_cndmask_b32_e64 v146, v146, v149, s[2:3]
	v_mul_f32_e32 v147, 0x37800000, v146
	v_cndmask_b32_e64 v146, v146, v147, s[0:1]
	ds_bpermute_b32 v147, v215, v142
	v_cmp_class_f32_e64 s[0:1], v144, v245
	v_fmac_f32_e32 v140, v42, v42
	v_fmac_f32_e32 v140, v61, v61
	v_cndmask_b32_e64 v144, v146, v144, s[0:1]
	s_waitcnt lgkmcnt(0)
	v_add_f32_e32 v147, v142, v147
	ds_bpermute_b32 v151, v216, v147
	v_div_fmas_f32 v142, v143, v150, v148
	v_div_fixup_f32 v142, v142, v145, s26
	v_div_scale_f32 v146, s[0:1], v144, v144, s26
	s_waitcnt lgkmcnt(0)
	v_add_f32_e32 v145, v147, v151
	ds_bpermute_b32 v147, v217, v145
	v_fmac_f32_e32 v140, v74, v74
	v_rcp_f32_e32 v149, v146
	v_fmac_f32_e32 v140, v93, v93
	v_fmac_f32_e32 v140, v106, v106
	s_waitcnt lgkmcnt(0)
	v_add_f32_e32 v145, v145, v147
	v_fmamk_f32 v145, v145, 0x3b800000, v244
	v_fmac_f32_e32 v140, v122, v122
	v_mul_f32_e32 v147, 0x4f800000, v145
	v_cmp_gt_f32_e64 s[0:1], s25, v145
	v_fma_f32 v143, -v146, v149, 1.0
	ds_bpermute_b32 v151, v213, v140
	v_cndmask_b32_e64 v145, v145, v147, s[0:1]
	v_fmac_f32_e32 v149, v143, v149
	v_div_scale_f32 v143, vcc, s26, v144, s26
	v_sqrt_f32_e32 v147, v145
	v_mul_f32_e32 v148, v143, v149
	v_fma_f32 v150, -v146, v148, v143
	v_fmac_f32_e32 v148, v150, v149
	v_fma_f32 v143, -v146, v148, v143
	v_add_u32_e32 v146, -1, v147
	s_waitcnt lgkmcnt(0)
	v_add_f32_e32 v140, v140, v151
	v_fma_f32 v150, -v146, v147, v145
	ds_bpermute_b32 v151, v214, v140
	v_cmp_ge_f32_e64 s[2:3], 0, v150
	v_add_u32_e32 v150, 1, v147
	v_mul_f32_e32 v138, v28, v28
	v_cndmask_b32_e64 v146, v147, v146, s[2:3]
	v_fma_f32 v147, -v150, v147, v145
	v_cmp_lt_f32_e64 s[2:3], 0, v147
	s_waitcnt lgkmcnt(0)
	v_add_f32_e32 v140, v140, v151
	v_fmac_f32_e32 v138, v12, v12
	v_cndmask_b32_e64 v146, v146, v150, s[2:3]
	v_mul_f32_e32 v147, 0x37800000, v146
	v_cndmask_b32_e64 v146, v146, v147, s[0:1]
	ds_bpermute_b32 v147, v215, v140
	v_cmp_class_f32_e64 s[0:1], v145, v245
	v_fmac_f32_e32 v138, v43, v43
	v_fmac_f32_e32 v138, v60, v60
	v_cndmask_b32_e64 v145, v146, v145, s[0:1]
	s_waitcnt lgkmcnt(0)
	v_add_f32_e32 v147, v140, v147
	ds_bpermute_b32 v151, v216, v147
	v_div_fmas_f32 v140, v143, v149, v148
	v_div_fixup_f32 v140, v140, v144, s26
	v_div_scale_f32 v146, s[0:1], v145, v145, s26
	s_waitcnt lgkmcnt(0)
	v_add_f32_e32 v144, v147, v151
	ds_bpermute_b32 v147, v217, v144
	v_fmac_f32_e32 v138, v75, v75
	v_rcp_f32_e32 v150, v146
	v_fmac_f32_e32 v138, v92, v92
	v_fmac_f32_e32 v138, v107, v107
	s_waitcnt lgkmcnt(0)
	v_add_f32_e32 v144, v144, v147
	v_fmamk_f32 v144, v144, 0x3b800000, v244
	v_fmac_f32_e32 v138, v125, v125
	v_mul_f32_e32 v147, 0x4f800000, v144
	v_cmp_gt_f32_e64 s[0:1], s25, v144
	v_fma_f32 v143, -v146, v150, 1.0
	ds_bpermute_b32 v151, v213, v138
	v_cndmask_b32_e64 v144, v144, v147, s[0:1]
	v_fmac_f32_e32 v150, v143, v150
	v_div_scale_f32 v143, vcc, s26, v145, s26
	v_sqrt_f32_e32 v147, v144
	v_mul_f32_e32 v148, v143, v150
	v_fma_f32 v149, -v146, v148, v143
	v_fmac_f32_e32 v148, v149, v150
	v_fma_f32 v143, -v146, v148, v143
	v_add_u32_e32 v146, -1, v147
	s_waitcnt lgkmcnt(0)
	v_add_f32_e32 v138, v138, v151
	v_fma_f32 v149, -v146, v147, v144
	ds_bpermute_b32 v151, v214, v138
	v_cmp_ge_f32_e64 s[2:3], 0, v149
	v_add_u32_e32 v149, 1, v147
	v_mul_f32_e32 v136, v27, v27
	v_cndmask_b32_e64 v146, v147, v146, s[2:3]
	v_fma_f32 v147, -v149, v147, v144
	v_cmp_lt_f32_e64 s[2:3], 0, v147
	s_waitcnt lgkmcnt(0)
	v_add_f32_e32 v138, v138, v151
	v_fmac_f32_e32 v136, v11, v11
	v_cndmask_b32_e64 v146, v146, v149, s[2:3]
	v_mul_f32_e32 v147, 0x37800000, v146
	v_cndmask_b32_e64 v146, v146, v147, s[0:1]
	ds_bpermute_b32 v147, v215, v138
	v_cmp_class_f32_e64 s[0:1], v144, v245
	v_fmac_f32_e32 v136, v44, v44
	v_fmac_f32_e32 v136, v59, v59
	v_cndmask_b32_e64 v144, v146, v144, s[0:1]
	s_waitcnt lgkmcnt(0)
	v_add_f32_e32 v147, v138, v147
	ds_bpermute_b32 v151, v216, v147
	v_div_fmas_f32 v138, v143, v150, v148
	v_div_fixup_f32 v138, v138, v145, s26
	v_div_scale_f32 v146, s[0:1], v144, v144, s26
	s_waitcnt lgkmcnt(0)
	v_add_f32_e32 v145, v147, v151
	ds_bpermute_b32 v147, v217, v145
	v_fmac_f32_e32 v136, v76, v76
	v_rcp_f32_e32 v149, v146
	v_fmac_f32_e32 v136, v91, v91
	v_fmac_f32_e32 v136, v108, v108
	s_waitcnt lgkmcnt(0)
	v_add_f32_e32 v145, v145, v147
	v_fmamk_f32 v145, v145, 0x3b800000, v244
	v_fmac_f32_e32 v136, v123, v123
	v_mul_f32_e32 v147, 0x4f800000, v145
	v_cmp_gt_f32_e64 s[0:1], s25, v145
	v_fma_f32 v143, -v146, v149, 1.0
	ds_bpermute_b32 v151, v213, v136
	v_cndmask_b32_e64 v145, v145, v147, s[0:1]
	v_fmac_f32_e32 v149, v143, v149
	v_div_scale_f32 v143, vcc, s26, v144, s26
	v_sqrt_f32_e32 v147, v145
	v_mul_f32_e32 v148, v143, v149
	v_fma_f32 v150, -v146, v148, v143
	v_fmac_f32_e32 v148, v150, v149
	v_fma_f32 v143, -v146, v148, v143
	v_add_u32_e32 v146, -1, v147
	s_waitcnt lgkmcnt(0)
	v_add_f32_e32 v136, v136, v151
	v_fma_f32 v150, -v146, v147, v145
	ds_bpermute_b32 v151, v214, v136
	v_cmp_ge_f32_e64 s[2:3], 0, v150
	v_add_u32_e32 v150, 1, v147
	v_mul_f32_e32 v134, v26, v26
	v_cndmask_b32_e64 v146, v147, v146, s[2:3]
	v_fma_f32 v147, -v150, v147, v145
	v_cmp_lt_f32_e64 s[2:3], 0, v147
	s_waitcnt lgkmcnt(0)
	v_add_f32_e32 v136, v136, v151
	v_fmac_f32_e32 v134, v8, v8
	v_cndmask_b32_e64 v146, v146, v150, s[2:3]
	v_mul_f32_e32 v147, 0x37800000, v146
	v_cndmask_b32_e64 v146, v146, v147, s[0:1]
	ds_bpermute_b32 v147, v215, v136
	v_cmp_class_f32_e64 s[0:1], v145, v245
	v_fmac_f32_e32 v134, v45, v45
	v_fmac_f32_e32 v134, v58, v58
	v_cndmask_b32_e64 v145, v146, v145, s[0:1]
	s_waitcnt lgkmcnt(0)
	v_add_f32_e32 v147, v136, v147
	ds_bpermute_b32 v151, v216, v147
	v_div_fmas_f32 v136, v143, v149, v148
	v_div_fixup_f32 v136, v136, v144, s26
	v_div_scale_f32 v146, s[0:1], v145, v145, s26
	s_waitcnt lgkmcnt(0)
	v_add_f32_e32 v144, v147, v151
	ds_bpermute_b32 v147, v217, v144
	v_fmac_f32_e32 v134, v77, v77
	v_rcp_f32_e32 v150, v146
	v_fmac_f32_e32 v134, v90, v90
	v_fmac_f32_e32 v134, v109, v109
	s_waitcnt lgkmcnt(0)
	v_add_f32_e32 v144, v144, v147
	v_sub_f32_e32 v127, v127, v153
	v_fmamk_f32 v144, v144, 0x3b800000, v244
	v_fmac_f32_e32 v134, v127, v127
	v_mul_f32_e32 v147, 0x4f800000, v144
	v_cmp_gt_f32_e64 s[0:1], s25, v144
	v_fma_f32 v143, -v146, v150, 1.0
	ds_bpermute_b32 v151, v213, v134
	v_cndmask_b32_e64 v144, v144, v147, s[0:1]
	v_fmac_f32_e32 v150, v143, v150
	v_div_scale_f32 v143, vcc, s26, v145, s26
	v_sqrt_f32_e32 v147, v144
	v_mul_f32_e32 v148, v143, v150
	v_fma_f32 v149, -v146, v148, v143
	v_fmac_f32_e32 v148, v149, v150
	v_fma_f32 v143, -v146, v148, v143
	v_add_u32_e32 v146, -1, v147
	s_waitcnt lgkmcnt(0)
	v_add_f32_e32 v134, v134, v151
	v_fma_f32 v149, -v146, v147, v144
	ds_bpermute_b32 v151, v214, v134
	v_cmp_ge_f32_e64 s[2:3], 0, v149
	v_add_u32_e32 v149, 1, v147
	v_mul_f32_e32 v132, v24, v24
	v_cndmask_b32_e64 v146, v147, v146, s[2:3]
	v_fma_f32 v147, -v149, v147, v144
	v_cmp_lt_f32_e64 s[2:3], 0, v147
	s_waitcnt lgkmcnt(0)
	v_add_f32_e32 v134, v134, v151
	v_fmac_f32_e32 v132, v6, v6
	v_cndmask_b32_e64 v146, v146, v149, s[2:3]
	v_mul_f32_e32 v147, 0x37800000, v146
	v_cndmask_b32_e64 v146, v146, v147, s[0:1]
	ds_bpermute_b32 v147, v215, v134
	v_cmp_class_f32_e64 s[0:1], v144, v245
	v_fmac_f32_e32 v132, v46, v46
	v_fmac_f32_e32 v132, v56, v56
	v_cndmask_b32_e64 v144, v146, v144, s[0:1]
	s_waitcnt lgkmcnt(0)
	v_add_f32_e32 v147, v134, v147
	ds_bpermute_b32 v151, v216, v147
	v_div_fmas_f32 v134, v143, v150, v148
	v_div_fixup_f32 v134, v134, v145, s26
	v_div_scale_f32 v146, s[0:1], v144, v144, s26
	s_waitcnt lgkmcnt(0)
	v_add_f32_e32 v145, v147, v151
	ds_bpermute_b32 v147, v217, v145
	v_fmac_f32_e32 v132, v78, v78
	v_rcp_f32_e32 v149, v146
	v_fmac_f32_e32 v132, v88, v88
	v_fmac_f32_e32 v132, v110, v110
	s_waitcnt lgkmcnt(0)
	v_add_f32_e32 v145, v145, v147
	v_sub_f32_e32 v126, v126, v154
	v_fmamk_f32 v145, v145, 0x3b800000, v244
	v_fmac_f32_e32 v132, v126, v126
	v_mul_f32_e32 v147, 0x4f800000, v145
	v_cmp_gt_f32_e64 s[0:1], s25, v145
	v_fma_f32 v143, -v146, v149, 1.0
	ds_bpermute_b32 v151, v213, v132
	v_cndmask_b32_e64 v145, v145, v147, s[0:1]
	v_fmac_f32_e32 v149, v143, v149
	v_div_scale_f32 v143, vcc, s26, v144, s26
	v_sqrt_f32_e32 v147, v145
	v_mul_f32_e32 v148, v143, v149
	v_fma_f32 v150, -v146, v148, v143
	v_fmac_f32_e32 v148, v150, v149
	v_fma_f32 v143, -v146, v148, v143
	v_add_u32_e32 v146, -1, v147
	s_waitcnt lgkmcnt(0)
	v_add_f32_e32 v132, v132, v151
	v_fma_f32 v150, -v146, v147, v145
	ds_bpermute_b32 v151, v214, v132
	v_cmp_ge_f32_e64 s[2:3], 0, v150
	v_add_u32_e32 v150, 1, v147
	v_mul_f32_e32 v130, v25, v25
	v_cndmask_b32_e64 v146, v147, v146, s[2:3]
	v_fma_f32 v147, -v150, v147, v145
	v_cmp_lt_f32_e64 s[2:3], 0, v147
	s_waitcnt lgkmcnt(0)
	v_add_f32_e32 v132, v132, v151
	v_fmac_f32_e32 v130, v9, v9
	v_cndmask_b32_e64 v146, v146, v150, s[2:3]
	v_mul_f32_e32 v147, 0x37800000, v146
	v_cndmask_b32_e64 v146, v146, v147, s[0:1]
	ds_bpermute_b32 v147, v215, v132
	v_cmp_class_f32_e64 s[0:1], v145, v245
	v_fmac_f32_e32 v130, v47, v47
	v_fmac_f32_e32 v130, v57, v57
	v_cndmask_b32_e64 v145, v146, v145, s[0:1]
	v_div_scale_f32 v146, s[0:1], v145, v145, s26
	s_waitcnt lgkmcnt(0)
	v_add_f32_e32 v147, v132, v147
	v_rcp_f32_e32 v150, v146
	ds_bpermute_b32 v151, v216, v147
	v_div_fmas_f32 v132, v143, v149, v148
	v_div_fixup_f32 v132, v132, v144, s26
	v_fma_f32 v143, -v146, v150, 1.0
	v_fmac_f32_e32 v150, v143, v150
	s_waitcnt lgkmcnt(0)
	v_add_f32_e32 v143, v147, v151
	ds_bpermute_b32 v144, v217, v143
	v_fmac_f32_e32 v130, v79, v79
	v_fmac_f32_e32 v130, v89, v89
	v_fmac_f32_e32 v130, v111, v111
	v_sub_f32_e32 v128, v128, v155
	s_waitcnt lgkmcnt(0)
	v_add_f32_e32 v143, v143, v144
	v_fmamk_f32 v143, v143, 0x3b800000, v244
	v_fmac_f32_e32 v130, v128, v128
	v_mul_f32_e32 v144, 0x4f800000, v143
	v_cmp_gt_f32_e64 s[0:1], s25, v143
	ds_bpermute_b32 v152, v213, v130
	v_div_scale_f32 v147, vcc, s26, v145, s26
	v_cndmask_b32_e64 v143, v143, v144, s[0:1]
	v_sqrt_f32_e32 v144, v143
	v_mul_f32_e32 v148, v147, v150
	v_fma_f32 v149, -v146, v148, v147
	v_fmac_f32_e32 v148, v149, v150
	v_fma_f32 v146, -v146, v148, v147
	v_add_u32_e32 v147, -1, v144
	s_waitcnt lgkmcnt(0)
	v_add_f32_e32 v130, v130, v152
	v_fma_f32 v151, -v147, v144, v143
	ds_bpermute_b32 v152, v214, v130
	v_cmp_ge_f32_e64 s[2:3], 0, v151
	v_add_u32_e32 v151, 1, v144
	global_load_dword v149, v[196:197], off
	v_cndmask_b32_e64 v147, v144, v147, s[2:3]
	v_fma_f32 v144, -v151, v144, v143
	v_cmp_lt_f32_e64 s[2:3], 0, v144
	s_waitcnt lgkmcnt(0)
	v_add_f32_e32 v130, v130, v152
	v_mul_f32_e32 v112, v112, v129
	v_cndmask_b32_e64 v144, v147, v151, s[2:3]
	v_mul_f32_e32 v147, 0x37800000, v144
	v_cndmask_b32_e64 v144, v144, v147, s[0:1]
	ds_bpermute_b32 v147, v215, v130
	v_cmp_class_f32_e64 s[0:1], v143, v245
	v_lshlrev_b32_e32 v153, 12, v222
	v_mul_f32_e32 v22, v22, v129
	v_cndmask_b32_e64 v143, v144, v143, s[0:1]
	v_div_scale_f32 v144, s[0:1], v143, v143, s26
	s_waitcnt lgkmcnt(0)
	v_add_f32_e32 v147, v130, v147
	v_rcp_f32_e32 v151, v144
	ds_bpermute_b32 v152, v216, v147
	v_div_fmas_f32 v130, v146, v150, v148
	v_div_fixup_f32 v130, v130, v145, s26
	v_fma_f32 v145, -v144, v151, 1.0
	global_load_dword v148, v[196:197], off offset:128
	v_fmac_f32_e32 v151, v145, v151
	s_waitcnt lgkmcnt(0)
	v_add_f32_e32 v145, v147, v152
	ds_bpermute_b32 v146, v217, v145
	v_div_scale_f32 v147, vcc, s26, v143, s26
	v_mul_f32_e32 v150, v147, v151
	v_fma_f32 v152, -v144, v150, v147
	s_waitcnt lgkmcnt(0)
	v_add_f32_e32 v145, v145, v146
	v_fmamk_f32 v145, v145, 0x3b800000, v244
	v_mul_f32_e32 v146, 0x4f800000, v145
	v_cmp_gt_f32_e64 s[0:1], s25, v145
	v_fmac_f32_e32 v150, v152, v151
	v_fma_f32 v144, -v144, v150, v147
	v_cndmask_b32_e64 v145, v145, v146, s[0:1]
	v_sqrt_f32_e32 v146, v145
	v_div_fmas_f32 v144, v144, v151, v150
	v_div_fixup_f32 v143, v144, v143, s26
	v_add3_u32 v153, s39, v194, v153
	v_add_u32_e32 v147, -1, v146
	v_fma_f32 v152, -v147, v146, v145
	v_cmp_ge_f32_e64 s[2:3], 0, v152
	v_add_u32_e32 v152, 1, v146
	v_mul_f32_e32 v10, v10, v131
	v_cndmask_b32_e64 v147, v146, v147, s[2:3]
	v_fma_f32 v146, -v152, v146, v145
	v_cmp_lt_f32_e64 s[2:3], 0, v146
	v_mul_f32_e32 v7, v7, v133
	v_mul_f32_e32 v5, v5, v135
	v_cndmask_b32_e64 v146, v147, v152, s[2:3]
	v_mul_f32_e32 v147, 0x37800000, v146
	v_cndmask_b32_e64 v146, v146, v147, s[0:1]
	v_cmp_class_f32_e64 s[0:1], v145, v245
	v_mul_f32_e32 v4, v4, v137
	v_mul_f32_e32 v2, v2, v139
	v_cndmask_b32_e64 v145, v146, v145, s[0:1]
	v_div_scale_f32 v146, s[0:1], v145, v145, s26
	v_rcp_f32_e32 v147, v146
	v_mul_f32_e32 v0, v0, v141
	v_mul_f32_e32 v3, v3, v142
	v_mul_f32_e32 v15, v15, v140
	v_fma_f32 v144, -v146, v147, 1.0
	v_fmac_f32_e32 v147, v144, v147
	v_div_scale_f32 v144, vcc, s26, v145, s26
	v_mul_f32_e32 v150, v144, v147
	v_fma_f32 v151, -v146, v150, v144
	v_fmac_f32_e32 v150, v151, v147
	v_fma_f32 v144, -v146, v150, v144
	v_div_fmas_f32 v144, v144, v147, v150
	v_div_fixup_f32 v144, v144, v145, s26
	global_load_dword v145, v[196:197], off offset:256
	global_load_dword v146, v[196:197], off offset:384
	global_load_dword v147, v[196:197], off offset:512
	global_load_dword v150, v[196:197], off offset:640
	global_load_dword v151, v[196:197], off offset:768
	global_load_dword v152, v[196:197], off offset:896
	v_mul_f32_e32 v14, v14, v138
	v_mul_f32_e32 v13, v13, v136
	v_mul_f32_e32 v12, v12, v134
	v_mul_f32_e32 v11, v11, v132
	v_mul_f32_e32 v8, v8, v130
	s_waitcnt vmcnt(7)
	v_mul_f32_e32 v112, v112, v149
	v_mul_f32_e32 v10, v10, v149
	v_mul_f32_e32 v7, v7, v149
	v_mul_f32_e32 v5, v5, v149
	v_mul_f32_e32 v4, v4, v149
	v_mul_f32_e32 v2, v2, v149
	v_mul_f32_e32 v0, v0, v149
	v_mul_f32_e32 v3, v3, v149
	v_mul_f32_e32 v15, v15, v149
	v_mul_f32_e32 v14, v14, v149
	v_mul_f32_e32 v13, v13, v149
	v_mul_f32_e32 v12, v12, v149
	v_mul_f32_e32 v11, v11, v149
	v_mul_f32_e32 v8, v8, v149
	v_mul_f32_e32 v6, v6, v143
	v_mul_f32_e32 v6, v149, v6
	v_mul_f32_e32 v9, v9, v144
	v_mul_f32_e32 v9, v149, v9
	s_add_i32 s0, s4, s33
	s_add_i32 s4, s0, s37
	s_lshl_b32 s0, s36, 5
	s_and_b32 s0, s0, 0xe00
	s_waitcnt vmcnt(6)
	v_mul_f32_e32 v22, v22, v148
	ds_write2_b32 v153, v112, v22 offset1:32
	v_mul_f32_e32 v22, v23, v131
	v_mul_f32_e32 v22, v22, v148
	v_add_u32_e32 v23, 0x400, v153
	ds_write2_b32 v23, v10, v22 offset1:32
	v_mul_f32_e32 v10, v21, v133
	v_mul_f32_e32 v10, v10, v148
	v_add_u32_e32 v21, 0x800, v153
	ds_write2_b32 v21, v7, v10 offset1:32
	v_mul_f32_e32 v7, v20, v135
	v_mul_f32_e32 v7, v7, v148
	v_add_u32_e32 v10, 0xc00, v153
	ds_write2_b32 v10, v5, v7 offset1:32
	v_mul_f32_e32 v5, v19, v137
	v_mul_f32_e32 v5, v5, v148
	v_add_u32_e32 v7, 0x2000, v153
	ds_write2_b32 v7, v4, v5 offset1:32
	v_mul_f32_e32 v4, v18, v139
	v_mul_f32_e32 v4, v4, v148
	v_add_u32_e32 v5, 0x2400, v153
	ds_write2_b32 v5, v2, v4 offset1:32
	v_mul_f32_e32 v2, v16, v141
	v_mul_f32_e32 v2, v2, v148
	v_add_u32_e32 v4, 0x2800, v153
	ds_write2_b32 v4, v0, v2 offset1:32
	v_mul_f32_e32 v0, v17, v142
	v_mul_f32_e32 v0, v0, v148
	v_add_u32_e32 v2, 0x2c00, v153
	ds_write2_b32 v2, v3, v0 offset1:32
	v_mul_f32_e32 v0, v31, v140
	v_mul_f32_e32 v0, v0, v148
	v_add_u32_e32 v3, 0x4000, v153
	ds_write2_b32 v3, v15, v0 offset1:32
	v_mul_f32_e32 v0, v30, v138
	v_mul_f32_e32 v0, v0, v148
	v_add_u32_e32 v15, 0x4400, v153
	ds_write2_b32 v15, v14, v0 offset1:32
	v_mul_f32_e32 v0, v29, v136
	v_mul_f32_e32 v0, v0, v148
	v_add_u32_e32 v14, 0x4800, v153
	ds_write2_b32 v14, v13, v0 offset1:32
	v_mul_f32_e32 v0, v28, v134
	v_mul_f32_e32 v0, v0, v148
	v_add_u32_e32 v13, 0x4c00, v153
	ds_write2_b32 v13, v12, v0 offset1:32
	v_mul_f32_e32 v0, v27, v132
	v_mul_f32_e32 v0, v0, v148
	v_add_u32_e32 v12, 0x6000, v153
	ds_write2_b32 v12, v11, v0 offset1:32
	v_mul_f32_e32 v0, v26, v130
	v_mul_f32_e32 v0, v0, v148
	v_add_u32_e32 v11, 0x6400, v153
	ds_write2_b32 v11, v8, v0 offset1:32
	v_mul_f32_e32 v0, v24, v143
	v_mul_f32_e32 v0, v0, v148
	v_add_u32_e32 v8, 0x6800, v153
	ds_write2_b32 v8, v6, v0 offset1:32
	v_mul_f32_e32 v0, v25, v144
	v_mul_f32_e32 v0, v0, v148
	v_add_u32_e32 v6, 0x6c00, v153
	ds_write2_b32 v6, v9, v0 offset1:32
	v_mul_f32_e32 v0, v32, v129
	v_mul_f32_e32 v32, v55, v129
	s_waitcnt vmcnt(5)
	v_mul_f32_e32 v0, v0, v145
	s_waitcnt vmcnt(4)
	v_mul_f32_e32 v32, v32, v146
	v_mul_f32_e32 v9, v33, v131
	ds_write2_b32 v153, v0, v32 offset0:64 offset1:96
	v_mul_f32_e32 v0, v54, v131
	v_mul_f32_e32 v9, v9, v145
	v_mul_f32_e32 v0, v0, v146
	v_mul_f32_e32 v16, v34, v133
	ds_write2_b32 v23, v9, v0 offset0:64 offset1:96
	v_mul_f32_e32 v0, v53, v133
	v_mul_f32_e32 v16, v16, v145
	v_mul_f32_e32 v0, v0, v146
	v_mul_f32_e32 v17, v35, v135
	ds_write2_b32 v21, v16, v0 offset0:64 offset1:96
	v_mul_f32_e32 v0, v52, v135
	v_mul_f32_e32 v17, v17, v145
	v_mul_f32_e32 v0, v0, v146
	v_mul_f32_e32 v18, v36, v137
	ds_write2_b32 v10, v17, v0 offset0:64 offset1:96
	v_mul_f32_e32 v0, v51, v137
	v_mul_f32_e32 v18, v18, v145
	v_mul_f32_e32 v0, v0, v146
	v_mul_f32_e32 v19, v37, v139
	ds_write2_b32 v7, v18, v0 offset0:64 offset1:96
	v_mul_f32_e32 v0, v50, v139
	v_mul_f32_e32 v19, v19, v145
	v_mul_f32_e32 v0, v0, v146
	v_mul_f32_e32 v20, v38, v141
	ds_write2_b32 v5, v19, v0 offset0:64 offset1:96
	v_mul_f32_e32 v0, v48, v141
	v_mul_f32_e32 v20, v20, v145
	v_mul_f32_e32 v0, v0, v146
	v_mul_f32_e32 v22, v39, v142
	ds_write2_b32 v4, v20, v0 offset0:64 offset1:96
	v_mul_f32_e32 v0, v49, v142
	v_mul_f32_e32 v22, v22, v145
	v_mul_f32_e32 v0, v0, v146
	v_mul_f32_e32 v24, v40, v140
	ds_write2_b32 v2, v22, v0 offset0:64 offset1:96
	v_mul_f32_e32 v0, v63, v140
	v_mul_f32_e32 v24, v24, v145
	v_mul_f32_e32 v0, v0, v146
	v_mul_f32_e32 v25, v41, v138
	ds_write2_b32 v3, v24, v0 offset0:64 offset1:96
	v_mul_f32_e32 v0, v62, v138
	v_mul_f32_e32 v25, v25, v145
	v_mul_f32_e32 v0, v0, v146
	v_mul_f32_e32 v26, v42, v136
	ds_write2_b32 v15, v25, v0 offset0:64 offset1:96
	v_mul_f32_e32 v0, v61, v136
	v_mul_f32_e32 v26, v26, v145
	v_mul_f32_e32 v0, v0, v146
	v_mul_f32_e32 v27, v43, v134
	ds_write2_b32 v14, v26, v0 offset0:64 offset1:96
	v_mul_f32_e32 v0, v60, v134
	v_mul_f32_e32 v27, v27, v145
	v_mul_f32_e32 v0, v0, v146
	v_mul_f32_e32 v28, v44, v132
	ds_write2_b32 v13, v27, v0 offset0:64 offset1:96
	v_mul_f32_e32 v0, v59, v132
	v_mul_f32_e32 v28, v28, v145
	v_mul_f32_e32 v0, v0, v146
	v_mul_f32_e32 v29, v45, v130
	ds_write2_b32 v12, v28, v0 offset0:64 offset1:96
	v_mul_f32_e32 v0, v58, v130
	v_mul_f32_e32 v29, v29, v145
	v_mul_f32_e32 v0, v0, v146
	v_mul_f32_e32 v30, v46, v143
	ds_write2_b32 v11, v29, v0 offset0:64 offset1:96
	v_mul_f32_e32 v0, v56, v143
	v_mul_f32_e32 v30, v30, v145
	v_mul_f32_e32 v0, v0, v146
	v_mul_f32_e32 v31, v47, v144
	ds_write2_b32 v8, v30, v0 offset0:64 offset1:96
	v_mul_f32_e32 v0, v57, v144
	v_mul_f32_e32 v31, v31, v145
	v_mul_f32_e32 v0, v0, v146
	ds_write2_b32 v6, v31, v0 offset0:64 offset1:96
	v_mul_f32_e32 v0, v64, v129
	v_mul_f32_e32 v32, v87, v129
	s_waitcnt vmcnt(3)
	v_mul_f32_e32 v0, v0, v147
	s_waitcnt vmcnt(2)
	v_mul_f32_e32 v32, v32, v150
	v_mul_f32_e32 v9, v65, v131
	ds_write2_b32 v153, v0, v32 offset0:128 offset1:160
	v_mul_f32_e32 v0, v86, v131
	v_mul_f32_e32 v9, v9, v147
	v_mul_f32_e32 v0, v0, v150
	v_mul_f32_e32 v16, v66, v133
	ds_write2_b32 v23, v9, v0 offset0:128 offset1:160
	v_mul_f32_e32 v0, v85, v133
	v_mul_f32_e32 v16, v16, v147
	v_mul_f32_e32 v0, v0, v150
	v_mul_f32_e32 v17, v67, v135
	ds_write2_b32 v21, v16, v0 offset0:128 offset1:160
	v_mul_f32_e32 v0, v84, v135
	v_mul_f32_e32 v17, v17, v147
	v_mul_f32_e32 v0, v0, v150
	v_mul_f32_e32 v18, v68, v137
	ds_write2_b32 v10, v17, v0 offset0:128 offset1:160
	v_mul_f32_e32 v0, v83, v137
	v_mul_f32_e32 v18, v18, v147
	v_mul_f32_e32 v0, v0, v150
	v_mul_f32_e32 v19, v69, v139
	ds_write2_b32 v7, v18, v0 offset0:128 offset1:160
	v_mul_f32_e32 v0, v82, v139
	v_mul_f32_e32 v19, v19, v147
	v_mul_f32_e32 v0, v0, v150
	v_mul_f32_e32 v20, v70, v141
	ds_write2_b32 v5, v19, v0 offset0:128 offset1:160
	v_mul_f32_e32 v0, v80, v141
	v_mul_f32_e32 v20, v20, v147
	v_mul_f32_e32 v0, v0, v150
	v_mul_f32_e32 v22, v71, v142
	ds_write2_b32 v4, v20, v0 offset0:128 offset1:160
	v_mul_f32_e32 v0, v81, v142
	v_mul_f32_e32 v22, v22, v147
	v_mul_f32_e32 v0, v0, v150
	v_mul_f32_e32 v24, v72, v140
	ds_write2_b32 v2, v22, v0 offset0:128 offset1:160
	v_mul_f32_e32 v0, v95, v140
	v_mul_f32_e32 v24, v24, v147
	v_mul_f32_e32 v0, v0, v150
	v_mul_f32_e32 v25, v73, v138
	ds_write2_b32 v3, v24, v0 offset0:128 offset1:160
	v_mul_f32_e32 v0, v94, v138
	v_mul_f32_e32 v25, v25, v147
	v_mul_f32_e32 v0, v0, v150
	v_mul_f32_e32 v26, v74, v136
	ds_write2_b32 v15, v25, v0 offset0:128 offset1:160
	v_mul_f32_e32 v0, v93, v136
	v_mul_f32_e32 v26, v26, v147
	v_mul_f32_e32 v0, v0, v150
	v_mul_f32_e32 v27, v75, v134
	ds_write2_b32 v14, v26, v0 offset0:128 offset1:160
	v_mul_f32_e32 v0, v92, v134
	v_mul_f32_e32 v27, v27, v147
	v_mul_f32_e32 v0, v0, v150
	v_mul_f32_e32 v28, v76, v132
	ds_write2_b32 v13, v27, v0 offset0:128 offset1:160
	v_mul_f32_e32 v0, v91, v132
	v_mul_f32_e32 v28, v28, v147
	v_mul_f32_e32 v0, v0, v150
	v_mul_f32_e32 v29, v77, v130
	ds_write2_b32 v12, v28, v0 offset0:128 offset1:160
	v_mul_f32_e32 v0, v90, v130
	v_mul_f32_e32 v29, v29, v147
	v_mul_f32_e32 v0, v0, v150
	v_mul_f32_e32 v30, v78, v143
	ds_write2_b32 v11, v29, v0 offset0:128 offset1:160
	v_mul_f32_e32 v0, v88, v143
	v_mul_f32_e32 v30, v30, v147
	v_mul_f32_e32 v0, v0, v150
	v_mul_f32_e32 v31, v79, v144
	ds_write2_b32 v8, v30, v0 offset0:128 offset1:160
	v_mul_f32_e32 v0, v89, v144
	v_mul_f32_e32 v31, v31, v147
	v_mul_f32_e32 v0, v0, v150
	ds_write2_b32 v6, v31, v0 offset0:128 offset1:160
	v_mul_f32_e32 v0, v96, v129
	v_mul_f32_e32 v32, v117, v129
	s_waitcnt vmcnt(1)
	v_mul_f32_e32 v0, v0, v151
	s_waitcnt vmcnt(0)
	v_mul_f32_e32 v32, v32, v152
	v_mul_f32_e32 v9, v97, v131
	ds_write2_b32 v153, v0, v32 offset0:192 offset1:224
	v_mul_f32_e32 v0, v116, v131
	v_mul_f32_e32 v9, v9, v151
	v_mul_f32_e32 v0, v0, v152
	v_mul_f32_e32 v16, v98, v133
	ds_write2_b32 v23, v9, v0 offset0:192 offset1:224
	v_mul_f32_e32 v0, v115, v133
	v_mul_f32_e32 v16, v16, v151
	v_mul_f32_e32 v0, v0, v152
	v_mul_f32_e32 v17, v99, v135
	ds_write2_b32 v21, v16, v0 offset0:192 offset1:224
	v_mul_f32_e32 v0, v114, v135
	v_mul_f32_e32 v17, v17, v151
	v_mul_f32_e32 v0, v0, v152
	v_mul_f32_e32 v18, v100, v137
	ds_write2_b32 v10, v17, v0 offset0:192 offset1:224
	v_mul_f32_e32 v0, v113, v137
	v_mul_f32_e32 v18, v18, v151
	v_mul_f32_e32 v0, v0, v152
	v_mul_f32_e32 v19, v101, v139
	ds_write2_b32 v7, v18, v0 offset0:192 offset1:224
	v_mul_f32_e32 v0, v119, v139
	v_mul_f32_e32 v19, v19, v151
	v_mul_f32_e32 v0, v0, v152
	v_mul_f32_e32 v20, v102, v141
	ds_write2_b32 v5, v19, v0 offset0:192 offset1:224
	v_mul_f32_e32 v0, v118, v141
	v_mul_f32_e32 v20, v20, v151
	v_mul_f32_e32 v0, v0, v152
	v_mul_f32_e32 v22, v103, v142
	ds_write2_b32 v4, v20, v0 offset0:192 offset1:224
	v_mul_f32_e32 v0, v120, v142
	v_mul_f32_e32 v22, v22, v151
	v_mul_f32_e32 v0, v0, v152
	v_mul_f32_e32 v24, v104, v140
	ds_write2_b32 v2, v22, v0 offset0:192 offset1:224
	v_mul_f32_e32 v0, v121, v140
	v_mul_f32_e32 v24, v24, v151
	v_mul_f32_e32 v0, v0, v152
	v_mul_f32_e32 v25, v105, v138
	ds_write2_b32 v3, v24, v0 offset0:192 offset1:224
	v_mul_f32_e32 v0, v124, v138
	v_mul_f32_e32 v25, v25, v151
	v_mul_f32_e32 v0, v0, v152
	v_mul_f32_e32 v26, v106, v136
	ds_write2_b32 v15, v25, v0 offset0:192 offset1:224
	v_mul_f32_e32 v0, v122, v136
	v_mul_f32_e32 v26, v26, v151
	v_mul_f32_e32 v0, v0, v152
	v_mul_f32_e32 v27, v107, v134
	ds_write2_b32 v14, v26, v0 offset0:192 offset1:224
	v_mul_f32_e32 v0, v125, v134
	v_mul_f32_e32 v27, v27, v151
	v_mul_f32_e32 v0, v0, v152
	v_mul_f32_e32 v28, v108, v132
	ds_write2_b32 v13, v27, v0 offset0:192 offset1:224
	v_mul_f32_e32 v0, v123, v132
	v_mul_f32_e32 v28, v28, v151
	v_mul_f32_e32 v0, v0, v152
	v_mul_f32_e32 v29, v109, v130
	ds_write2_b32 v12, v28, v0 offset0:192 offset1:224
	v_mul_f32_e32 v0, v127, v130
	v_mul_f32_e32 v29, v29, v151
	v_mul_f32_e32 v0, v0, v152
	v_mul_f32_e32 v30, v110, v143
	ds_write2_b32 v11, v29, v0 offset0:192 offset1:224
	v_mul_f32_e32 v0, v126, v143
	v_mul_f32_e32 v30, v30, v151
	v_mul_f32_e32 v0, v0, v152
	v_mul_f32_e32 v31, v111, v144
	ds_write2_b32 v8, v30, v0 offset0:192 offset1:224
	v_mul_f32_e32 v0, v128, v144
	v_mul_f32_e32 v31, v31, v151
	v_mul_f32_e32 v0, v0, v152
	ds_write2_b32 v6, v31, v0 offset0:192 offset1:224
	v_mov_b32_e32 v0, v220
	s_mov_b64 s[2:3], 0
	v_ashrrev_i32_e32 v4, 5, v0
	v_ashrrev_i32_e32 v5, 31, v4
	v_lshl_add_u64 v[2:3], v[4:5], 0, s[4:5]
	v_lshlrev_b32_e32 v5, 4, v0
	v_lshlrev_b64 v[2:3], 12, v[2:3]
	v_and_b32_e32 v5, 0x1f0, v5
	v_and_b32_e32 v0, 31, v0
	v_or3_b32 v2, s0, v5, v2
	v_lshl_add_u32 v4, v4, 10, s38
	v_lshlrev_b32_e32 v0, 5, v0
	v_lshl_add_u64 v[2:3], s[80:81], 0, v[2:3]
	v_add3_u32 v0, v4, v0, 0
	v_lshl_add_u64 v[248:249], v[2:3], 0, s[2:3]
	v_add_co_u32_e32 v250, vcc, s30, v248
	s_nop 1
	v_addc_co_u32_e32 v251, vcc, 0, v249, vcc
	global_load_dwordx4 v[128:131], v[250:251], off
	v_add_co_u32_e32 v250, vcc, s34, v248
	s_nop 1
	v_addc_co_u32_e32 v251, vcc, 0, v249, vcc
	global_load_dwordx4 v[132:135], v[250:251], off
	v_add_co_u32_e32 v250, vcc, 0x1a200000, v248
	s_nop 1
	v_addc_co_u32_e32 v251, vcc, 0, v249, vcc
	global_load_dwordx4 v[136:139], v[250:251], off
	v_add_co_u32_e32 v250, vcc, s28, v248
	s_nop 1
	v_addc_co_u32_e32 v251, vcc, 0, v249, vcc
	global_load_dwordx4 v[140:143], v[250:251], off
	s_add_u32 s2, s2, 0x8000
	s_addc_u32 s3, s3, 0
	v_lshl_add_u64 v[248:249], v[2:3], 0, s[2:3]
	v_add_co_u32_e32 v250, vcc, s30, v248
	s_nop 1
	v_addc_co_u32_e32 v251, vcc, 0, v249, vcc
	global_load_dwordx4 v[144:147], v[250:251], off
	v_add_co_u32_e32 v250, vcc, s34, v248
	s_nop 1
	v_addc_co_u32_e32 v251, vcc, 0, v249, vcc
	global_load_dwordx4 v[148:151], v[250:251], off
	v_add_co_u32_e32 v250, vcc, 0x1a200000, v248
	s_nop 1
	v_addc_co_u32_e32 v251, vcc, 0, v249, vcc
	global_load_dwordx4 v[152:155], v[250:251], off
	v_add_co_u32_e32 v250, vcc, s28, v248
	s_nop 1
	v_addc_co_u32_e32 v251, vcc, 0, v249, vcc
	global_load_dwordx4 v[156:159], v[250:251], off
	s_add_u32 s2, s2, 0x8000
	s_addc_u32 s3, s3, 0
	v_lshl_add_u64 v[248:249], v[2:3], 0, s[2:3]
	v_add_co_u32_e32 v250, vcc, s30, v248
	s_nop 1
	v_addc_co_u32_e32 v251, vcc, 0, v249, vcc
	global_load_dwordx4 v[160:163], v[250:251], off
	v_add_co_u32_e32 v250, vcc, s34, v248
	s_nop 1
	v_addc_co_u32_e32 v251, vcc, 0, v249, vcc
	global_load_dwordx4 v[164:167], v[250:251], off
	v_add_co_u32_e32 v250, vcc, 0x1a200000, v248
	s_nop 1
	v_addc_co_u32_e32 v251, vcc, 0, v249, vcc
	global_load_dwordx4 v[168:171], v[250:251], off
	v_add_co_u32_e32 v250, vcc, s28, v248
	s_nop 1
	v_addc_co_u32_e32 v251, vcc, 0, v249, vcc
	global_load_dwordx4 v[172:175], v[250:251], off
	s_add_u32 s2, s2, 0x8000
	s_addc_u32 s3, s3, 0
	v_lshl_add_u64 v[248:249], v[2:3], 0, s[2:3]
	v_add_co_u32_e32 v250, vcc, s30, v248
	s_nop 1
	v_addc_co_u32_e32 v251, vcc, 0, v249, vcc
	global_load_dwordx4 v[176:179], v[250:251], off
	v_add_co_u32_e32 v250, vcc, s34, v248
	s_nop 1
	v_addc_co_u32_e32 v251, vcc, 0, v249, vcc
	global_load_dwordx4 v[180:183], v[250:251], off
	v_add_co_u32_e32 v250, vcc, 0x1a200000, v248
	s_nop 1
	v_addc_co_u32_e32 v251, vcc, 0, v249, vcc
	global_load_dwordx4 v[184:187], v[250:251], off
	v_add_co_u32_e32 v250, vcc, s28, v248
	s_nop 1
	v_addc_co_u32_e32 v251, vcc, 0, v249, vcc
	global_load_dwordx4 v[188:191], v[250:251], off
	s_add_u32 s2, s2, 0x8000
	s_addc_u32 s3, s3, 0
	s_mov_b64 s[2:3], 0
	v_lshl_add_u64 v[52:53], v[2:3], 0, s[2:3]
	v_add_co_u32_e64 v54, s[0:1], s27, v52
	s_nop 1
	v_addc_co_u32_e64 v55, s[0:1], 0, v53, s[0:1]
	s_nop 1
	ds_read_b128 v[4:7], v0
	ds_read_b128 v[8:11], v0 offset:16
	ds_read_b128 v[12:15], v0 offset:2048
	ds_read_b128 v[16:19], v0 offset:2064
	ds_read_b128 v[20:23], v0 offset:4096
	ds_read_b128 v[24:27], v0 offset:4112
	ds_read_b128 v[28:31], v0 offset:6144
	ds_read_b128 v[32:35], v0 offset:6160
	s_nop 1
	s_nop 1
	s_nop 1
	v_add_co_u32_e32 v56, vcc, s29, v52
	s_add_u32 s2, s2, 0x8000
	s_nop 1
	v_addc_co_u32_e32 v57, vcc, 0, v53, vcc
	v_add_co_u32_e32 v58, vcc, s31, v52
	s_addc_u32 s3, s3, 0
	s_nop 1
	v_addc_co_u32_e32 v59, vcc, 0, v53, vcc
	v_add_u32_e32 v0, 0x2000, v0
	v_add_co_u32_e32 v52, vcc, s35, v52
	s_nop 1
	v_addc_co_u32_e32 v53, vcc, 0, v53, vcc
	s_waitcnt vmcnt(12)
	v_lshlrev_b32_e32 v60, 16, v128
	v_and_b32_e32 v61, 0xffff0000, v128
	v_lshlrev_b32_e32 v128, 16, v129
	v_and_b32_e32 v129, 0xffff0000, v129
	v_lshlrev_b32_e32 v62, 16, v130
	v_and_b32_e32 v63, 0xffff0000, v130
	v_lshlrev_b32_e32 v130, 16, v131
	v_and_b32_e32 v131, 0xffff0000, v131
	v_lshlrev_b32_e32 v64, 16, v132
	v_and_b32_e32 v65, 0xffff0000, v132
	v_lshlrev_b32_e32 v132, 16, v133
	v_and_b32_e32 v133, 0xffff0000, v133
	v_lshlrev_b32_e32 v66, 16, v134
	v_and_b32_e32 v67, 0xffff0000, v134
	v_lshlrev_b32_e32 v134, 16, v135
	v_and_b32_e32 v135, 0xffff0000, v135
	v_lshlrev_b32_e32 v68, 16, v136
	v_and_b32_e32 v69, 0xffff0000, v136
	v_lshlrev_b32_e32 v136, 16, v137
	v_and_b32_e32 v137, 0xffff0000, v137
	v_lshlrev_b32_e32 v70, 16, v138
	v_and_b32_e32 v71, 0xffff0000, v138
	v_lshlrev_b32_e32 v138, 16, v139
	v_and_b32_e32 v139, 0xffff0000, v139
	v_lshlrev_b32_e32 v72, 16, v140
	v_and_b32_e32 v73, 0xffff0000, v140
	v_lshlrev_b32_e32 v140, 16, v141
	v_and_b32_e32 v141, 0xffff0000, v141
	v_lshlrev_b32_e32 v74, 16, v142
	v_and_b32_e32 v75, 0xffff0000, v142
	v_lshlrev_b32_e32 v142, 16, v143
	v_and_b32_e32 v143, 0xffff0000, v143
	s_waitcnt lgkmcnt(3)
	v_pk_mul_f32 v[20:21], v[20:21], v[60:61]
	v_pk_mul_f32 v[22:23], v[22:23], v[128:129]
	s_waitcnt lgkmcnt(2)
	v_pk_mul_f32 v[24:25], v[24:25], v[62:63]
	v_pk_mul_f32 v[26:27], v[26:27], v[130:131]
	s_waitcnt lgkmcnt(1)
	v_pk_mul_f32 v[28:29], v[28:29], v[64:65]
	v_pk_mul_f32 v[30:31], v[30:31], v[132:133]
	s_waitcnt lgkmcnt(0)
	v_pk_mul_f32 v[32:33], v[32:33], v[66:67]
	v_pk_mul_f32 v[34:35], v[34:35], v[134:135]
	v_pk_mul_f32 v[128:129], v[4:5], v[68:69]
	v_pk_mul_f32 v[130:131], v[6:7], v[136:137]
	v_pk_mul_f32 v[132:133], v[8:9], v[70:71]
	v_pk_mul_f32 v[134:135], v[10:11], v[138:139]
	v_pk_mul_f32 v[136:137], v[12:13], v[72:73]
	v_pk_mul_f32 v[138:139], v[14:15], v[140:141]
	v_pk_mul_f32 v[140:141], v[16:17], v[74:75]
	v_pk_mul_f32 v[142:143], v[18:19], v[142:143]
	v_cvt_pk_bf16_f32 v4, v20, v21
	v_cvt_pk_bf16_f32 v5, v22, v23
	v_cvt_pk_bf16_f32 v6, v24, v25
	v_cvt_pk_bf16_f32 v7, v26, v27
	v_cvt_pk_bf16_f32 v8, v28, v29
	v_cvt_pk_bf16_f32 v9, v30, v31
	v_cvt_pk_bf16_f32 v10, v32, v33
	v_cvt_pk_bf16_f32 v11, v34, v35
	v_cvt_pk_bf16_f32 v12, v128, v129
	v_cvt_pk_bf16_f32 v13, v130, v131
	v_cvt_pk_bf16_f32 v14, v132, v133
	v_cvt_pk_bf16_f32 v15, v134, v135
	v_cvt_pk_bf16_f32 v16, v136, v137
	v_cvt_pk_bf16_f32 v17, v138, v139
	v_cvt_pk_bf16_f32 v18, v140, v141
	v_cvt_pk_bf16_f32 v19, v142, v143
	global_store_dwordx4 v[58:59], v[4:7], off
	global_store_dwordx4 v[52:53], v[8:11], off
	global_store_dwordx4 v[54:55], v[12:15], off
	global_store_dwordx4 v[56:57], v[16:19], off
	v_lshl_add_u64 v[52:53], v[2:3], 0, s[2:3]
	v_add_co_u32_e64 v54, s[0:1], s27, v52
	s_nop 1
	v_addc_co_u32_e64 v55, s[0:1], 0, v53, s[0:1]
	s_nop 1
	ds_read_b128 v[4:7], v0
	ds_read_b128 v[8:11], v0 offset:16
	ds_read_b128 v[12:15], v0 offset:2048
	ds_read_b128 v[16:19], v0 offset:2064
	ds_read_b128 v[20:23], v0 offset:4096
	ds_read_b128 v[24:27], v0 offset:4112
	ds_read_b128 v[28:31], v0 offset:6144
	ds_read_b128 v[32:35], v0 offset:6160
	s_nop 1
	s_nop 1
	s_nop 1
	v_add_co_u32_e32 v56, vcc, s29, v52
	s_add_u32 s2, s2, 0x8000
	s_nop 1
	v_addc_co_u32_e32 v57, vcc, 0, v53, vcc
	v_add_co_u32_e32 v58, vcc, s31, v52
	s_addc_u32 s3, s3, 0
	s_nop 1
	v_addc_co_u32_e32 v59, vcc, 0, v53, vcc
	v_add_u32_e32 v0, 0x2000, v0
	v_add_co_u32_e32 v52, vcc, s35, v52
	s_nop 1
	v_addc_co_u32_e32 v53, vcc, 0, v53, vcc
	s_waitcnt vmcnt(12)
	v_lshlrev_b32_e32 v60, 16, v144
	v_and_b32_e32 v61, 0xffff0000, v144
	v_lshlrev_b32_e32 v144, 16, v145
	v_and_b32_e32 v145, 0xffff0000, v145
	v_lshlrev_b32_e32 v62, 16, v146
	v_and_b32_e32 v63, 0xffff0000, v146
	v_lshlrev_b32_e32 v146, 16, v147
	v_and_b32_e32 v147, 0xffff0000, v147
	v_lshlrev_b32_e32 v64, 16, v148
	v_and_b32_e32 v65, 0xffff0000, v148
	v_lshlrev_b32_e32 v148, 16, v149
	v_and_b32_e32 v149, 0xffff0000, v149
	v_lshlrev_b32_e32 v66, 16, v150
	v_and_b32_e32 v67, 0xffff0000, v150
	v_lshlrev_b32_e32 v150, 16, v151
	v_and_b32_e32 v151, 0xffff0000, v151
	v_lshlrev_b32_e32 v68, 16, v152
	v_and_b32_e32 v69, 0xffff0000, v152
	v_lshlrev_b32_e32 v152, 16, v153
	v_and_b32_e32 v153, 0xffff0000, v153
	v_lshlrev_b32_e32 v70, 16, v154
	v_and_b32_e32 v71, 0xffff0000, v154
	v_lshlrev_b32_e32 v154, 16, v155
	v_and_b32_e32 v155, 0xffff0000, v155
	v_lshlrev_b32_e32 v72, 16, v156
	v_and_b32_e32 v73, 0xffff0000, v156
	v_lshlrev_b32_e32 v156, 16, v157
	v_and_b32_e32 v157, 0xffff0000, v157
	v_lshlrev_b32_e32 v74, 16, v158
	v_and_b32_e32 v75, 0xffff0000, v158
	v_lshlrev_b32_e32 v158, 16, v159
	v_and_b32_e32 v159, 0xffff0000, v159
	s_waitcnt lgkmcnt(3)
	v_pk_mul_f32 v[20:21], v[20:21], v[60:61]
	v_pk_mul_f32 v[22:23], v[22:23], v[144:145]
	s_waitcnt lgkmcnt(2)
	v_pk_mul_f32 v[24:25], v[24:25], v[62:63]
	v_pk_mul_f32 v[26:27], v[26:27], v[146:147]
	s_waitcnt lgkmcnt(1)
	v_pk_mul_f32 v[28:29], v[28:29], v[64:65]
	v_pk_mul_f32 v[30:31], v[30:31], v[148:149]
	s_waitcnt lgkmcnt(0)
	v_pk_mul_f32 v[32:33], v[32:33], v[66:67]
	v_pk_mul_f32 v[34:35], v[34:35], v[150:151]
	v_pk_mul_f32 v[144:145], v[4:5], v[68:69]
	v_pk_mul_f32 v[146:147], v[6:7], v[152:153]
	v_pk_mul_f32 v[148:149], v[8:9], v[70:71]
	v_pk_mul_f32 v[150:151], v[10:11], v[154:155]
	v_pk_mul_f32 v[152:153], v[12:13], v[72:73]
	v_pk_mul_f32 v[154:155], v[14:15], v[156:157]
	v_pk_mul_f32 v[156:157], v[16:17], v[74:75]
	v_pk_mul_f32 v[158:159], v[18:19], v[158:159]
	v_cvt_pk_bf16_f32 v4, v20, v21
	v_cvt_pk_bf16_f32 v5, v22, v23
	v_cvt_pk_bf16_f32 v6, v24, v25
	v_cvt_pk_bf16_f32 v7, v26, v27
	v_cvt_pk_bf16_f32 v8, v28, v29
	v_cvt_pk_bf16_f32 v9, v30, v31
	v_cvt_pk_bf16_f32 v10, v32, v33
	v_cvt_pk_bf16_f32 v11, v34, v35
	v_cvt_pk_bf16_f32 v12, v144, v145
	v_cvt_pk_bf16_f32 v13, v146, v147
	v_cvt_pk_bf16_f32 v14, v148, v149
	v_cvt_pk_bf16_f32 v15, v150, v151
	v_cvt_pk_bf16_f32 v16, v152, v153
	v_cvt_pk_bf16_f32 v17, v154, v155
	v_cvt_pk_bf16_f32 v18, v156, v157
	v_cvt_pk_bf16_f32 v19, v158, v159
	global_store_dwordx4 v[58:59], v[4:7], off
	global_store_dwordx4 v[52:53], v[8:11], off
	global_store_dwordx4 v[54:55], v[12:15], off
	global_store_dwordx4 v[56:57], v[16:19], off
	v_lshl_add_u64 v[52:53], v[2:3], 0, s[2:3]
	v_add_co_u32_e64 v54, s[0:1], s27, v52
	s_nop 1
	v_addc_co_u32_e64 v55, s[0:1], 0, v53, s[0:1]
	s_nop 1
	ds_read_b128 v[4:7], v0
	ds_read_b128 v[8:11], v0 offset:16
	ds_read_b128 v[12:15], v0 offset:2048
	ds_read_b128 v[16:19], v0 offset:2064
	ds_read_b128 v[20:23], v0 offset:4096
	ds_read_b128 v[24:27], v0 offset:4112
	ds_read_b128 v[28:31], v0 offset:6144
	ds_read_b128 v[32:35], v0 offset:6160
	s_nop 1
	s_nop 1
	s_nop 1
	v_add_co_u32_e32 v56, vcc, s29, v52
	s_add_u32 s2, s2, 0x8000
	s_nop 1
	v_addc_co_u32_e32 v57, vcc, 0, v53, vcc
	v_add_co_u32_e32 v58, vcc, s31, v52
	s_addc_u32 s3, s3, 0
	s_nop 1
	v_addc_co_u32_e32 v59, vcc, 0, v53, vcc
	v_add_u32_e32 v0, 0x2000, v0
	v_add_co_u32_e32 v52, vcc, s35, v52
	s_nop 1
	v_addc_co_u32_e32 v53, vcc, 0, v53, vcc
	s_waitcnt vmcnt(12)
	v_lshlrev_b32_e32 v60, 16, v160
	v_and_b32_e32 v61, 0xffff0000, v160
	v_lshlrev_b32_e32 v160, 16, v161
	v_and_b32_e32 v161, 0xffff0000, v161
	v_lshlrev_b32_e32 v62, 16, v162
	v_and_b32_e32 v63, 0xffff0000, v162
	v_lshlrev_b32_e32 v162, 16, v163
	v_and_b32_e32 v163, 0xffff0000, v163
	v_lshlrev_b32_e32 v64, 16, v164
	v_and_b32_e32 v65, 0xffff0000, v164
	v_lshlrev_b32_e32 v164, 16, v165
	v_and_b32_e32 v165, 0xffff0000, v165
	v_lshlrev_b32_e32 v66, 16, v166
	v_and_b32_e32 v67, 0xffff0000, v166
	v_lshlrev_b32_e32 v166, 16, v167
	v_and_b32_e32 v167, 0xffff0000, v167
	v_lshlrev_b32_e32 v68, 16, v168
	v_and_b32_e32 v69, 0xffff0000, v168
	v_lshlrev_b32_e32 v168, 16, v169
	v_and_b32_e32 v169, 0xffff0000, v169
	v_lshlrev_b32_e32 v70, 16, v170
	v_and_b32_e32 v71, 0xffff0000, v170
	v_lshlrev_b32_e32 v170, 16, v171
	v_and_b32_e32 v171, 0xffff0000, v171
	v_lshlrev_b32_e32 v72, 16, v172
	v_and_b32_e32 v73, 0xffff0000, v172
	v_lshlrev_b32_e32 v172, 16, v173
	v_and_b32_e32 v173, 0xffff0000, v173
	v_lshlrev_b32_e32 v74, 16, v174
	v_and_b32_e32 v75, 0xffff0000, v174
	v_lshlrev_b32_e32 v174, 16, v175
	v_and_b32_e32 v175, 0xffff0000, v175
	s_waitcnt lgkmcnt(3)
	v_pk_mul_f32 v[20:21], v[20:21], v[60:61]
	v_pk_mul_f32 v[22:23], v[22:23], v[160:161]
	s_waitcnt lgkmcnt(2)
	v_pk_mul_f32 v[24:25], v[24:25], v[62:63]
	v_pk_mul_f32 v[26:27], v[26:27], v[162:163]
	s_waitcnt lgkmcnt(1)
	v_pk_mul_f32 v[28:29], v[28:29], v[64:65]
	v_pk_mul_f32 v[30:31], v[30:31], v[164:165]
	s_waitcnt lgkmcnt(0)
	v_pk_mul_f32 v[32:33], v[32:33], v[66:67]
	v_pk_mul_f32 v[34:35], v[34:35], v[166:167]
	v_pk_mul_f32 v[160:161], v[4:5], v[68:69]
	v_pk_mul_f32 v[162:163], v[6:7], v[168:169]
	v_pk_mul_f32 v[164:165], v[8:9], v[70:71]
	v_pk_mul_f32 v[166:167], v[10:11], v[170:171]
	v_pk_mul_f32 v[168:169], v[12:13], v[72:73]
	v_pk_mul_f32 v[170:171], v[14:15], v[172:173]
	v_pk_mul_f32 v[172:173], v[16:17], v[74:75]
	v_pk_mul_f32 v[174:175], v[18:19], v[174:175]
	v_cvt_pk_bf16_f32 v4, v20, v21
	v_cvt_pk_bf16_f32 v5, v22, v23
	v_cvt_pk_bf16_f32 v6, v24, v25
	v_cvt_pk_bf16_f32 v7, v26, v27
	v_cvt_pk_bf16_f32 v8, v28, v29
	v_cvt_pk_bf16_f32 v9, v30, v31
	v_cvt_pk_bf16_f32 v10, v32, v33
	v_cvt_pk_bf16_f32 v11, v34, v35
	v_cvt_pk_bf16_f32 v12, v160, v161
	v_cvt_pk_bf16_f32 v13, v162, v163
	v_cvt_pk_bf16_f32 v14, v164, v165
	v_cvt_pk_bf16_f32 v15, v166, v167
	v_cvt_pk_bf16_f32 v16, v168, v169
	v_cvt_pk_bf16_f32 v17, v170, v171
	v_cvt_pk_bf16_f32 v18, v172, v173
	v_cvt_pk_bf16_f32 v19, v174, v175
	global_store_dwordx4 v[58:59], v[4:7], off
	global_store_dwordx4 v[52:53], v[8:11], off
	global_store_dwordx4 v[54:55], v[12:15], off
	global_store_dwordx4 v[56:57], v[16:19], off
	v_lshl_add_u64 v[52:53], v[2:3], 0, s[2:3]
	v_add_co_u32_e64 v54, s[0:1], s27, v52
	s_nop 1
	v_addc_co_u32_e64 v55, s[0:1], 0, v53, s[0:1]
	s_nop 1
	ds_read_b128 v[4:7], v0
	ds_read_b128 v[8:11], v0 offset:16
	ds_read_b128 v[12:15], v0 offset:2048
	ds_read_b128 v[16:19], v0 offset:2064
	ds_read_b128 v[20:23], v0 offset:4096
	ds_read_b128 v[24:27], v0 offset:4112
	ds_read_b128 v[28:31], v0 offset:6144
	ds_read_b128 v[32:35], v0 offset:6160
	s_nop 1
	s_nop 1
	s_nop 1
	v_add_co_u32_e32 v56, vcc, s29, v52
	s_add_u32 s2, s2, 0x8000
	s_nop 1
	v_addc_co_u32_e32 v57, vcc, 0, v53, vcc
	v_add_co_u32_e32 v58, vcc, s31, v52
	s_addc_u32 s3, s3, 0
	s_nop 1
	v_addc_co_u32_e32 v59, vcc, 0, v53, vcc
	v_add_u32_e32 v0, 0x2000, v0
	v_add_co_u32_e32 v52, vcc, s35, v52
	s_nop 1
	v_addc_co_u32_e32 v53, vcc, 0, v53, vcc
	s_waitcnt vmcnt(12)
	v_lshlrev_b32_e32 v60, 16, v176
	v_and_b32_e32 v61, 0xffff0000, v176
	v_lshlrev_b32_e32 v176, 16, v177
	v_and_b32_e32 v177, 0xffff0000, v177
	v_lshlrev_b32_e32 v62, 16, v178
	v_and_b32_e32 v63, 0xffff0000, v178
	v_lshlrev_b32_e32 v178, 16, v179
	v_and_b32_e32 v179, 0xffff0000, v179
	v_lshlrev_b32_e32 v64, 16, v180
	v_and_b32_e32 v65, 0xffff0000, v180
	v_lshlrev_b32_e32 v180, 16, v181
	v_and_b32_e32 v181, 0xffff0000, v181
	v_lshlrev_b32_e32 v66, 16, v182
	v_and_b32_e32 v67, 0xffff0000, v182
	v_lshlrev_b32_e32 v182, 16, v183
	v_and_b32_e32 v183, 0xffff0000, v183
	v_lshlrev_b32_e32 v68, 16, v184
	v_and_b32_e32 v69, 0xffff0000, v184
	v_lshlrev_b32_e32 v184, 16, v185
	v_and_b32_e32 v185, 0xffff0000, v185
	v_lshlrev_b32_e32 v70, 16, v186
	v_and_b32_e32 v71, 0xffff0000, v186
	v_lshlrev_b32_e32 v186, 16, v187
	v_and_b32_e32 v187, 0xffff0000, v187
	v_lshlrev_b32_e32 v72, 16, v188
	v_and_b32_e32 v73, 0xffff0000, v188
	v_lshlrev_b32_e32 v188, 16, v189
	v_and_b32_e32 v189, 0xffff0000, v189
	v_lshlrev_b32_e32 v74, 16, v190
	v_and_b32_e32 v75, 0xffff0000, v190
	v_lshlrev_b32_e32 v190, 16, v191
	v_and_b32_e32 v191, 0xffff0000, v191
	s_waitcnt lgkmcnt(3)
	v_pk_mul_f32 v[20:21], v[20:21], v[60:61]
	v_pk_mul_f32 v[22:23], v[22:23], v[176:177]
	s_waitcnt lgkmcnt(2)
	v_pk_mul_f32 v[24:25], v[24:25], v[62:63]
	v_pk_mul_f32 v[26:27], v[26:27], v[178:179]
	s_waitcnt lgkmcnt(1)
	v_pk_mul_f32 v[28:29], v[28:29], v[64:65]
	v_pk_mul_f32 v[30:31], v[30:31], v[180:181]
	s_waitcnt lgkmcnt(0)
	v_pk_mul_f32 v[32:33], v[32:33], v[66:67]
	v_pk_mul_f32 v[34:35], v[34:35], v[182:183]
	v_pk_mul_f32 v[176:177], v[4:5], v[68:69]
	v_pk_mul_f32 v[178:179], v[6:7], v[184:185]
	v_pk_mul_f32 v[180:181], v[8:9], v[70:71]
	v_pk_mul_f32 v[182:183], v[10:11], v[186:187]
	v_pk_mul_f32 v[184:185], v[12:13], v[72:73]
	v_pk_mul_f32 v[186:187], v[14:15], v[188:189]
	v_pk_mul_f32 v[188:189], v[16:17], v[74:75]
	v_pk_mul_f32 v[190:191], v[18:19], v[190:191]
	v_cvt_pk_bf16_f32 v4, v20, v21
	v_cvt_pk_bf16_f32 v5, v22, v23
	v_cvt_pk_bf16_f32 v6, v24, v25
	v_cvt_pk_bf16_f32 v7, v26, v27
	v_cvt_pk_bf16_f32 v8, v28, v29
	v_cvt_pk_bf16_f32 v9, v30, v31
	v_cvt_pk_bf16_f32 v10, v32, v33
	v_cvt_pk_bf16_f32 v11, v34, v35
	v_cvt_pk_bf16_f32 v12, v176, v177
	v_cvt_pk_bf16_f32 v13, v178, v179
	v_cvt_pk_bf16_f32 v14, v180, v181
	v_cvt_pk_bf16_f32 v15, v182, v183
	v_cvt_pk_bf16_f32 v16, v184, v185
	v_cvt_pk_bf16_f32 v17, v186, v187
	v_cvt_pk_bf16_f32 v18, v188, v189
	v_cvt_pk_bf16_f32 v19, v190, v191
	global_store_dwordx4 v[58:59], v[4:7], off
	global_store_dwordx4 v[52:53], v[8:11], off
	global_store_dwordx4 v[54:55], v[12:15], off
	global_store_dwordx4 v[56:57], v[16:19], off
	s_branch .LBB0_266

.LBB0_1623:
	s_andn2_b64 vcc, exec, s[0:1]
	s_waitcnt lgkmcnt(0)
	s_barrier
	s_cbranch_vccnz .LBB0_1590
	ds_read2st64_b32 v[4:5], v143 offset1:1
	ds_read2st64_b32 v[12:13], v143 offset0:2 offset1:3
	ds_read2st64_b32 v[14:15], v143 offset0:4 offset1:5
	ds_read2st64_b32 v[16:17], v143 offset0:6 offset1:7
	s_lshl_b32 s0, s48, 6
	s_and_b32 s4, s0, 0x2000
	s_waitcnt lgkmcnt(2)
	v_sub_f32_e32 v7, v135, v12
	v_sub_f32_e32 v112, v0, v4
	v_sub_f32_e32 v10, v134, v5
	v_sub_f32_e32 v5, v136, v13
	s_waitcnt lgkmcnt(1)
	v_sub_f32_e32 v4, v2, v14
	v_sub_f32_e32 v2, v20, v15
	s_waitcnt lgkmcnt(0)
	v_sub_f32_e32 v0, v21, v16
	ds_read2st64_b32 v[12:13], v143 offset0:8 offset1:9
	v_sub_f32_e32 v3, v3, v17
	ds_read2st64_b32 v[16:17], v143 offset0:10 offset1:11
	ds_read2st64_b32 v[20:21], v143 offset0:12 offset1:13
	ds_read2st64_b32 v[30:31], v143 offset0:14 offset1:15
	s_waitcnt lgkmcnt(3)
	v_sub_f32_e32 v15, v6, v12
	v_sub_f32_e32 v14, v8, v13
	s_waitcnt lgkmcnt(2)
	v_sub_f32_e32 v13, v9, v16
	v_sub_f32_e32 v12, v22, v17
	s_waitcnt lgkmcnt(1)
	v_sub_f32_e32 v8, v28, v21
	s_waitcnt lgkmcnt(0)
	v_sub_f32_e32 v6, v29, v30
	ds_read2st64_b32 v[16:17], v143 offset0:16 offset1:17
	v_sub_f32_e32 v9, v23, v31
	ds_read2st64_b32 v[28:29], v143 offset0:18 offset1:19
	ds_read2st64_b32 v[30:31], v143 offset0:20 offset1:21
	ds_read2st64_b32 v[32:33], v143 offset0:22 offset1:23
	v_sub_f32_e32 v11, v11, v20
	s_waitcnt lgkmcnt(3)
	v_sub_f32_e32 v22, v133, v16
	v_sub_f32_e32 v23, v132, v17
	s_waitcnt lgkmcnt(2)
	v_sub_f32_e32 v21, v131, v28
	v_sub_f32_e32 v20, v130, v29
	s_waitcnt lgkmcnt(0)
	v_sub_f32_e32 v16, v35, v32
	v_sub_f32_e32 v17, v34, v33
	ds_read2st64_b32 v[28:29], v143 offset0:24 offset1:25
	ds_read2st64_b32 v[32:33], v143 offset0:26 offset1:27
	ds_read2st64_b32 v[34:35], v143 offset0:28 offset1:29
	ds_read2st64_b32 v[46:47], v143 offset0:30 offset1:31
	v_sub_f32_e32 v19, v19, v30
	v_sub_f32_e32 v18, v18, v31
	v_mul_f32_e32 v151, v22, v22
	s_waitcnt lgkmcnt(3)
	v_sub_f32_e32 v31, v39, v28
	v_sub_f32_e32 v30, v38, v29
	s_waitcnt lgkmcnt(2)
	v_sub_f32_e32 v29, v25, v32
	v_sub_f32_e32 v28, v24, v33
	s_waitcnt lgkmcnt(1)
	v_sub_f32_e32 v27, v27, v34
	v_sub_f32_e32 v26, v26, v35
	s_waitcnt lgkmcnt(0)
	v_sub_f32_e32 v24, v43, v46
	v_sub_f32_e32 v25, v42, v47
	ds_read2st64_b32 v[32:33], v143 offset0:32 offset1:33
	ds_read2st64_b32 v[34:35], v143 offset0:34 offset1:35
	ds_read2st64_b32 v[38:39], v143 offset0:36 offset1:37
	ds_read2st64_b32 v[42:43], v143 offset0:38 offset1:39
	v_fmac_f32_e32 v151, v112, v112
	v_mul_f32_e32 v148, v23, v23
	v_fmac_f32_e32 v148, v10, v10
	s_waitcnt lgkmcnt(1)
	v_sub_f32_e32 v36, v36, v38
	v_sub_f32_e32 v37, v37, v39
	s_waitcnt lgkmcnt(0)
	v_sub_f32_e32 v38, v53, v42
	v_sub_f32_e32 v39, v52, v43
	ds_read2st64_b32 v[42:43], v143 offset0:40 offset1:41
	ds_read2st64_b32 v[46:47], v143 offset0:42 offset1:43
	ds_read2st64_b32 v[48:49], v143 offset0:44 offset1:45
	ds_read2st64_b32 v[52:53], v143 offset0:46 offset1:47
	v_sub_f32_e32 v32, v161, v32
	v_fmac_f32_e32 v151, v32, v32
	v_sub_f32_e32 v33, v160, v33
	s_waitcnt lgkmcnt(3)
	v_sub_f32_e32 v40, v40, v42
	v_sub_f32_e32 v41, v41, v43
	s_waitcnt lgkmcnt(2)
	v_sub_f32_e32 v42, v55, v46
	v_sub_f32_e32 v43, v54, v47
	s_waitcnt lgkmcnt(1)
	v_sub_f32_e32 v44, v44, v48
	v_sub_f32_e32 v45, v45, v49
	s_waitcnt lgkmcnt(0)
	v_sub_f32_e32 v46, v61, v52
	v_sub_f32_e32 v47, v60, v53
	ds_read2st64_b32 v[48:49], v143 offset0:48 offset1:49
	ds_read2st64_b32 v[60:61], v143 offset0:50 offset1:51
	ds_read2st64_b32 v[62:63], v143 offset0:52 offset1:53
	ds_read2st64_b32 v[64:65], v143 offset0:54 offset1:55
	v_fmac_f32_e32 v148, v33, v33
	v_mul_f32_e32 v144, v21, v21
	s_waitcnt lgkmcnt(2)
	v_sub_f32_e32 v53, v153, v60
	v_sub_f32_e32 v55, v155, v48
	v_sub_f32_e32 v54, v154, v49
	v_sub_f32_e32 v52, v152, v61
	s_waitcnt lgkmcnt(0)
	v_sub_f32_e32 v48, v87, v64
	v_sub_f32_e32 v49, v86, v65
	ds_read2st64_b32 v[60:61], v143 offset0:56 offset1:57
	ds_read2st64_b32 v[64:65], v143 offset0:58 offset1:59
	ds_read2st64_b32 v[86:87], v143 offset0:60 offset1:61
	ds_read2st64_b32 v[152:153], v143 offset0:62 offset1:63
	v_sub_f32_e32 v51, v51, v62
	v_sub_f32_e32 v50, v50, v63
	v_fmac_f32_e32 v151, v55, v55
	s_waitcnt lgkmcnt(3)
	v_sub_f32_e32 v63, v157, v60
	v_sub_f32_e32 v62, v156, v61
	s_waitcnt lgkmcnt(2)
	v_sub_f32_e32 v61, v57, v64
	v_sub_f32_e32 v60, v56, v65
	s_waitcnt lgkmcnt(1)
	v_sub_f32_e32 v59, v59, v86
	v_sub_f32_e32 v58, v58, v87
	s_waitcnt lgkmcnt(0)
	v_sub_f32_e32 v56, v95, v152
	v_sub_f32_e32 v57, v94, v153
	ds_read2st64_b32 v[64:65], v143 offset0:64 offset1:65
	ds_read2st64_b32 v[86:87], v143 offset0:66 offset1:67
	ds_read2st64_b32 v[94:95], v143 offset0:68 offset1:69
	ds_read2st64_b32 v[152:153], v143 offset0:70 offset1:71
	v_fmac_f32_e32 v148, v54, v54
	v_fmac_f32_e32 v144, v7, v7
	s_waitcnt lgkmcnt(2)
	v_sub_f32_e32 v66, v66, v86
	v_sub_f32_e32 v64, v69, v64
	v_sub_f32_e32 v65, v68, v65
	v_sub_f32_e32 v67, v67, v87
	s_waitcnt lgkmcnt(1)
	v_sub_f32_e32 v68, v73, v94
	v_sub_f32_e32 v69, v72, v95
	s_waitcnt lgkmcnt(0)
	v_sub_f32_e32 v70, v70, v152
	v_sub_f32_e32 v71, v71, v153
	ds_read2st64_b32 v[72:73], v143 offset0:72 offset1:73
	ds_read2st64_b32 v[86:87], v143 offset0:74 offset1:75
	ds_read2st64_b32 v[94:95], v143 offset0:76 offset1:77
	ds_read2st64_b32 v[152:153], v143 offset0:78 offset1:79
	v_fmac_f32_e32 v151, v64, v64
	v_fmac_f32_e32 v148, v65, v65
	s_waitcnt lgkmcnt(2)
	v_sub_f32_e32 v74, v74, v86
	v_sub_f32_e32 v72, v77, v72
	v_sub_f32_e32 v73, v76, v73
	s_waitcnt lgkmcnt(1)
	v_sub_f32_e32 v76, v81, v94
	v_sub_f32_e32 v77, v80, v95
	s_waitcnt lgkmcnt(0)
	v_sub_f32_e32 v78, v78, v152
	v_sub_f32_e32 v79, v79, v153
	ds_read2st64_b32 v[80:81], v143 offset0:80 offset1:81
	ds_read2st64_b32 v[94:95], v143 offset0:82 offset1:83
	ds_read2st64_b32 v[152:153], v143 offset0:84 offset1:85
	ds_read2st64_b32 v[154:155], v143 offset0:86 offset1:87
	v_sub_f32_e32 v75, v75, v87
	v_sub_f32_e32 v34, v159, v34
	v_fmac_f32_e32 v144, v34, v34
	s_waitcnt lgkmcnt(3)
	v_sub_f32_e32 v87, v85, v80
	v_sub_f32_e32 v86, v84, v81
	s_waitcnt lgkmcnt(2)
	v_sub_f32_e32 v85, v83, v94
	v_sub_f32_e32 v84, v82, v95
	s_waitcnt lgkmcnt(1)
	v_sub_f32_e32 v83, v147, v152
	v_sub_f32_e32 v82, v146, v153
	s_waitcnt lgkmcnt(0)
	v_sub_f32_e32 v80, v89, v154
	v_sub_f32_e32 v81, v88, v155
	ds_read2st64_b32 v[88:89], v143 offset0:88 offset1:89
	ds_read2st64_b32 v[146:147], v143 offset0:90 offset1:91
	ds_read2st64_b32 v[152:153], v143 offset0:92 offset1:93
	ds_read2st64_b32 v[154:155], v143 offset0:94 offset1:95
	v_fmac_f32_e32 v151, v87, v87
	v_fmac_f32_e32 v148, v86, v86
	v_fmac_f32_e32 v144, v53, v53
	s_waitcnt lgkmcnt(3)
	v_sub_f32_e32 v95, v93, v88
	v_sub_f32_e32 v94, v92, v89
	s_waitcnt lgkmcnt(2)
	v_sub_f32_e32 v93, v91, v146
	v_sub_f32_e32 v92, v90, v147
	s_waitcnt lgkmcnt(1)
	v_sub_f32_e32 v91, v150, v152
	v_sub_f32_e32 v90, v149, v153
	s_waitcnt lgkmcnt(0)
	v_sub_f32_e32 v88, v97, v154
	v_sub_f32_e32 v89, v96, v155
	ds_read2st64_b32 v[96:97], v143 offset0:96 offset1:97
	ds_read2st64_b32 v[146:147], v143 offset0:98 offset1:99
	ds_read2st64_b32 v[152:153], v143 offset0:100 offset1:101
	ds_read2st64_b32 v[154:155], v143 offset0:102 offset1:103
	v_fmac_f32_e32 v144, v66, v66
	v_fmac_f32_e32 v144, v85, v85
	s_waitcnt lgkmcnt(2)
	v_sub_f32_e32 v98, v98, v146
	v_sub_f32_e32 v96, v101, v96
	v_sub_f32_e32 v97, v100, v97
	v_sub_f32_e32 v99, v99, v147
	s_waitcnt lgkmcnt(1)
	v_sub_f32_e32 v100, v105, v152
	v_sub_f32_e32 v101, v104, v153
	s_waitcnt lgkmcnt(0)
	v_sub_f32_e32 v102, v102, v154
	v_sub_f32_e32 v103, v103, v155
	ds_read2st64_b32 v[104:105], v143 offset0:104 offset1:105
	ds_read2st64_b32 v[146:147], v143 offset0:106 offset1:107
	ds_read2st64_b32 v[152:153], v143 offset0:108 offset1:109
	ds_read2st64_b32 v[154:155], v143 offset0:110 offset1:111
	v_fmac_f32_e32 v151, v96, v96
	v_fmac_f32_e32 v148, v97, v97
	s_waitcnt lgkmcnt(2)
	v_sub_f32_e32 v106, v106, v146
	v_sub_f32_e32 v107, v107, v147
	ds_read2st64_b32 v[146:147], v143 offset0:112 offset1:113
	v_sub_f32_e32 v104, v109, v104
	v_sub_f32_e32 v105, v108, v105
	s_waitcnt lgkmcnt(2)
	v_sub_f32_e32 v108, v145, v152
	v_sub_f32_e32 v109, v113, v153
	s_waitcnt lgkmcnt(1)
	v_sub_f32_e32 v110, v110, v154
	v_sub_f32_e32 v111, v111, v155
	ds_read2st64_b32 v[152:153], v143 offset0:114 offset1:115
	ds_read2st64_b32 v[154:155], v143 offset0:116 offset1:117
	ds_read2st64_b32 v[156:157], v143 offset0:118 offset1:119
	s_waitcnt lgkmcnt(3)
	v_sub_f32_e32 v117, v117, v146
	v_fmac_f32_e32 v151, v117, v117
	v_sub_f32_e32 v116, v116, v147
	s_waitcnt lgkmcnt(1)
	v_sub_f32_e32 v113, v121, v154
	ds_bpermute_b32 v121, v213, v151
	ds_read2st64_b32 v[146:147], v143 offset0:120 offset1:121
	v_sub_f32_e32 v115, v115, v152
	v_sub_f32_e32 v114, v114, v153
	v_sub_f32_e32 v119, v119, v155
	s_waitcnt lgkmcnt(1)
	v_add_f32_e32 v121, v151, v121
	ds_bpermute_b32 v145, v214, v121
	ds_read2st64_b32 v[150:151], v143 offset0:122 offset1:123
	ds_read2st64_b32 v[152:153], v143 offset0:124 offset1:125
	ds_read2st64_b32 v[154:155], v143 offset0:126 offset1:127
	v_fmac_f32_e32 v148, v116, v116
	s_waitcnt lgkmcnt(4)
	v_sub_f32_e32 v124, v124, v147
	ds_bpermute_b32 v147, v213, v148
	s_waitcnt lgkmcnt(4)
	v_add_f32_e32 v145, v121, v145
	ds_bpermute_b32 v149, v215, v145
	v_sub_f32_e32 v121, v125, v146
	v_fmac_f32_e32 v144, v98, v98
	s_waitcnt lgkmcnt(1)
	v_add_f32_e32 v147, v148, v147
	ds_bpermute_b32 v148, v214, v147
	s_waitcnt lgkmcnt(1)
	v_add_f32_e32 v125, v145, v149
	ds_bpermute_b32 v143, v216, v125
	v_fmac_f32_e32 v144, v115, v115
	v_sub_f32_e32 v122, v122, v150
	v_mul_f32_e32 v131, v20, v20
	v_fmac_f32_e32 v131, v5, v5
	s_waitcnt lgkmcnt(0)
	v_add_f32_e32 v143, v125, v143
	ds_bpermute_b32 v145, v217, v143
	v_sub_f32_e32 v125, v123, v151
	v_sub_f32_e32 v123, v129, v152
	ds_bpermute_b32 v151, v213, v144
	v_sub_f32_e32 v35, v158, v35
	s_waitcnt lgkmcnt(1)
	v_add_f32_e32 v129, v143, v145
	v_fmamk_f32 v129, v129, 0x3b800000, v244
	v_mul_f32_e32 v143, 0x4f800000, v129
	v_cmp_gt_f32_e32 vcc, s24, v129
	s_waitcnt lgkmcnt(0)
	v_add_f32_e32 v144, v144, v151
	ds_bpermute_b32 v151, v214, v144
	v_cndmask_b32_e32 v129, v129, v143, vcc
	v_sqrt_f32_e32 v143, v129
	v_fmac_f32_e32 v131, v35, v35
	v_fmac_f32_e32 v131, v52, v52
	s_waitcnt lgkmcnt(0)
	v_add_f32_e32 v144, v144, v151
	v_add_u32_e32 v145, -1, v143
	v_fma_f32 v146, -v145, v143, v129
	v_cmp_ge_f32_e64 s[0:1], 0, v146
	v_add_u32_e32 v146, 1, v143
	v_fmac_f32_e32 v131, v67, v67
	v_cndmask_b32_e64 v145, v143, v145, s[0:1]
	v_fma_f32 v143, -v146, v143, v129
	v_cmp_lt_f32_e64 s[0:1], 0, v143
	v_fmac_f32_e32 v131, v84, v84
	v_fmac_f32_e32 v131, v99, v99
	v_cndmask_b32_e64 v143, v145, v146, s[0:1]
	v_mul_f32_e32 v145, 0x37800000, v143
	v_cndmask_b32_e32 v143, v143, v145, vcc
	v_add_f32_e32 v145, v147, v148
	ds_bpermute_b32 v146, v215, v145
	v_cmp_class_f32_e32 vcc, v129, v245
	v_fmac_f32_e32 v131, v114, v114
	ds_bpermute_b32 v151, v213, v131
	v_cndmask_b32_e32 v129, v143, v129, vcc
	s_waitcnt lgkmcnt(1)
	v_add_f32_e32 v145, v145, v146
	ds_bpermute_b32 v146, v216, v145
	v_div_scale_f32 v143, s[0:1], v129, v129, s25
	v_rcp_f32_e32 v147, v143
	s_waitcnt lgkmcnt(1)
	v_add_f32_e32 v131, v131, v151
	s_waitcnt lgkmcnt(0)
	v_add_f32_e32 v145, v145, v146
	ds_bpermute_b32 v146, v217, v145
	v_fma_f32 v148, -v143, v147, 1.0
	v_fmac_f32_e32 v147, v148, v147
	v_div_scale_f32 v148, vcc, s25, v129, s25
	s_waitcnt lgkmcnt(0)
	v_add_f32_e32 v145, v145, v146
	v_fmamk_f32 v145, v145, 0x3b800000, v244
	v_mul_f32_e32 v146, 0x4f800000, v145
	v_cmp_gt_f32_e64 s[0:1], s24, v145
	v_mul_f32_e32 v149, v148, v147
	v_fma_f32 v150, -v143, v149, v148
	v_cndmask_b32_e64 v145, v145, v146, s[0:1]
	v_sqrt_f32_e32 v146, v145
	v_fmac_f32_e32 v149, v150, v147
	v_fma_f32 v143, -v143, v149, v148
	v_div_fmas_f32 v143, v143, v147, v149
	v_add_u32_e32 v148, -1, v146
	v_fma_f32 v150, -v148, v146, v145
	v_cmp_ge_f32_e64 s[2:3], 0, v150
	v_add_u32_e32 v150, 1, v146
	v_div_fixup_f32 v129, v143, v129, s25
	v_cndmask_b32_e64 v148, v146, v148, s[2:3]
	v_fma_f32 v146, -v150, v146, v145
	v_cmp_lt_f32_e64 s[2:3], 0, v146
	ds_bpermute_b32 v151, v214, v131
	v_mul_f32_e32 v133, v19, v19
	v_cndmask_b32_e64 v146, v148, v150, s[2:3]
	v_mul_f32_e32 v148, 0x37800000, v146
	v_cndmask_b32_e64 v146, v146, v148, s[0:1]
	ds_bpermute_b32 v148, v215, v144
	v_cmp_class_f32_e64 s[0:1], v145, v245
	s_waitcnt lgkmcnt(1)
	v_add_f32_e32 v131, v131, v151
	v_fmac_f32_e32 v133, v4, v4
	v_cndmask_b32_e64 v145, v146, v145, s[0:1]
	s_waitcnt lgkmcnt(0)
	v_add_f32_e32 v144, v144, v148
	ds_bpermute_b32 v148, v216, v144
	v_div_scale_f32 v146, s[0:1], v145, v145, s25
	v_rcp_f32_e32 v150, v146
	v_fmac_f32_e32 v133, v36, v36
	s_waitcnt lgkmcnt(0)
	v_add_f32_e32 v144, v144, v148
	ds_bpermute_b32 v147, v217, v144
	v_fma_f32 v143, -v146, v150, 1.0
	v_fmac_f32_e32 v150, v143, v150
	v_div_scale_f32 v143, vcc, s25, v145, s25
	s_waitcnt lgkmcnt(0)
	v_add_f32_e32 v144, v144, v147
	v_fmamk_f32 v144, v144, 0x3b800000, v244
	v_mul_f32_e32 v147, 0x4f800000, v144
	v_cmp_gt_f32_e64 s[0:1], s24, v144
	v_mul_f32_e32 v148, v143, v150
	v_fma_f32 v149, -v146, v148, v143
	v_cndmask_b32_e64 v144, v144, v147, s[0:1]
	v_sqrt_f32_e32 v147, v144
	v_fmac_f32_e32 v148, v149, v150
	v_fma_f32 v143, -v146, v148, v143
	v_fmac_f32_e32 v133, v51, v51
	v_add_u32_e32 v146, -1, v147
	v_fma_f32 v149, -v146, v147, v144
	v_cmp_ge_f32_e64 s[2:3], 0, v149
	v_add_u32_e32 v149, 1, v147
	v_fmac_f32_e32 v133, v68, v68
	v_cndmask_b32_e64 v146, v147, v146, s[2:3]
	v_fma_f32 v147, -v149, v147, v144
	v_cmp_lt_f32_e64 s[2:3], 0, v147
	v_fmac_f32_e32 v133, v83, v83
	v_fmac_f32_e32 v133, v100, v100
	v_cndmask_b32_e64 v146, v146, v149, s[2:3]
	v_mul_f32_e32 v147, 0x37800000, v146
	v_cndmask_b32_e64 v146, v146, v147, s[0:1]
	ds_bpermute_b32 v147, v215, v131
	v_cmp_class_f32_e64 s[0:1], v144, v245
	v_fmac_f32_e32 v133, v113, v113
	v_mul_f32_e32 v135, v18, v18
	v_cndmask_b32_e64 v144, v146, v144, s[0:1]
	s_waitcnt lgkmcnt(0)
	v_add_f32_e32 v147, v131, v147
	ds_bpermute_b32 v151, v216, v147
	v_div_fmas_f32 v131, v143, v150, v148
	v_div_fixup_f32 v131, v131, v145, s25
	v_div_scale_f32 v146, s[0:1], v144, v144, s25
	s_waitcnt lgkmcnt(0)
	v_add_f32_e32 v145, v147, v151
	ds_bpermute_b32 v147, v217, v145
	v_rcp_f32_e32 v149, v146
	ds_bpermute_b32 v151, v213, v133
	v_fmac_f32_e32 v135, v2, v2
	v_fmac_f32_e32 v135, v37, v37
	s_waitcnt lgkmcnt(1)
	v_add_f32_e32 v145, v145, v147
	v_fmamk_f32 v145, v145, 0x3b800000, v244
	v_mul_f32_e32 v147, 0x4f800000, v145
	v_cmp_gt_f32_e64 s[0:1], s24, v145
	v_fma_f32 v143, -v146, v149, 1.0
	v_fmac_f32_e32 v149, v143, v149
	v_cndmask_b32_e64 v145, v145, v147, s[0:1]
	v_div_scale_f32 v143, vcc, s25, v144, s25
	v_sqrt_f32_e32 v147, v145
	v_mul_f32_e32 v148, v143, v149
	v_fma_f32 v150, -v146, v148, v143
	v_fmac_f32_e32 v148, v150, v149
	v_fma_f32 v143, -v146, v148, v143
	v_add_u32_e32 v146, -1, v147
	s_waitcnt lgkmcnt(0)
	v_add_f32_e32 v133, v133, v151
	v_fma_f32 v150, -v146, v147, v145
	ds_bpermute_b32 v151, v214, v133
	v_cmp_ge_f32_e64 s[2:3], 0, v150
	v_add_u32_e32 v150, 1, v147
	v_fmac_f32_e32 v135, v50, v50
	v_cndmask_b32_e64 v146, v147, v146, s[2:3]
	v_fma_f32 v147, -v150, v147, v145
	v_cmp_lt_f32_e64 s[2:3], 0, v147
	s_waitcnt lgkmcnt(0)
	v_add_f32_e32 v133, v133, v151
	v_fmac_f32_e32 v135, v69, v69
	v_cndmask_b32_e64 v146, v146, v150, s[2:3]
	v_mul_f32_e32 v147, 0x37800000, v146
	v_cndmask_b32_e64 v146, v146, v147, s[0:1]
	ds_bpermute_b32 v147, v215, v133
	v_cmp_class_f32_e64 s[0:1], v145, v245
	v_fmac_f32_e32 v135, v82, v82
	v_fmac_f32_e32 v135, v101, v101
	v_cndmask_b32_e64 v145, v146, v145, s[0:1]
	s_waitcnt lgkmcnt(0)
	v_add_f32_e32 v147, v133, v147
	ds_bpermute_b32 v151, v216, v147
	v_div_fmas_f32 v133, v143, v149, v148
	v_div_fixup_f32 v133, v133, v144, s25
	v_div_scale_f32 v146, s[0:1], v145, v145, s25
	s_waitcnt lgkmcnt(0)
	v_add_f32_e32 v144, v147, v151
	ds_bpermute_b32 v147, v217, v144
	v_rcp_f32_e32 v150, v146
	v_fmac_f32_e32 v135, v119, v119
	ds_bpermute_b32 v151, v213, v135
	v_mul_f32_e32 v137, v16, v16
	s_waitcnt lgkmcnt(1)
	v_add_f32_e32 v144, v144, v147
	v_fmamk_f32 v144, v144, 0x3b800000, v244
	v_mul_f32_e32 v147, 0x4f800000, v144
	v_cmp_gt_f32_e64 s[0:1], s24, v144
	v_fma_f32 v143, -v146, v150, 1.0
	v_fmac_f32_e32 v150, v143, v150
	v_cndmask_b32_e64 v144, v144, v147, s[0:1]
	v_div_scale_f32 v143, vcc, s25, v145, s25
	v_sqrt_f32_e32 v147, v144
	v_mul_f32_e32 v148, v143, v150
	v_fma_f32 v149, -v146, v148, v143
	v_fmac_f32_e32 v148, v149, v150
	v_fma_f32 v143, -v146, v148, v143
	v_add_u32_e32 v146, -1, v147
	s_waitcnt lgkmcnt(0)
	v_add_f32_e32 v135, v135, v151
	v_fma_f32 v149, -v146, v147, v144
	ds_bpermute_b32 v151, v214, v135
	v_cmp_ge_f32_e64 s[2:3], 0, v149
	v_add_u32_e32 v149, 1, v147
	v_fmac_f32_e32 v137, v0, v0
	v_cndmask_b32_e64 v146, v147, v146, s[2:3]
	v_fma_f32 v147, -v149, v147, v144
	v_cmp_lt_f32_e64 s[2:3], 0, v147
	s_waitcnt lgkmcnt(0)
	v_add_f32_e32 v135, v135, v151
	v_fmac_f32_e32 v137, v38, v38
	v_cndmask_b32_e64 v146, v146, v149, s[2:3]
	v_mul_f32_e32 v147, 0x37800000, v146
	v_cndmask_b32_e64 v146, v146, v147, s[0:1]
	ds_bpermute_b32 v147, v215, v135
	v_cmp_class_f32_e64 s[0:1], v144, v245
	v_fmac_f32_e32 v137, v48, v48
	v_fmac_f32_e32 v137, v70, v70
	v_cndmask_b32_e64 v144, v146, v144, s[0:1]
	s_waitcnt lgkmcnt(0)
	v_add_f32_e32 v147, v135, v147
	ds_bpermute_b32 v151, v216, v147
	v_div_fmas_f32 v135, v143, v150, v148
	v_div_fixup_f32 v135, v135, v145, s25
	v_div_scale_f32 v146, s[0:1], v144, v144, s25
	s_waitcnt lgkmcnt(0)
	v_add_f32_e32 v145, v147, v151
	ds_bpermute_b32 v147, v217, v145
	v_rcp_f32_e32 v149, v146
	v_fmac_f32_e32 v137, v80, v80
	v_fmac_f32_e32 v137, v102, v102
	v_sub_f32_e32 v118, v118, v156
	s_waitcnt lgkmcnt(0)
	v_add_f32_e32 v145, v145, v147
	v_fmamk_f32 v145, v145, 0x3b800000, v244
	v_fmac_f32_e32 v137, v118, v118
	v_mul_f32_e32 v147, 0x4f800000, v145
	v_cmp_gt_f32_e64 s[0:1], s24, v145
	v_fma_f32 v143, -v146, v149, 1.0
	ds_bpermute_b32 v151, v213, v137
	v_cndmask_b32_e64 v145, v145, v147, s[0:1]
	v_fmac_f32_e32 v149, v143, v149
	v_div_scale_f32 v143, vcc, s25, v144, s25
	v_sqrt_f32_e32 v147, v145
	v_mul_f32_e32 v148, v143, v149
	v_fma_f32 v150, -v146, v148, v143
	v_fmac_f32_e32 v148, v150, v149
	v_fma_f32 v143, -v146, v148, v143
	v_add_u32_e32 v146, -1, v147
	s_waitcnt lgkmcnt(0)
	v_add_f32_e32 v137, v137, v151
	v_fma_f32 v150, -v146, v147, v145
	ds_bpermute_b32 v151, v214, v137
	v_cmp_ge_f32_e64 s[2:3], 0, v150
	v_add_u32_e32 v150, 1, v147
	v_mul_f32_e32 v139, v17, v17
	v_cndmask_b32_e64 v146, v147, v146, s[2:3]
	v_fma_f32 v147, -v150, v147, v145
	v_cmp_lt_f32_e64 s[2:3], 0, v147
	s_waitcnt lgkmcnt(0)
	v_add_f32_e32 v137, v137, v151
	v_fmac_f32_e32 v139, v3, v3
	v_cndmask_b32_e64 v146, v146, v150, s[2:3]
	v_mul_f32_e32 v147, 0x37800000, v146
	v_cndmask_b32_e64 v146, v146, v147, s[0:1]
	ds_bpermute_b32 v147, v215, v137
	v_cmp_class_f32_e64 s[0:1], v145, v245
	v_fmac_f32_e32 v139, v39, v39
	v_fmac_f32_e32 v139, v49, v49
	v_cndmask_b32_e64 v145, v146, v145, s[0:1]
	s_waitcnt lgkmcnt(0)
	v_add_f32_e32 v147, v137, v147
	ds_bpermute_b32 v151, v216, v147
	v_div_fmas_f32 v137, v143, v149, v148
	v_div_fixup_f32 v137, v137, v144, s25
	v_div_scale_f32 v146, s[0:1], v145, v145, s25
	s_waitcnt lgkmcnt(0)
	v_add_f32_e32 v144, v147, v151
	ds_bpermute_b32 v147, v217, v144
	v_fmac_f32_e32 v139, v71, v71
	v_rcp_f32_e32 v150, v146
	v_fmac_f32_e32 v139, v81, v81
	v_fmac_f32_e32 v139, v103, v103
	s_waitcnt lgkmcnt(0)
	v_add_f32_e32 v144, v144, v147
	v_sub_f32_e32 v120, v120, v157
	v_fmamk_f32 v144, v144, 0x3b800000, v244
	v_fmac_f32_e32 v139, v120, v120
	v_mul_f32_e32 v147, 0x4f800000, v144
	v_cmp_gt_f32_e64 s[0:1], s24, v144
	v_fma_f32 v143, -v146, v150, 1.0
	ds_bpermute_b32 v151, v213, v139
	v_cndmask_b32_e64 v144, v144, v147, s[0:1]
	v_fmac_f32_e32 v150, v143, v150
	v_div_scale_f32 v143, vcc, s25, v145, s25
	v_sqrt_f32_e32 v147, v144
	v_mul_f32_e32 v148, v143, v150
	v_fma_f32 v149, -v146, v148, v143
	v_fmac_f32_e32 v148, v149, v150
	v_fma_f32 v143, -v146, v148, v143
	v_add_u32_e32 v146, -1, v147
	s_waitcnt lgkmcnt(0)
	v_add_f32_e32 v139, v139, v151
	v_fma_f32 v149, -v146, v147, v144
	ds_bpermute_b32 v151, v214, v139
	v_cmp_ge_f32_e64 s[2:3], 0, v149
	v_add_u32_e32 v149, 1, v147
	v_mul_f32_e32 v141, v31, v31
	v_cndmask_b32_e64 v146, v147, v146, s[2:3]
	v_fma_f32 v147, -v149, v147, v144
	v_cmp_lt_f32_e64 s[2:3], 0, v147
	s_waitcnt lgkmcnt(0)
	v_add_f32_e32 v139, v139, v151
	v_fmac_f32_e32 v141, v15, v15
	v_cndmask_b32_e64 v146, v146, v149, s[2:3]
	v_mul_f32_e32 v147, 0x37800000, v146
	v_cndmask_b32_e64 v146, v146, v147, s[0:1]
	ds_bpermute_b32 v147, v215, v139
	v_cmp_class_f32_e64 s[0:1], v144, v245
	v_fmac_f32_e32 v141, v40, v40
	v_fmac_f32_e32 v141, v63, v63
	v_cndmask_b32_e64 v144, v146, v144, s[0:1]
	s_waitcnt lgkmcnt(0)
	v_add_f32_e32 v147, v139, v147
	ds_bpermute_b32 v151, v216, v147
	v_div_fmas_f32 v139, v143, v150, v148
	v_div_fixup_f32 v139, v139, v145, s25
	v_div_scale_f32 v146, s[0:1], v144, v144, s25
	s_waitcnt lgkmcnt(0)
	v_add_f32_e32 v145, v147, v151
	ds_bpermute_b32 v147, v217, v145
	v_fmac_f32_e32 v141, v72, v72
	v_rcp_f32_e32 v149, v146
	v_fmac_f32_e32 v141, v95, v95
	v_fmac_f32_e32 v141, v104, v104
	s_waitcnt lgkmcnt(0)
	v_add_f32_e32 v145, v145, v147
	v_fmamk_f32 v145, v145, 0x3b800000, v244
	v_fmac_f32_e32 v141, v121, v121
	v_mul_f32_e32 v147, 0x4f800000, v145
	v_cmp_gt_f32_e64 s[0:1], s24, v145
	v_fma_f32 v143, -v146, v149, 1.0
	ds_bpermute_b32 v151, v213, v141
	v_cndmask_b32_e64 v145, v145, v147, s[0:1]
	v_fmac_f32_e32 v149, v143, v149
	v_div_scale_f32 v143, vcc, s25, v144, s25
	v_sqrt_f32_e32 v147, v145
	v_mul_f32_e32 v148, v143, v149
	v_fma_f32 v150, -v146, v148, v143
	v_fmac_f32_e32 v148, v150, v149
	v_fma_f32 v143, -v146, v148, v143
	v_add_u32_e32 v146, -1, v147
	s_waitcnt lgkmcnt(0)
	v_add_f32_e32 v141, v141, v151
	v_fma_f32 v150, -v146, v147, v145
	ds_bpermute_b32 v151, v214, v141
	v_cmp_ge_f32_e64 s[2:3], 0, v150
	v_add_u32_e32 v150, 1, v147
	v_mul_f32_e32 v142, v30, v30
	v_cndmask_b32_e64 v146, v147, v146, s[2:3]
	v_fma_f32 v147, -v150, v147, v145
	v_cmp_lt_f32_e64 s[2:3], 0, v147
	s_waitcnt lgkmcnt(0)
	v_add_f32_e32 v141, v141, v151
	v_fmac_f32_e32 v142, v14, v14
	v_cndmask_b32_e64 v146, v146, v150, s[2:3]
	v_mul_f32_e32 v147, 0x37800000, v146
	v_cndmask_b32_e64 v146, v146, v147, s[0:1]
	ds_bpermute_b32 v147, v215, v141
	v_cmp_class_f32_e64 s[0:1], v145, v245
	v_fmac_f32_e32 v142, v41, v41
	v_fmac_f32_e32 v142, v62, v62
	v_cndmask_b32_e64 v145, v146, v145, s[0:1]
	s_waitcnt lgkmcnt(0)
	v_add_f32_e32 v147, v141, v147
	ds_bpermute_b32 v151, v216, v147
	v_div_fmas_f32 v141, v143, v149, v148
	v_div_fixup_f32 v141, v141, v144, s25
	v_div_scale_f32 v146, s[0:1], v145, v145, s25
	s_waitcnt lgkmcnt(0)
	v_add_f32_e32 v144, v147, v151
	ds_bpermute_b32 v147, v217, v144
	v_fmac_f32_e32 v142, v73, v73
	v_rcp_f32_e32 v150, v146
	v_fmac_f32_e32 v142, v94, v94
	v_fmac_f32_e32 v142, v105, v105
	s_waitcnt lgkmcnt(0)
	v_add_f32_e32 v144, v144, v147
	v_fmamk_f32 v144, v144, 0x3b800000, v244
	v_fmac_f32_e32 v142, v124, v124
	v_mul_f32_e32 v147, 0x4f800000, v144
	v_cmp_gt_f32_e64 s[0:1], s24, v144
	v_fma_f32 v143, -v146, v150, 1.0
	ds_bpermute_b32 v151, v213, v142
	v_cndmask_b32_e64 v144, v144, v147, s[0:1]
	v_fmac_f32_e32 v150, v143, v150
	v_div_scale_f32 v143, vcc, s25, v145, s25
	v_sqrt_f32_e32 v147, v144
	v_mul_f32_e32 v148, v143, v150
	v_fma_f32 v149, -v146, v148, v143
	v_fmac_f32_e32 v148, v149, v150
	v_fma_f32 v143, -v146, v148, v143
	v_add_u32_e32 v146, -1, v147
	s_waitcnt lgkmcnt(0)
	v_add_f32_e32 v142, v142, v151
	v_fma_f32 v149, -v146, v147, v144
	ds_bpermute_b32 v151, v214, v142
	v_cmp_ge_f32_e64 s[2:3], 0, v149
	v_add_u32_e32 v149, 1, v147
	v_mul_f32_e32 v140, v29, v29
	v_cndmask_b32_e64 v146, v147, v146, s[2:3]
	v_fma_f32 v147, -v149, v147, v144
	v_cmp_lt_f32_e64 s[2:3], 0, v147
	s_waitcnt lgkmcnt(0)
	v_add_f32_e32 v142, v142, v151
	v_fmac_f32_e32 v140, v13, v13
	v_cndmask_b32_e64 v146, v146, v149, s[2:3]
	v_mul_f32_e32 v147, 0x37800000, v146
	v_cndmask_b32_e64 v146, v146, v147, s[0:1]
	ds_bpermute_b32 v147, v215, v142
	v_cmp_class_f32_e64 s[0:1], v144, v245
	v_fmac_f32_e32 v140, v42, v42
	v_fmac_f32_e32 v140, v61, v61
	v_cndmask_b32_e64 v144, v146, v144, s[0:1]
	s_waitcnt lgkmcnt(0)
	v_add_f32_e32 v147, v142, v147
	ds_bpermute_b32 v151, v216, v147
	v_div_fmas_f32 v142, v143, v150, v148
	v_div_fixup_f32 v142, v142, v145, s25
	v_div_scale_f32 v146, s[0:1], v144, v144, s25
	s_waitcnt lgkmcnt(0)
	v_add_f32_e32 v145, v147, v151
	ds_bpermute_b32 v147, v217, v145
	v_fmac_f32_e32 v140, v74, v74
	v_rcp_f32_e32 v149, v146
	v_fmac_f32_e32 v140, v93, v93
	v_fmac_f32_e32 v140, v106, v106
	s_waitcnt lgkmcnt(0)
	v_add_f32_e32 v145, v145, v147
	v_fmamk_f32 v145, v145, 0x3b800000, v244
	v_fmac_f32_e32 v140, v122, v122
	v_mul_f32_e32 v147, 0x4f800000, v145
	v_cmp_gt_f32_e64 s[0:1], s24, v145
	v_fma_f32 v143, -v146, v149, 1.0
	ds_bpermute_b32 v151, v213, v140
	v_cndmask_b32_e64 v145, v145, v147, s[0:1]
	v_fmac_f32_e32 v149, v143, v149
	v_div_scale_f32 v143, vcc, s25, v144, s25
	v_sqrt_f32_e32 v147, v145
	v_mul_f32_e32 v148, v143, v149
	v_fma_f32 v150, -v146, v148, v143
	v_fmac_f32_e32 v148, v150, v149
	v_fma_f32 v143, -v146, v148, v143
	v_add_u32_e32 v146, -1, v147
	s_waitcnt lgkmcnt(0)
	v_add_f32_e32 v140, v140, v151
	v_fma_f32 v150, -v146, v147, v145
	ds_bpermute_b32 v151, v214, v140
	v_cmp_ge_f32_e64 s[2:3], 0, v150
	v_add_u32_e32 v150, 1, v147
	v_mul_f32_e32 v138, v28, v28
	v_cndmask_b32_e64 v146, v147, v146, s[2:3]
	v_fma_f32 v147, -v150, v147, v145
	v_cmp_lt_f32_e64 s[2:3], 0, v147
	s_waitcnt lgkmcnt(0)
	v_add_f32_e32 v140, v140, v151
	v_fmac_f32_e32 v138, v12, v12
	v_cndmask_b32_e64 v146, v146, v150, s[2:3]
	v_mul_f32_e32 v147, 0x37800000, v146
	v_cndmask_b32_e64 v146, v146, v147, s[0:1]
	ds_bpermute_b32 v147, v215, v140
	v_cmp_class_f32_e64 s[0:1], v145, v245
	v_fmac_f32_e32 v138, v43, v43
	v_fmac_f32_e32 v138, v60, v60
	v_cndmask_b32_e64 v145, v146, v145, s[0:1]
	s_waitcnt lgkmcnt(0)
	v_add_f32_e32 v147, v140, v147
	ds_bpermute_b32 v151, v216, v147
	v_div_fmas_f32 v140, v143, v149, v148
	v_div_fixup_f32 v140, v140, v144, s25
	v_div_scale_f32 v146, s[0:1], v145, v145, s25
	s_waitcnt lgkmcnt(0)
	v_add_f32_e32 v144, v147, v151
	ds_bpermute_b32 v147, v217, v144
	v_fmac_f32_e32 v138, v75, v75
	v_rcp_f32_e32 v150, v146
	v_fmac_f32_e32 v138, v92, v92
	v_fmac_f32_e32 v138, v107, v107
	s_waitcnt lgkmcnt(0)
	v_add_f32_e32 v144, v144, v147
	v_fmamk_f32 v144, v144, 0x3b800000, v244
	v_fmac_f32_e32 v138, v125, v125
	v_mul_f32_e32 v147, 0x4f800000, v144
	v_cmp_gt_f32_e64 s[0:1], s24, v144
	v_fma_f32 v143, -v146, v150, 1.0
	ds_bpermute_b32 v151, v213, v138
	v_cndmask_b32_e64 v144, v144, v147, s[0:1]
	v_fmac_f32_e32 v150, v143, v150
	v_div_scale_f32 v143, vcc, s25, v145, s25
	v_sqrt_f32_e32 v147, v144
	v_mul_f32_e32 v148, v143, v150
	v_fma_f32 v149, -v146, v148, v143
	v_fmac_f32_e32 v148, v149, v150
	v_fma_f32 v143, -v146, v148, v143
	v_add_u32_e32 v146, -1, v147
	s_waitcnt lgkmcnt(0)
	v_add_f32_e32 v138, v138, v151
	v_fma_f32 v149, -v146, v147, v144
	ds_bpermute_b32 v151, v214, v138
	v_cmp_ge_f32_e64 s[2:3], 0, v149
	v_add_u32_e32 v149, 1, v147
	v_mul_f32_e32 v136, v27, v27
	v_cndmask_b32_e64 v146, v147, v146, s[2:3]
	v_fma_f32 v147, -v149, v147, v144
	v_cmp_lt_f32_e64 s[2:3], 0, v147
	s_waitcnt lgkmcnt(0)
	v_add_f32_e32 v138, v138, v151
	v_fmac_f32_e32 v136, v11, v11
	v_cndmask_b32_e64 v146, v146, v149, s[2:3]
	v_mul_f32_e32 v147, 0x37800000, v146
	v_cndmask_b32_e64 v146, v146, v147, s[0:1]
	ds_bpermute_b32 v147, v215, v138
	v_cmp_class_f32_e64 s[0:1], v144, v245
	v_fmac_f32_e32 v136, v44, v44
	v_fmac_f32_e32 v136, v59, v59
	v_cndmask_b32_e64 v144, v146, v144, s[0:1]
	s_waitcnt lgkmcnt(0)
	v_add_f32_e32 v147, v138, v147
	ds_bpermute_b32 v151, v216, v147
	v_div_fmas_f32 v138, v143, v150, v148
	v_div_fixup_f32 v138, v138, v145, s25
	v_div_scale_f32 v146, s[0:1], v144, v144, s25
	s_waitcnt lgkmcnt(0)
	v_add_f32_e32 v145, v147, v151
	ds_bpermute_b32 v147, v217, v145
	v_fmac_f32_e32 v136, v76, v76
	v_rcp_f32_e32 v149, v146
	v_fmac_f32_e32 v136, v91, v91
	v_fmac_f32_e32 v136, v108, v108
	s_waitcnt lgkmcnt(0)
	v_add_f32_e32 v145, v145, v147
	v_fmamk_f32 v145, v145, 0x3b800000, v244
	v_fmac_f32_e32 v136, v123, v123
	v_mul_f32_e32 v147, 0x4f800000, v145
	v_cmp_gt_f32_e64 s[0:1], s24, v145
	v_fma_f32 v143, -v146, v149, 1.0
	ds_bpermute_b32 v151, v213, v136
	v_cndmask_b32_e64 v145, v145, v147, s[0:1]
	v_fmac_f32_e32 v149, v143, v149
	v_div_scale_f32 v143, vcc, s25, v144, s25
	v_sqrt_f32_e32 v147, v145
	v_mul_f32_e32 v148, v143, v149
	v_fma_f32 v150, -v146, v148, v143
	v_fmac_f32_e32 v148, v150, v149
	v_fma_f32 v143, -v146, v148, v143
	v_add_u32_e32 v146, -1, v147
	s_waitcnt lgkmcnt(0)
	v_add_f32_e32 v136, v136, v151
	v_fma_f32 v150, -v146, v147, v145
	ds_bpermute_b32 v151, v214, v136
	v_cmp_ge_f32_e64 s[2:3], 0, v150
	v_add_u32_e32 v150, 1, v147
	v_mul_f32_e32 v134, v26, v26
	v_cndmask_b32_e64 v146, v147, v146, s[2:3]
	v_fma_f32 v147, -v150, v147, v145
	v_cmp_lt_f32_e64 s[2:3], 0, v147
	s_waitcnt lgkmcnt(0)
	v_add_f32_e32 v136, v136, v151
	v_fmac_f32_e32 v134, v8, v8
	v_cndmask_b32_e64 v146, v146, v150, s[2:3]
	v_mul_f32_e32 v147, 0x37800000, v146
	v_cndmask_b32_e64 v146, v146, v147, s[0:1]
	ds_bpermute_b32 v147, v215, v136
	v_cmp_class_f32_e64 s[0:1], v145, v245
	v_fmac_f32_e32 v134, v45, v45
	v_fmac_f32_e32 v134, v58, v58
	v_cndmask_b32_e64 v145, v146, v145, s[0:1]
	s_waitcnt lgkmcnt(0)
	v_add_f32_e32 v147, v136, v147
	ds_bpermute_b32 v151, v216, v147
	v_div_fmas_f32 v136, v143, v149, v148
	v_div_fixup_f32 v136, v136, v144, s25
	v_div_scale_f32 v146, s[0:1], v145, v145, s25
	s_waitcnt lgkmcnt(0)
	v_add_f32_e32 v144, v147, v151
	ds_bpermute_b32 v147, v217, v144
	v_fmac_f32_e32 v134, v77, v77
	v_rcp_f32_e32 v150, v146
	v_fmac_f32_e32 v134, v90, v90
	v_fmac_f32_e32 v134, v109, v109
	s_waitcnt lgkmcnt(0)
	v_add_f32_e32 v144, v144, v147
	v_sub_f32_e32 v127, v127, v153
	v_fmamk_f32 v144, v144, 0x3b800000, v244
	v_fmac_f32_e32 v134, v127, v127
	v_mul_f32_e32 v147, 0x4f800000, v144
	v_cmp_gt_f32_e64 s[0:1], s24, v144
	v_fma_f32 v143, -v146, v150, 1.0
	ds_bpermute_b32 v151, v213, v134
	v_cndmask_b32_e64 v144, v144, v147, s[0:1]
	v_fmac_f32_e32 v150, v143, v150
	v_div_scale_f32 v143, vcc, s25, v145, s25
	v_sqrt_f32_e32 v147, v144
	v_mul_f32_e32 v148, v143, v150
	v_fma_f32 v149, -v146, v148, v143
	v_fmac_f32_e32 v148, v149, v150
	v_fma_f32 v143, -v146, v148, v143
	v_add_u32_e32 v146, -1, v147
	s_waitcnt lgkmcnt(0)
	v_add_f32_e32 v134, v134, v151
	v_fma_f32 v149, -v146, v147, v144
	ds_bpermute_b32 v151, v214, v134
	v_cmp_ge_f32_e64 s[2:3], 0, v149
	v_add_u32_e32 v149, 1, v147
	v_mul_f32_e32 v132, v24, v24
	v_cndmask_b32_e64 v146, v147, v146, s[2:3]
	v_fma_f32 v147, -v149, v147, v144
	v_cmp_lt_f32_e64 s[2:3], 0, v147
	s_waitcnt lgkmcnt(0)
	v_add_f32_e32 v134, v134, v151
	v_fmac_f32_e32 v132, v6, v6
	v_cndmask_b32_e64 v146, v146, v149, s[2:3]
	v_mul_f32_e32 v147, 0x37800000, v146
	v_cndmask_b32_e64 v146, v146, v147, s[0:1]
	ds_bpermute_b32 v147, v215, v134
	v_cmp_class_f32_e64 s[0:1], v144, v245
	v_fmac_f32_e32 v132, v46, v46
	v_fmac_f32_e32 v132, v56, v56
	v_cndmask_b32_e64 v144, v146, v144, s[0:1]
	s_waitcnt lgkmcnt(0)
	v_add_f32_e32 v147, v134, v147
	ds_bpermute_b32 v151, v216, v147
	v_div_fmas_f32 v134, v143, v150, v148
	v_div_fixup_f32 v134, v134, v145, s25
	v_div_scale_f32 v146, s[0:1], v144, v144, s25
	s_waitcnt lgkmcnt(0)
	v_add_f32_e32 v145, v147, v151
	ds_bpermute_b32 v147, v217, v145
	v_fmac_f32_e32 v132, v78, v78
	v_rcp_f32_e32 v149, v146
	v_fmac_f32_e32 v132, v88, v88
	v_fmac_f32_e32 v132, v110, v110
	s_waitcnt lgkmcnt(0)
	v_add_f32_e32 v145, v145, v147
	v_sub_f32_e32 v126, v126, v154
	v_fmamk_f32 v145, v145, 0x3b800000, v244
	v_fmac_f32_e32 v132, v126, v126
	v_mul_f32_e32 v147, 0x4f800000, v145
	v_cmp_gt_f32_e64 s[0:1], s24, v145
	v_fma_f32 v143, -v146, v149, 1.0
	ds_bpermute_b32 v151, v213, v132
	v_cndmask_b32_e64 v145, v145, v147, s[0:1]
	v_fmac_f32_e32 v149, v143, v149
	v_div_scale_f32 v143, vcc, s25, v144, s25
	v_sqrt_f32_e32 v147, v145
	v_mul_f32_e32 v148, v143, v149
	v_fma_f32 v150, -v146, v148, v143
	v_fmac_f32_e32 v148, v150, v149
	v_fma_f32 v143, -v146, v148, v143
	v_add_u32_e32 v146, -1, v147
	s_waitcnt lgkmcnt(0)
	v_add_f32_e32 v132, v132, v151
	v_fma_f32 v150, -v146, v147, v145
	ds_bpermute_b32 v151, v214, v132
	v_cmp_ge_f32_e64 s[2:3], 0, v150
	v_add_u32_e32 v150, 1, v147
	v_mul_f32_e32 v130, v25, v25
	v_cndmask_b32_e64 v146, v147, v146, s[2:3]
	v_fma_f32 v147, -v150, v147, v145
	v_cmp_lt_f32_e64 s[2:3], 0, v147
	s_waitcnt lgkmcnt(0)
	v_add_f32_e32 v132, v132, v151
	v_fmac_f32_e32 v130, v9, v9
	v_cndmask_b32_e64 v146, v146, v150, s[2:3]
	v_mul_f32_e32 v147, 0x37800000, v146
	v_cndmask_b32_e64 v146, v146, v147, s[0:1]
	ds_bpermute_b32 v147, v215, v132
	v_cmp_class_f32_e64 s[0:1], v145, v245
	v_fmac_f32_e32 v130, v47, v47
	v_fmac_f32_e32 v130, v57, v57
	v_cndmask_b32_e64 v145, v146, v145, s[0:1]
	v_div_scale_f32 v146, s[0:1], v145, v145, s25
	s_waitcnt lgkmcnt(0)
	v_add_f32_e32 v147, v132, v147
	v_rcp_f32_e32 v150, v146
	ds_bpermute_b32 v151, v216, v147
	v_div_fmas_f32 v132, v143, v149, v148
	v_div_fixup_f32 v132, v132, v144, s25
	v_fma_f32 v143, -v146, v150, 1.0
	v_fmac_f32_e32 v150, v143, v150
	s_waitcnt lgkmcnt(0)
	v_add_f32_e32 v143, v147, v151
	ds_bpermute_b32 v144, v217, v143
	v_fmac_f32_e32 v130, v79, v79
	v_fmac_f32_e32 v130, v89, v89
	v_fmac_f32_e32 v130, v111, v111
	v_sub_f32_e32 v128, v128, v155
	s_waitcnt lgkmcnt(0)
	v_add_f32_e32 v143, v143, v144
	v_fmamk_f32 v143, v143, 0x3b800000, v244
	v_fmac_f32_e32 v130, v128, v128
	v_mul_f32_e32 v144, 0x4f800000, v143
	v_cmp_gt_f32_e64 s[0:1], s24, v143
	ds_bpermute_b32 v152, v213, v130
	v_div_scale_f32 v147, vcc, s25, v145, s25
	v_cndmask_b32_e64 v143, v143, v144, s[0:1]
	v_sqrt_f32_e32 v144, v143
	v_mul_f32_e32 v148, v147, v150
	v_fma_f32 v149, -v146, v148, v147
	v_fmac_f32_e32 v148, v149, v150
	v_fma_f32 v146, -v146, v148, v147
	v_add_u32_e32 v147, -1, v144
	s_waitcnt lgkmcnt(0)
	v_add_f32_e32 v130, v130, v152
	v_fma_f32 v151, -v147, v144, v143
	ds_bpermute_b32 v152, v214, v130
	v_cmp_ge_f32_e64 s[2:3], 0, v151
	v_add_u32_e32 v151, 1, v144
	global_load_dword v149, v[196:197], off offset:1024
	v_cndmask_b32_e64 v147, v144, v147, s[2:3]
	v_fma_f32 v144, -v151, v144, v143
	v_cmp_lt_f32_e64 s[2:3], 0, v144
	s_waitcnt lgkmcnt(0)
	v_add_f32_e32 v130, v130, v152
	v_mul_f32_e32 v112, v112, v129
	v_cndmask_b32_e64 v144, v147, v151, s[2:3]
	v_mul_f32_e32 v147, 0x37800000, v144
	v_cndmask_b32_e64 v144, v144, v147, s[0:1]
	ds_bpermute_b32 v147, v215, v130
	v_cmp_class_f32_e64 s[0:1], v143, v245
	v_lshlrev_b32_e32 v153, 12, v222
	v_mul_f32_e32 v22, v22, v129
	v_cndmask_b32_e64 v143, v144, v143, s[0:1]
	v_div_scale_f32 v144, s[0:1], v143, v143, s25
	s_waitcnt lgkmcnt(0)
	v_add_f32_e32 v147, v130, v147
	v_rcp_f32_e32 v151, v144
	ds_bpermute_b32 v152, v216, v147
	v_div_fmas_f32 v130, v146, v150, v148
	v_div_fixup_f32 v130, v130, v145, s25
	v_fma_f32 v145, -v144, v151, 1.0
	global_load_dword v148, v[196:197], off offset:1152
	v_fmac_f32_e32 v151, v145, v151
	s_waitcnt lgkmcnt(0)
	v_add_f32_e32 v145, v147, v152
	ds_bpermute_b32 v146, v217, v145
	v_div_scale_f32 v147, vcc, s25, v143, s25
	v_mul_f32_e32 v150, v147, v151
	v_fma_f32 v152, -v144, v150, v147
	s_waitcnt lgkmcnt(0)
	v_add_f32_e32 v145, v145, v146
	v_fmamk_f32 v145, v145, 0x3b800000, v244
	v_mul_f32_e32 v146, 0x4f800000, v145
	v_cmp_gt_f32_e64 s[0:1], s24, v145
	v_fmac_f32_e32 v150, v152, v151
	v_fma_f32 v144, -v144, v150, v147
	v_cndmask_b32_e64 v145, v145, v146, s[0:1]
	v_sqrt_f32_e32 v146, v145
	v_div_fmas_f32 v144, v144, v151, v150
	v_div_fixup_f32 v143, v144, v143, s25
	v_add3_u32 v153, s37, v194, v153
	v_add_u32_e32 v147, -1, v146
	v_fma_f32 v152, -v147, v146, v145
	v_cmp_ge_f32_e64 s[2:3], 0, v152
	v_add_u32_e32 v152, 1, v146
	v_mul_f32_e32 v10, v10, v131
	v_cndmask_b32_e64 v147, v146, v147, s[2:3]
	v_fma_f32 v146, -v152, v146, v145
	v_cmp_lt_f32_e64 s[2:3], 0, v146
	v_mul_f32_e32 v7, v7, v133
	v_mul_f32_e32 v5, v5, v135
	v_cndmask_b32_e64 v146, v147, v152, s[2:3]
	v_mul_f32_e32 v147, 0x37800000, v146
	v_cndmask_b32_e64 v146, v146, v147, s[0:1]
	v_cmp_class_f32_e64 s[0:1], v145, v245
	v_mul_f32_e32 v4, v4, v137
	v_mul_f32_e32 v2, v2, v139
	v_cndmask_b32_e64 v145, v146, v145, s[0:1]
	v_div_scale_f32 v146, s[0:1], v145, v145, s25
	v_rcp_f32_e32 v147, v146
	v_mul_f32_e32 v0, v0, v141
	v_mul_f32_e32 v3, v3, v142
	v_mul_f32_e32 v15, v15, v140
	v_fma_f32 v144, -v146, v147, 1.0
	v_fmac_f32_e32 v147, v144, v147
	v_div_scale_f32 v144, vcc, s25, v145, s25
	v_mul_f32_e32 v150, v144, v147
	v_fma_f32 v151, -v146, v150, v144
	v_fmac_f32_e32 v150, v151, v147
	v_fma_f32 v144, -v146, v150, v144
	v_div_fmas_f32 v144, v144, v147, v150
	v_div_fixup_f32 v144, v144, v145, s25
	global_load_dword v145, v[196:197], off offset:1280
	global_load_dword v146, v[196:197], off offset:1408
	global_load_dword v147, v[196:197], off offset:1536
	global_load_dword v150, v[196:197], off offset:1664
	global_load_dword v151, v[196:197], off offset:1792
	global_load_dword v152, v[196:197], off offset:1920
	v_mul_f32_e32 v14, v14, v138
	v_mul_f32_e32 v13, v13, v136
	v_mul_f32_e32 v12, v12, v134
	v_mul_f32_e32 v11, v11, v132
	v_mul_f32_e32 v8, v8, v130
	s_waitcnt vmcnt(7)
	v_mul_f32_e32 v112, v112, v149
	v_mul_f32_e32 v10, v10, v149
	v_mul_f32_e32 v7, v7, v149
	v_mul_f32_e32 v5, v5, v149
	v_mul_f32_e32 v4, v4, v149
	v_mul_f32_e32 v2, v2, v149
	v_mul_f32_e32 v0, v0, v149
	v_mul_f32_e32 v3, v3, v149
	v_mul_f32_e32 v15, v15, v149
	v_mul_f32_e32 v14, v14, v149
	v_mul_f32_e32 v13, v13, v149
	v_mul_f32_e32 v12, v12, v149
	v_mul_f32_e32 v11, v11, v149
	v_mul_f32_e32 v8, v8, v149
	v_mul_f32_e32 v6, v6, v143
	v_mul_f32_e32 v6, v149, v6
	v_mul_f32_e32 v9, v9, v144
	v_mul_f32_e32 v9, v149, v9
	s_add_i32 s0, s4, s33
	s_add_i32 s4, s0, s35
	s_lshl_b32 s0, s48, 5
	s_and_b32 s0, s0, 0xe00
	s_waitcnt vmcnt(6)
	v_mul_f32_e32 v22, v22, v148
	ds_write2_b32 v153, v112, v22 offset1:32
	v_mul_f32_e32 v22, v23, v131
	v_mul_f32_e32 v22, v22, v148
	v_add_u32_e32 v23, 0x400, v153
	ds_write2_b32 v23, v10, v22 offset1:32
	v_mul_f32_e32 v10, v21, v133
	v_mul_f32_e32 v10, v10, v148
	v_add_u32_e32 v21, 0x800, v153
	ds_write2_b32 v21, v7, v10 offset1:32
	v_mul_f32_e32 v7, v20, v135
	v_mul_f32_e32 v7, v7, v148
	v_add_u32_e32 v10, 0xc00, v153
	ds_write2_b32 v10, v5, v7 offset1:32
	v_mul_f32_e32 v5, v19, v137
	v_mul_f32_e32 v5, v5, v148
	v_add_u32_e32 v7, 0x2000, v153
	ds_write2_b32 v7, v4, v5 offset1:32
	v_mul_f32_e32 v4, v18, v139
	v_mul_f32_e32 v4, v4, v148
	v_add_u32_e32 v5, 0x2400, v153
	ds_write2_b32 v5, v2, v4 offset1:32
	v_mul_f32_e32 v2, v16, v141
	v_mul_f32_e32 v2, v2, v148
	v_add_u32_e32 v4, 0x2800, v153
	ds_write2_b32 v4, v0, v2 offset1:32
	v_mul_f32_e32 v0, v17, v142
	v_mul_f32_e32 v0, v0, v148
	v_add_u32_e32 v2, 0x2c00, v153
	ds_write2_b32 v2, v3, v0 offset1:32
	v_mul_f32_e32 v0, v31, v140
	v_mul_f32_e32 v0, v0, v148
	v_add_u32_e32 v3, 0x4000, v153
	ds_write2_b32 v3, v15, v0 offset1:32
	v_mul_f32_e32 v0, v30, v138
	v_mul_f32_e32 v0, v0, v148
	v_add_u32_e32 v15, 0x4400, v153
	ds_write2_b32 v15, v14, v0 offset1:32
	v_mul_f32_e32 v0, v29, v136
	v_mul_f32_e32 v0, v0, v148
	v_add_u32_e32 v14, 0x4800, v153
	ds_write2_b32 v14, v13, v0 offset1:32
	v_mul_f32_e32 v0, v28, v134
	v_mul_f32_e32 v0, v0, v148
	v_add_u32_e32 v13, 0x4c00, v153
	ds_write2_b32 v13, v12, v0 offset1:32
	v_mul_f32_e32 v0, v27, v132
	v_mul_f32_e32 v0, v0, v148
	v_add_u32_e32 v12, 0x6000, v153
	ds_write2_b32 v12, v11, v0 offset1:32
	v_mul_f32_e32 v0, v26, v130
	v_mul_f32_e32 v0, v0, v148
	v_add_u32_e32 v11, 0x6400, v153
	ds_write2_b32 v11, v8, v0 offset1:32
	v_mul_f32_e32 v0, v24, v143
	v_mul_f32_e32 v0, v0, v148
	v_add_u32_e32 v8, 0x6800, v153
	ds_write2_b32 v8, v6, v0 offset1:32
	v_mul_f32_e32 v0, v25, v144
	v_mul_f32_e32 v0, v0, v148
	v_add_u32_e32 v6, 0x6c00, v153
	ds_write2_b32 v6, v9, v0 offset1:32
	v_mul_f32_e32 v0, v32, v129
	v_mul_f32_e32 v32, v55, v129
	s_waitcnt vmcnt(5)
	v_mul_f32_e32 v0, v0, v145
	s_waitcnt vmcnt(4)
	v_mul_f32_e32 v32, v32, v146
	v_mul_f32_e32 v9, v33, v131
	ds_write2_b32 v153, v0, v32 offset0:64 offset1:96
	v_mul_f32_e32 v0, v54, v131
	v_mul_f32_e32 v9, v9, v145
	v_mul_f32_e32 v0, v0, v146
	v_mul_f32_e32 v16, v34, v133
	ds_write2_b32 v23, v9, v0 offset0:64 offset1:96
	v_mul_f32_e32 v0, v53, v133
	v_mul_f32_e32 v16, v16, v145
	v_mul_f32_e32 v0, v0, v146
	v_mul_f32_e32 v17, v35, v135
	ds_write2_b32 v21, v16, v0 offset0:64 offset1:96
	v_mul_f32_e32 v0, v52, v135
	v_mul_f32_e32 v17, v17, v145
	v_mul_f32_e32 v0, v0, v146
	v_mul_f32_e32 v18, v36, v137
	ds_write2_b32 v10, v17, v0 offset0:64 offset1:96
	v_mul_f32_e32 v0, v51, v137
	v_mul_f32_e32 v18, v18, v145
	v_mul_f32_e32 v0, v0, v146
	v_mul_f32_e32 v19, v37, v139
	ds_write2_b32 v7, v18, v0 offset0:64 offset1:96
	v_mul_f32_e32 v0, v50, v139
	v_mul_f32_e32 v19, v19, v145
	v_mul_f32_e32 v0, v0, v146
	v_mul_f32_e32 v20, v38, v141
	ds_write2_b32 v5, v19, v0 offset0:64 offset1:96
	v_mul_f32_e32 v0, v48, v141
	v_mul_f32_e32 v20, v20, v145
	v_mul_f32_e32 v0, v0, v146
	v_mul_f32_e32 v22, v39, v142
	ds_write2_b32 v4, v20, v0 offset0:64 offset1:96
	v_mul_f32_e32 v0, v49, v142
	v_mul_f32_e32 v22, v22, v145
	v_mul_f32_e32 v0, v0, v146
	v_mul_f32_e32 v24, v40, v140
	ds_write2_b32 v2, v22, v0 offset0:64 offset1:96
	v_mul_f32_e32 v0, v63, v140
	v_mul_f32_e32 v24, v24, v145
	v_mul_f32_e32 v0, v0, v146
	v_mul_f32_e32 v25, v41, v138
	ds_write2_b32 v3, v24, v0 offset0:64 offset1:96
	v_mul_f32_e32 v0, v62, v138
	v_mul_f32_e32 v25, v25, v145
	v_mul_f32_e32 v0, v0, v146
	v_mul_f32_e32 v26, v42, v136
	ds_write2_b32 v15, v25, v0 offset0:64 offset1:96
	v_mul_f32_e32 v0, v61, v136
	v_mul_f32_e32 v26, v26, v145
	v_mul_f32_e32 v0, v0, v146
	v_mul_f32_e32 v27, v43, v134
	ds_write2_b32 v14, v26, v0 offset0:64 offset1:96
	v_mul_f32_e32 v0, v60, v134
	v_mul_f32_e32 v27, v27, v145
	v_mul_f32_e32 v0, v0, v146
	v_mul_f32_e32 v28, v44, v132
	ds_write2_b32 v13, v27, v0 offset0:64 offset1:96
	v_mul_f32_e32 v0, v59, v132
	v_mul_f32_e32 v28, v28, v145
	v_mul_f32_e32 v0, v0, v146
	v_mul_f32_e32 v29, v45, v130
	ds_write2_b32 v12, v28, v0 offset0:64 offset1:96
	v_mul_f32_e32 v0, v58, v130
	v_mul_f32_e32 v29, v29, v145
	v_mul_f32_e32 v0, v0, v146
	v_mul_f32_e32 v30, v46, v143
	ds_write2_b32 v11, v29, v0 offset0:64 offset1:96
	v_mul_f32_e32 v0, v56, v143
	v_mul_f32_e32 v30, v30, v145
	v_mul_f32_e32 v0, v0, v146
	v_mul_f32_e32 v31, v47, v144
	ds_write2_b32 v8, v30, v0 offset0:64 offset1:96
	v_mul_f32_e32 v0, v57, v144
	v_mul_f32_e32 v31, v31, v145
	v_mul_f32_e32 v0, v0, v146
	ds_write2_b32 v6, v31, v0 offset0:64 offset1:96
	v_mul_f32_e32 v0, v64, v129
	v_mul_f32_e32 v32, v87, v129
	s_waitcnt vmcnt(3)
	v_mul_f32_e32 v0, v0, v147
	s_waitcnt vmcnt(2)
	v_mul_f32_e32 v32, v32, v150
	v_mul_f32_e32 v9, v65, v131
	ds_write2_b32 v153, v0, v32 offset0:128 offset1:160
	v_mul_f32_e32 v0, v86, v131
	v_mul_f32_e32 v9, v9, v147
	v_mul_f32_e32 v0, v0, v150
	v_mul_f32_e32 v16, v66, v133
	ds_write2_b32 v23, v9, v0 offset0:128 offset1:160
	v_mul_f32_e32 v0, v85, v133
	v_mul_f32_e32 v16, v16, v147
	v_mul_f32_e32 v0, v0, v150
	v_mul_f32_e32 v17, v67, v135
	ds_write2_b32 v21, v16, v0 offset0:128 offset1:160
	v_mul_f32_e32 v0, v84, v135
	v_mul_f32_e32 v17, v17, v147
	v_mul_f32_e32 v0, v0, v150
	v_mul_f32_e32 v18, v68, v137
	ds_write2_b32 v10, v17, v0 offset0:128 offset1:160
	v_mul_f32_e32 v0, v83, v137
	v_mul_f32_e32 v18, v18, v147
	v_mul_f32_e32 v0, v0, v150
	v_mul_f32_e32 v19, v69, v139
	ds_write2_b32 v7, v18, v0 offset0:128 offset1:160
	v_mul_f32_e32 v0, v82, v139
	v_mul_f32_e32 v19, v19, v147
	v_mul_f32_e32 v0, v0, v150
	v_mul_f32_e32 v20, v70, v141
	ds_write2_b32 v5, v19, v0 offset0:128 offset1:160
	v_mul_f32_e32 v0, v80, v141
	v_mul_f32_e32 v20, v20, v147
	v_mul_f32_e32 v0, v0, v150
	v_mul_f32_e32 v22, v71, v142
	ds_write2_b32 v4, v20, v0 offset0:128 offset1:160
	v_mul_f32_e32 v0, v81, v142
	v_mul_f32_e32 v22, v22, v147
	v_mul_f32_e32 v0, v0, v150
	v_mul_f32_e32 v24, v72, v140
	ds_write2_b32 v2, v22, v0 offset0:128 offset1:160
	v_mul_f32_e32 v0, v95, v140
	v_mul_f32_e32 v24, v24, v147
	v_mul_f32_e32 v0, v0, v150
	v_mul_f32_e32 v25, v73, v138
	ds_write2_b32 v3, v24, v0 offset0:128 offset1:160
	v_mul_f32_e32 v0, v94, v138
	v_mul_f32_e32 v25, v25, v147
	v_mul_f32_e32 v0, v0, v150
	v_mul_f32_e32 v26, v74, v136
	ds_write2_b32 v15, v25, v0 offset0:128 offset1:160
	v_mul_f32_e32 v0, v93, v136
	v_mul_f32_e32 v26, v26, v147
	v_mul_f32_e32 v0, v0, v150
	v_mul_f32_e32 v27, v75, v134
	ds_write2_b32 v14, v26, v0 offset0:128 offset1:160
	v_mul_f32_e32 v0, v92, v134
	v_mul_f32_e32 v27, v27, v147
	v_mul_f32_e32 v0, v0, v150
	v_mul_f32_e32 v28, v76, v132
	ds_write2_b32 v13, v27, v0 offset0:128 offset1:160
	v_mul_f32_e32 v0, v91, v132
	v_mul_f32_e32 v28, v28, v147
	v_mul_f32_e32 v0, v0, v150
	v_mul_f32_e32 v29, v77, v130
	ds_write2_b32 v12, v28, v0 offset0:128 offset1:160
	v_mul_f32_e32 v0, v90, v130
	v_mul_f32_e32 v29, v29, v147
	v_mul_f32_e32 v0, v0, v150
	v_mul_f32_e32 v30, v78, v143
	ds_write2_b32 v11, v29, v0 offset0:128 offset1:160
	v_mul_f32_e32 v0, v88, v143
	v_mul_f32_e32 v30, v30, v147
	v_mul_f32_e32 v0, v0, v150
	v_mul_f32_e32 v31, v79, v144
	ds_write2_b32 v8, v30, v0 offset0:128 offset1:160
	v_mul_f32_e32 v0, v89, v144
	v_mul_f32_e32 v31, v31, v147
	v_mul_f32_e32 v0, v0, v150
	ds_write2_b32 v6, v31, v0 offset0:128 offset1:160
	v_mul_f32_e32 v0, v96, v129
	v_mul_f32_e32 v32, v117, v129
	s_waitcnt vmcnt(1)
	v_mul_f32_e32 v0, v0, v151
	s_waitcnt vmcnt(0)
	v_mul_f32_e32 v32, v32, v152
	v_mul_f32_e32 v9, v97, v131
	ds_write2_b32 v153, v0, v32 offset0:192 offset1:224
	v_mul_f32_e32 v0, v116, v131
	v_mul_f32_e32 v9, v9, v151
	v_mul_f32_e32 v0, v0, v152
	v_mul_f32_e32 v16, v98, v133
	ds_write2_b32 v23, v9, v0 offset0:192 offset1:224
	v_mul_f32_e32 v0, v115, v133
	v_mul_f32_e32 v16, v16, v151
	v_mul_f32_e32 v0, v0, v152
	v_mul_f32_e32 v17, v99, v135
	ds_write2_b32 v21, v16, v0 offset0:192 offset1:224
	v_mul_f32_e32 v0, v114, v135
	v_mul_f32_e32 v17, v17, v151
	v_mul_f32_e32 v0, v0, v152
	v_mul_f32_e32 v18, v100, v137
	ds_write2_b32 v10, v17, v0 offset0:192 offset1:224
	v_mul_f32_e32 v0, v113, v137
	v_mul_f32_e32 v18, v18, v151
	v_mul_f32_e32 v0, v0, v152
	v_mul_f32_e32 v19, v101, v139
	ds_write2_b32 v7, v18, v0 offset0:192 offset1:224
	v_mul_f32_e32 v0, v119, v139
	v_mul_f32_e32 v19, v19, v151
	v_mul_f32_e32 v0, v0, v152
	v_mul_f32_e32 v20, v102, v141
	ds_write2_b32 v5, v19, v0 offset0:192 offset1:224
	v_mul_f32_e32 v0, v118, v141
	v_mul_f32_e32 v20, v20, v151
	v_mul_f32_e32 v0, v0, v152
	v_mul_f32_e32 v22, v103, v142
	ds_write2_b32 v4, v20, v0 offset0:192 offset1:224
	v_mul_f32_e32 v0, v120, v142
	v_mul_f32_e32 v22, v22, v151
	v_mul_f32_e32 v0, v0, v152
	v_mul_f32_e32 v24, v104, v140
	ds_write2_b32 v2, v22, v0 offset0:192 offset1:224
	v_mul_f32_e32 v0, v121, v140
	v_mul_f32_e32 v24, v24, v151
	v_mul_f32_e32 v0, v0, v152
	v_mul_f32_e32 v25, v105, v138
	ds_write2_b32 v3, v24, v0 offset0:192 offset1:224
	v_mul_f32_e32 v0, v124, v138
	v_mul_f32_e32 v25, v25, v151
	v_mul_f32_e32 v0, v0, v152
	v_mul_f32_e32 v26, v106, v136
	ds_write2_b32 v15, v25, v0 offset0:192 offset1:224
	v_mul_f32_e32 v0, v122, v136
	v_mul_f32_e32 v26, v26, v151
	v_mul_f32_e32 v0, v0, v152
	v_mul_f32_e32 v27, v107, v134
	ds_write2_b32 v14, v26, v0 offset0:192 offset1:224
	v_mul_f32_e32 v0, v125, v134
	v_mul_f32_e32 v27, v27, v151
	v_mul_f32_e32 v0, v0, v152
	v_mul_f32_e32 v28, v108, v132
	ds_write2_b32 v13, v27, v0 offset0:192 offset1:224
	v_mul_f32_e32 v0, v123, v132
	v_mul_f32_e32 v28, v28, v151
	v_mul_f32_e32 v0, v0, v152
	v_mul_f32_e32 v29, v109, v130
	ds_write2_b32 v12, v28, v0 offset0:192 offset1:224
	v_mul_f32_e32 v0, v127, v130
	v_mul_f32_e32 v29, v29, v151
	v_mul_f32_e32 v0, v0, v152
	v_mul_f32_e32 v30, v110, v143
	ds_write2_b32 v11, v29, v0 offset0:192 offset1:224
	v_mul_f32_e32 v0, v126, v143
	v_mul_f32_e32 v30, v30, v151
	v_mul_f32_e32 v0, v0, v152
	v_mul_f32_e32 v31, v111, v144
	ds_write2_b32 v8, v30, v0 offset0:192 offset1:224
	v_mul_f32_e32 v0, v128, v144
	v_mul_f32_e32 v31, v31, v151
	v_mul_f32_e32 v0, v0, v152
	ds_write2_b32 v6, v31, v0 offset0:192 offset1:224
	v_mov_b32_e32 v0, v220
	s_mov_b64 s[2:3], 0
	v_ashrrev_i32_e32 v4, 5, v0
	v_ashrrev_i32_e32 v5, 31, v4
	v_lshl_add_u64 v[2:3], v[4:5], 0, s[4:5]
	v_lshlrev_b32_e32 v5, 4, v0
	v_lshlrev_b64 v[2:3], 12, v[2:3]
	v_and_b32_e32 v5, 0x1f0, v5
	v_and_b32_e32 v0, 31, v0
	v_or3_b32 v2, s0, v5, v2
	v_lshl_add_u32 v4, v4, 10, s36
	v_lshlrev_b32_e32 v0, 5, v0
	v_lshl_add_u64 v[2:3], s[80:81], 0, v[2:3]
	v_add3_u32 v0, v4, v0, 0
	v_lshl_add_u64 v[248:249], v[2:3], 0, s[2:3]
	v_add_co_u32_e32 v250, vcc, s29, v248
	s_nop 1
	v_addc_co_u32_e32 v251, vcc, 0, v249, vcc
	global_load_dwordx4 v[128:131], v[250:251], off
	v_add_co_u32_e32 v250, vcc, s31, v248
	s_nop 1
	v_addc_co_u32_e32 v251, vcc, 0, v249, vcc
	global_load_dwordx4 v[132:135], v[250:251], off
	v_add_co_u32_e32 v250, vcc, 0x1a200000, v248
	s_nop 1
	v_addc_co_u32_e32 v251, vcc, 0, v249, vcc
	global_load_dwordx4 v[136:139], v[250:251], off
	v_add_co_u32_e32 v250, vcc, s27, v248
	s_nop 1
	v_addc_co_u32_e32 v251, vcc, 0, v249, vcc
	global_load_dwordx4 v[140:143], v[250:251], off
	s_add_u32 s2, s2, 0x8000
	s_addc_u32 s3, s3, 0
	v_lshl_add_u64 v[248:249], v[2:3], 0, s[2:3]
	v_add_co_u32_e32 v250, vcc, s29, v248
	s_nop 1
	v_addc_co_u32_e32 v251, vcc, 0, v249, vcc
	global_load_dwordx4 v[144:147], v[250:251], off
	v_add_co_u32_e32 v250, vcc, s31, v248
	s_nop 1
	v_addc_co_u32_e32 v251, vcc, 0, v249, vcc
	global_load_dwordx4 v[148:151], v[250:251], off
	v_add_co_u32_e32 v250, vcc, 0x1a200000, v248
	s_nop 1
	v_addc_co_u32_e32 v251, vcc, 0, v249, vcc
	global_load_dwordx4 v[152:155], v[250:251], off
	v_add_co_u32_e32 v250, vcc, s27, v248
	s_nop 1
	v_addc_co_u32_e32 v251, vcc, 0, v249, vcc
	global_load_dwordx4 v[156:159], v[250:251], off
	s_add_u32 s2, s2, 0x8000
	s_addc_u32 s3, s3, 0
	v_lshl_add_u64 v[248:249], v[2:3], 0, s[2:3]
	v_add_co_u32_e32 v250, vcc, s29, v248
	s_nop 1
	v_addc_co_u32_e32 v251, vcc, 0, v249, vcc
	global_load_dwordx4 v[160:163], v[250:251], off
	v_add_co_u32_e32 v250, vcc, s31, v248
	s_nop 1
	v_addc_co_u32_e32 v251, vcc, 0, v249, vcc
	global_load_dwordx4 v[164:167], v[250:251], off
	v_add_co_u32_e32 v250, vcc, 0x1a200000, v248
	s_nop 1
	v_addc_co_u32_e32 v251, vcc, 0, v249, vcc
	global_load_dwordx4 v[168:171], v[250:251], off
	v_add_co_u32_e32 v250, vcc, s27, v248
	s_nop 1
	v_addc_co_u32_e32 v251, vcc, 0, v249, vcc
	global_load_dwordx4 v[172:175], v[250:251], off
	s_add_u32 s2, s2, 0x8000
	s_addc_u32 s3, s3, 0
	v_lshl_add_u64 v[248:249], v[2:3], 0, s[2:3]
	v_add_co_u32_e32 v250, vcc, s29, v248
	s_nop 1
	v_addc_co_u32_e32 v251, vcc, 0, v249, vcc
	global_load_dwordx4 v[176:179], v[250:251], off
	v_add_co_u32_e32 v250, vcc, s31, v248
	s_nop 1
	v_addc_co_u32_e32 v251, vcc, 0, v249, vcc
	global_load_dwordx4 v[180:183], v[250:251], off
	v_add_co_u32_e32 v250, vcc, 0x1a200000, v248
	s_nop 1
	v_addc_co_u32_e32 v251, vcc, 0, v249, vcc
	global_load_dwordx4 v[184:187], v[250:251], off
	v_add_co_u32_e32 v250, vcc, s27, v248
	s_nop 1
	v_addc_co_u32_e32 v251, vcc, 0, v249, vcc
	global_load_dwordx4 v[188:191], v[250:251], off
	s_add_u32 s2, s2, 0x8000
	s_addc_u32 s3, s3, 0
	s_mov_b64 s[2:3], 0
	v_lshl_add_u64 v[52:53], v[2:3], 0, s[2:3]
	v_add_co_u32_e64 v54, s[0:1], s26, v52
	s_nop 1
	v_addc_co_u32_e64 v55, s[0:1], 0, v53, s[0:1]
	s_nop 1
	ds_read_b128 v[4:7], v0
	ds_read_b128 v[8:11], v0 offset:16
	ds_read_b128 v[12:15], v0 offset:2048
	ds_read_b128 v[16:19], v0 offset:2064
	ds_read_b128 v[20:23], v0 offset:4096
	ds_read_b128 v[24:27], v0 offset:4112
	ds_read_b128 v[28:31], v0 offset:6144
	ds_read_b128 v[32:35], v0 offset:6160
	s_nop 1
	s_nop 1
	s_nop 1
	v_add_co_u32_e32 v56, vcc, s28, v52
	s_add_u32 s2, s2, 0x8000
	s_nop 1
	v_addc_co_u32_e32 v57, vcc, 0, v53, vcc
	v_add_co_u32_e32 v58, vcc, s30, v52
	s_addc_u32 s3, s3, 0
	s_nop 1
	v_addc_co_u32_e32 v59, vcc, 0, v53, vcc
	v_add_u32_e32 v0, 0x2000, v0
	v_add_co_u32_e32 v52, vcc, s34, v52
	s_nop 1
	v_addc_co_u32_e32 v53, vcc, 0, v53, vcc
	s_waitcnt vmcnt(12)
	v_lshlrev_b32_e32 v60, 16, v128
	v_and_b32_e32 v61, 0xffff0000, v128
	v_lshlrev_b32_e32 v128, 16, v129
	v_and_b32_e32 v129, 0xffff0000, v129
	v_lshlrev_b32_e32 v62, 16, v130
	v_and_b32_e32 v63, 0xffff0000, v130
	v_lshlrev_b32_e32 v130, 16, v131
	v_and_b32_e32 v131, 0xffff0000, v131
	v_lshlrev_b32_e32 v64, 16, v132
	v_and_b32_e32 v65, 0xffff0000, v132
	v_lshlrev_b32_e32 v132, 16, v133
	v_and_b32_e32 v133, 0xffff0000, v133
	v_lshlrev_b32_e32 v66, 16, v134
	v_and_b32_e32 v67, 0xffff0000, v134
	v_lshlrev_b32_e32 v134, 16, v135
	v_and_b32_e32 v135, 0xffff0000, v135
	v_lshlrev_b32_e32 v68, 16, v136
	v_and_b32_e32 v69, 0xffff0000, v136
	v_lshlrev_b32_e32 v136, 16, v137
	v_and_b32_e32 v137, 0xffff0000, v137
	v_lshlrev_b32_e32 v70, 16, v138
	v_and_b32_e32 v71, 0xffff0000, v138
	v_lshlrev_b32_e32 v138, 16, v139
	v_and_b32_e32 v139, 0xffff0000, v139
	v_lshlrev_b32_e32 v72, 16, v140
	v_and_b32_e32 v73, 0xffff0000, v140
	v_lshlrev_b32_e32 v140, 16, v141
	v_and_b32_e32 v141, 0xffff0000, v141
	v_lshlrev_b32_e32 v74, 16, v142
	v_and_b32_e32 v75, 0xffff0000, v142
	v_lshlrev_b32_e32 v142, 16, v143
	v_and_b32_e32 v143, 0xffff0000, v143
	s_waitcnt lgkmcnt(3)
	v_pk_mul_f32 v[20:21], v[20:21], v[60:61]
	v_pk_mul_f32 v[22:23], v[22:23], v[128:129]
	s_waitcnt lgkmcnt(2)
	v_pk_mul_f32 v[24:25], v[24:25], v[62:63]
	v_pk_mul_f32 v[26:27], v[26:27], v[130:131]
	s_waitcnt lgkmcnt(1)
	v_pk_mul_f32 v[28:29], v[28:29], v[64:65]
	v_pk_mul_f32 v[30:31], v[30:31], v[132:133]
	s_waitcnt lgkmcnt(0)
	v_pk_mul_f32 v[32:33], v[32:33], v[66:67]
	v_pk_mul_f32 v[34:35], v[34:35], v[134:135]
	v_pk_mul_f32 v[128:129], v[4:5], v[68:69]
	v_pk_mul_f32 v[130:131], v[6:7], v[136:137]
	v_pk_mul_f32 v[132:133], v[8:9], v[70:71]
	v_pk_mul_f32 v[134:135], v[10:11], v[138:139]
	v_pk_mul_f32 v[136:137], v[12:13], v[72:73]
	v_pk_mul_f32 v[138:139], v[14:15], v[140:141]
	v_pk_mul_f32 v[140:141], v[16:17], v[74:75]
	v_pk_mul_f32 v[142:143], v[18:19], v[142:143]
	v_cvt_pk_bf16_f32 v4, v20, v21
	v_cvt_pk_bf16_f32 v5, v22, v23
	v_cvt_pk_bf16_f32 v6, v24, v25
	v_cvt_pk_bf16_f32 v7, v26, v27
	v_cvt_pk_bf16_f32 v8, v28, v29
	v_cvt_pk_bf16_f32 v9, v30, v31
	v_cvt_pk_bf16_f32 v10, v32, v33
	v_cvt_pk_bf16_f32 v11, v34, v35
	v_cvt_pk_bf16_f32 v12, v128, v129
	v_cvt_pk_bf16_f32 v13, v130, v131
	v_cvt_pk_bf16_f32 v14, v132, v133
	v_cvt_pk_bf16_f32 v15, v134, v135
	v_cvt_pk_bf16_f32 v16, v136, v137
	v_cvt_pk_bf16_f32 v17, v138, v139
	v_cvt_pk_bf16_f32 v18, v140, v141
	v_cvt_pk_bf16_f32 v19, v142, v143
	global_store_dwordx4 v[58:59], v[4:7], off
	global_store_dwordx4 v[52:53], v[8:11], off
	global_store_dwordx4 v[54:55], v[12:15], off
	global_store_dwordx4 v[56:57], v[16:19], off
	v_lshl_add_u64 v[52:53], v[2:3], 0, s[2:3]
	v_add_co_u32_e64 v54, s[0:1], s26, v52
	s_nop 1
	v_addc_co_u32_e64 v55, s[0:1], 0, v53, s[0:1]
	s_nop 1
	ds_read_b128 v[4:7], v0
	ds_read_b128 v[8:11], v0 offset:16
	ds_read_b128 v[12:15], v0 offset:2048
	ds_read_b128 v[16:19], v0 offset:2064
	ds_read_b128 v[20:23], v0 offset:4096
	ds_read_b128 v[24:27], v0 offset:4112
	ds_read_b128 v[28:31], v0 offset:6144
	ds_read_b128 v[32:35], v0 offset:6160
	s_nop 1
	s_nop 1
	s_nop 1
	v_add_co_u32_e32 v56, vcc, s28, v52
	s_add_u32 s2, s2, 0x8000
	s_nop 1
	v_addc_co_u32_e32 v57, vcc, 0, v53, vcc
	v_add_co_u32_e32 v58, vcc, s30, v52
	s_addc_u32 s3, s3, 0
	s_nop 1
	v_addc_co_u32_e32 v59, vcc, 0, v53, vcc
	v_add_u32_e32 v0, 0x2000, v0
	v_add_co_u32_e32 v52, vcc, s34, v52
	s_nop 1
	v_addc_co_u32_e32 v53, vcc, 0, v53, vcc
	s_waitcnt vmcnt(12)
	v_lshlrev_b32_e32 v60, 16, v144
	v_and_b32_e32 v61, 0xffff0000, v144
	v_lshlrev_b32_e32 v144, 16, v145
	v_and_b32_e32 v145, 0xffff0000, v145
	v_lshlrev_b32_e32 v62, 16, v146
	v_and_b32_e32 v63, 0xffff0000, v146
	v_lshlrev_b32_e32 v146, 16, v147
	v_and_b32_e32 v147, 0xffff0000, v147
	v_lshlrev_b32_e32 v64, 16, v148
	v_and_b32_e32 v65, 0xffff0000, v148
	v_lshlrev_b32_e32 v148, 16, v149
	v_and_b32_e32 v149, 0xffff0000, v149
	v_lshlrev_b32_e32 v66, 16, v150
	v_and_b32_e32 v67, 0xffff0000, v150
	v_lshlrev_b32_e32 v150, 16, v151
	v_and_b32_e32 v151, 0xffff0000, v151
	v_lshlrev_b32_e32 v68, 16, v152
	v_and_b32_e32 v69, 0xffff0000, v152
	v_lshlrev_b32_e32 v152, 16, v153
	v_and_b32_e32 v153, 0xffff0000, v153
	v_lshlrev_b32_e32 v70, 16, v154
	v_and_b32_e32 v71, 0xffff0000, v154
	v_lshlrev_b32_e32 v154, 16, v155
	v_and_b32_e32 v155, 0xffff0000, v155
	v_lshlrev_b32_e32 v72, 16, v156
	v_and_b32_e32 v73, 0xffff0000, v156
	v_lshlrev_b32_e32 v156, 16, v157
	v_and_b32_e32 v157, 0xffff0000, v157
	v_lshlrev_b32_e32 v74, 16, v158
	v_and_b32_e32 v75, 0xffff0000, v158
	v_lshlrev_b32_e32 v158, 16, v159
	v_and_b32_e32 v159, 0xffff0000, v159
	s_waitcnt lgkmcnt(3)
	v_pk_mul_f32 v[20:21], v[20:21], v[60:61]
	v_pk_mul_f32 v[22:23], v[22:23], v[144:145]
	s_waitcnt lgkmcnt(2)
	v_pk_mul_f32 v[24:25], v[24:25], v[62:63]
	v_pk_mul_f32 v[26:27], v[26:27], v[146:147]
	s_waitcnt lgkmcnt(1)
	v_pk_mul_f32 v[28:29], v[28:29], v[64:65]
	v_pk_mul_f32 v[30:31], v[30:31], v[148:149]
	s_waitcnt lgkmcnt(0)
	v_pk_mul_f32 v[32:33], v[32:33], v[66:67]
	v_pk_mul_f32 v[34:35], v[34:35], v[150:151]
	v_pk_mul_f32 v[144:145], v[4:5], v[68:69]
	v_pk_mul_f32 v[146:147], v[6:7], v[152:153]
	v_pk_mul_f32 v[148:149], v[8:9], v[70:71]
	v_pk_mul_f32 v[150:151], v[10:11], v[154:155]
	v_pk_mul_f32 v[152:153], v[12:13], v[72:73]
	v_pk_mul_f32 v[154:155], v[14:15], v[156:157]
	v_pk_mul_f32 v[156:157], v[16:17], v[74:75]
	v_pk_mul_f32 v[158:159], v[18:19], v[158:159]
	v_cvt_pk_bf16_f32 v4, v20, v21
	v_cvt_pk_bf16_f32 v5, v22, v23
	v_cvt_pk_bf16_f32 v6, v24, v25
	v_cvt_pk_bf16_f32 v7, v26, v27
	v_cvt_pk_bf16_f32 v8, v28, v29
	v_cvt_pk_bf16_f32 v9, v30, v31
	v_cvt_pk_bf16_f32 v10, v32, v33
	v_cvt_pk_bf16_f32 v11, v34, v35
	v_cvt_pk_bf16_f32 v12, v144, v145
	v_cvt_pk_bf16_f32 v13, v146, v147
	v_cvt_pk_bf16_f32 v14, v148, v149
	v_cvt_pk_bf16_f32 v15, v150, v151
	v_cvt_pk_bf16_f32 v16, v152, v153
	v_cvt_pk_bf16_f32 v17, v154, v155
	v_cvt_pk_bf16_f32 v18, v156, v157
	v_cvt_pk_bf16_f32 v19, v158, v159
	global_store_dwordx4 v[58:59], v[4:7], off
	global_store_dwordx4 v[52:53], v[8:11], off
	global_store_dwordx4 v[54:55], v[12:15], off
	global_store_dwordx4 v[56:57], v[16:19], off
	v_lshl_add_u64 v[52:53], v[2:3], 0, s[2:3]
	v_add_co_u32_e64 v54, s[0:1], s26, v52
	s_nop 1
	v_addc_co_u32_e64 v55, s[0:1], 0, v53, s[0:1]
	s_nop 1
	ds_read_b128 v[4:7], v0
	ds_read_b128 v[8:11], v0 offset:16
	ds_read_b128 v[12:15], v0 offset:2048
	ds_read_b128 v[16:19], v0 offset:2064
	ds_read_b128 v[20:23], v0 offset:4096
	ds_read_b128 v[24:27], v0 offset:4112
	ds_read_b128 v[28:31], v0 offset:6144
	ds_read_b128 v[32:35], v0 offset:6160
	s_nop 1
	s_nop 1
	s_nop 1
	v_add_co_u32_e32 v56, vcc, s28, v52
	s_add_u32 s2, s2, 0x8000
	s_nop 1
	v_addc_co_u32_e32 v57, vcc, 0, v53, vcc
	v_add_co_u32_e32 v58, vcc, s30, v52
	s_addc_u32 s3, s3, 0
	s_nop 1
	v_addc_co_u32_e32 v59, vcc, 0, v53, vcc
	v_add_u32_e32 v0, 0x2000, v0
	v_add_co_u32_e32 v52, vcc, s34, v52
	s_nop 1
	v_addc_co_u32_e32 v53, vcc, 0, v53, vcc
	s_waitcnt vmcnt(12)
	v_lshlrev_b32_e32 v60, 16, v160
	v_and_b32_e32 v61, 0xffff0000, v160
	v_lshlrev_b32_e32 v160, 16, v161
	v_and_b32_e32 v161, 0xffff0000, v161
	v_lshlrev_b32_e32 v62, 16, v162
	v_and_b32_e32 v63, 0xffff0000, v162
	v_lshlrev_b32_e32 v162, 16, v163
	v_and_b32_e32 v163, 0xffff0000, v163
	v_lshlrev_b32_e32 v64, 16, v164
	v_and_b32_e32 v65, 0xffff0000, v164
	v_lshlrev_b32_e32 v164, 16, v165
	v_and_b32_e32 v165, 0xffff0000, v165
	v_lshlrev_b32_e32 v66, 16, v166
	v_and_b32_e32 v67, 0xffff0000, v166
	v_lshlrev_b32_e32 v166, 16, v167
	v_and_b32_e32 v167, 0xffff0000, v167
	v_lshlrev_b32_e32 v68, 16, v168
	v_and_b32_e32 v69, 0xffff0000, v168
	v_lshlrev_b32_e32 v168, 16, v169
	v_and_b32_e32 v169, 0xffff0000, v169
	v_lshlrev_b32_e32 v70, 16, v170
	v_and_b32_e32 v71, 0xffff0000, v170
	v_lshlrev_b32_e32 v170, 16, v171
	v_and_b32_e32 v171, 0xffff0000, v171
	v_lshlrev_b32_e32 v72, 16, v172
	v_and_b32_e32 v73, 0xffff0000, v172
	v_lshlrev_b32_e32 v172, 16, v173
	v_and_b32_e32 v173, 0xffff0000, v173
	v_lshlrev_b32_e32 v74, 16, v174
	v_and_b32_e32 v75, 0xffff0000, v174
	v_lshlrev_b32_e32 v174, 16, v175
	v_and_b32_e32 v175, 0xffff0000, v175
	s_waitcnt lgkmcnt(3)
	v_pk_mul_f32 v[20:21], v[20:21], v[60:61]
	v_pk_mul_f32 v[22:23], v[22:23], v[160:161]
	s_waitcnt lgkmcnt(2)
	v_pk_mul_f32 v[24:25], v[24:25], v[62:63]
	v_pk_mul_f32 v[26:27], v[26:27], v[162:163]
	s_waitcnt lgkmcnt(1)
	v_pk_mul_f32 v[28:29], v[28:29], v[64:65]
	v_pk_mul_f32 v[30:31], v[30:31], v[164:165]
	s_waitcnt lgkmcnt(0)
	v_pk_mul_f32 v[32:33], v[32:33], v[66:67]
	v_pk_mul_f32 v[34:35], v[34:35], v[166:167]
	v_pk_mul_f32 v[160:161], v[4:5], v[68:69]
	v_pk_mul_f32 v[162:163], v[6:7], v[168:169]
	v_pk_mul_f32 v[164:165], v[8:9], v[70:71]
	v_pk_mul_f32 v[166:167], v[10:11], v[170:171]
	v_pk_mul_f32 v[168:169], v[12:13], v[72:73]
	v_pk_mul_f32 v[170:171], v[14:15], v[172:173]
	v_pk_mul_f32 v[172:173], v[16:17], v[74:75]
	v_pk_mul_f32 v[174:175], v[18:19], v[174:175]
	v_cvt_pk_bf16_f32 v4, v20, v21
	v_cvt_pk_bf16_f32 v5, v22, v23
	v_cvt_pk_bf16_f32 v6, v24, v25
	v_cvt_pk_bf16_f32 v7, v26, v27
	v_cvt_pk_bf16_f32 v8, v28, v29
	v_cvt_pk_bf16_f32 v9, v30, v31
	v_cvt_pk_bf16_f32 v10, v32, v33
	v_cvt_pk_bf16_f32 v11, v34, v35
	v_cvt_pk_bf16_f32 v12, v160, v161
	v_cvt_pk_bf16_f32 v13, v162, v163
	v_cvt_pk_bf16_f32 v14, v164, v165
	v_cvt_pk_bf16_f32 v15, v166, v167
	v_cvt_pk_bf16_f32 v16, v168, v169
	v_cvt_pk_bf16_f32 v17, v170, v171
	v_cvt_pk_bf16_f32 v18, v172, v173
	v_cvt_pk_bf16_f32 v19, v174, v175
	global_store_dwordx4 v[58:59], v[4:7], off
	global_store_dwordx4 v[52:53], v[8:11], off
	global_store_dwordx4 v[54:55], v[12:15], off
	global_store_dwordx4 v[56:57], v[16:19], off
	v_lshl_add_u64 v[52:53], v[2:3], 0, s[2:3]
	v_add_co_u32_e64 v54, s[0:1], s26, v52
	s_nop 1
	v_addc_co_u32_e64 v55, s[0:1], 0, v53, s[0:1]
	s_nop 1
	ds_read_b128 v[4:7], v0
	ds_read_b128 v[8:11], v0 offset:16
	ds_read_b128 v[12:15], v0 offset:2048
	ds_read_b128 v[16:19], v0 offset:2064
	ds_read_b128 v[20:23], v0 offset:4096
	ds_read_b128 v[24:27], v0 offset:4112
	ds_read_b128 v[28:31], v0 offset:6144
	ds_read_b128 v[32:35], v0 offset:6160
	s_nop 1
	s_nop 1
	s_nop 1
	v_add_co_u32_e32 v56, vcc, s28, v52
	s_add_u32 s2, s2, 0x8000
	s_nop 1
	v_addc_co_u32_e32 v57, vcc, 0, v53, vcc
	v_add_co_u32_e32 v58, vcc, s30, v52
	s_addc_u32 s3, s3, 0
	s_nop 1
	v_addc_co_u32_e32 v59, vcc, 0, v53, vcc
	v_add_u32_e32 v0, 0x2000, v0
	v_add_co_u32_e32 v52, vcc, s34, v52
	s_nop 1
	v_addc_co_u32_e32 v53, vcc, 0, v53, vcc
	s_waitcnt vmcnt(12)
	v_lshlrev_b32_e32 v60, 16, v176
	v_and_b32_e32 v61, 0xffff0000, v176
	v_lshlrev_b32_e32 v176, 16, v177
	v_and_b32_e32 v177, 0xffff0000, v177
	v_lshlrev_b32_e32 v62, 16, v178
	v_and_b32_e32 v63, 0xffff0000, v178
	v_lshlrev_b32_e32 v178, 16, v179
	v_and_b32_e32 v179, 0xffff0000, v179
	v_lshlrev_b32_e32 v64, 16, v180
	v_and_b32_e32 v65, 0xffff0000, v180
	v_lshlrev_b32_e32 v180, 16, v181
	v_and_b32_e32 v181, 0xffff0000, v181
	v_lshlrev_b32_e32 v66, 16, v182
	v_and_b32_e32 v67, 0xffff0000, v182
	v_lshlrev_b32_e32 v182, 16, v183
	v_and_b32_e32 v183, 0xffff0000, v183
	v_lshlrev_b32_e32 v68, 16, v184
	v_and_b32_e32 v69, 0xffff0000, v184
	v_lshlrev_b32_e32 v184, 16, v185
	v_and_b32_e32 v185, 0xffff0000, v185
	v_lshlrev_b32_e32 v70, 16, v186
	v_and_b32_e32 v71, 0xffff0000, v186
	v_lshlrev_b32_e32 v186, 16, v187
	v_and_b32_e32 v187, 0xffff0000, v187
	v_lshlrev_b32_e32 v72, 16, v188
	v_and_b32_e32 v73, 0xffff0000, v188
	v_lshlrev_b32_e32 v188, 16, v189
	v_and_b32_e32 v189, 0xffff0000, v189
	v_lshlrev_b32_e32 v74, 16, v190
	v_and_b32_e32 v75, 0xffff0000, v190
	v_lshlrev_b32_e32 v190, 16, v191
	v_and_b32_e32 v191, 0xffff0000, v191
	s_waitcnt lgkmcnt(3)
	v_pk_mul_f32 v[20:21], v[20:21], v[60:61]
	v_pk_mul_f32 v[22:23], v[22:23], v[176:177]
	s_waitcnt lgkmcnt(2)
	v_pk_mul_f32 v[24:25], v[24:25], v[62:63]
	v_pk_mul_f32 v[26:27], v[26:27], v[178:179]
	s_waitcnt lgkmcnt(1)
	v_pk_mul_f32 v[28:29], v[28:29], v[64:65]
	v_pk_mul_f32 v[30:31], v[30:31], v[180:181]
	s_waitcnt lgkmcnt(0)
	v_pk_mul_f32 v[32:33], v[32:33], v[66:67]
	v_pk_mul_f32 v[34:35], v[34:35], v[182:183]
	v_pk_mul_f32 v[176:177], v[4:5], v[68:69]
	v_pk_mul_f32 v[178:179], v[6:7], v[184:185]
	v_pk_mul_f32 v[180:181], v[8:9], v[70:71]
	v_pk_mul_f32 v[182:183], v[10:11], v[186:187]
	v_pk_mul_f32 v[184:185], v[12:13], v[72:73]
	v_pk_mul_f32 v[186:187], v[14:15], v[188:189]
	v_pk_mul_f32 v[188:189], v[16:17], v[74:75]
	v_pk_mul_f32 v[190:191], v[18:19], v[190:191]
	v_cvt_pk_bf16_f32 v4, v20, v21
	v_cvt_pk_bf16_f32 v5, v22, v23
	v_cvt_pk_bf16_f32 v6, v24, v25
	v_cvt_pk_bf16_f32 v7, v26, v27
	v_cvt_pk_bf16_f32 v8, v28, v29
	v_cvt_pk_bf16_f32 v9, v30, v31
	v_cvt_pk_bf16_f32 v10, v32, v33
	v_cvt_pk_bf16_f32 v11, v34, v35
	v_cvt_pk_bf16_f32 v12, v176, v177
	v_cvt_pk_bf16_f32 v13, v178, v179
	v_cvt_pk_bf16_f32 v14, v180, v181
	v_cvt_pk_bf16_f32 v15, v182, v183
	v_cvt_pk_bf16_f32 v16, v184, v185
	v_cvt_pk_bf16_f32 v17, v186, v187
	v_cvt_pk_bf16_f32 v18, v188, v189
	v_cvt_pk_bf16_f32 v19, v190, v191
	global_store_dwordx4 v[58:59], v[4:7], off
	global_store_dwordx4 v[52:53], v[8:11], off
	global_store_dwordx4 v[54:55], v[12:15], off
	global_store_dwordx4 v[56:57], v[16:19], off
	s_branch .LBB0_1590
